# GEMM MFMA blocks: priority raise moved before the opening barrier and the drop after the closing barrier (no scalar op between barriers and MFMAs)
# baseline (speedup 1.0000x reference)
; #define PG8_STAGE(bufoff, gbase, voff) do { _Pragma("unroll") for (int _i = 0; _i < 2; ++_i) \
;         __builtin_amdgcn_global_load_lds((const unsigned*)((const char*)(gbase) + (voff)[_i]), (PG8_LAS unsigned*)(lds + (bufoff) + ldsw + _i * 8192), 16, 0, 0); } while (0)
; #define PG8_LDA(dst, b, h) do { _Pragma("unroll") for (int m = 0; m < 4; ++m) _Pragma("unroll") for (int k = 0; k < 2; ++k) dst[m][k] = *(const PG8_LAS bf16x8*)(lds + PG8_SA(b, h) + aoff + m * 2048 + k * 1024); } while (0)
; #define PG8_LDB(dst, b, h) do { _Pragma("unroll") for (int n = 0; n < 2; ++n) _Pragma("unroll") for (int k = 0; k < 2; ++k) dst[n][k] = *(const PG8_LAS bf16x8*)(lds + PG8_SB(b, h) + boff + n * 2048 + k * 1024); } while (0)
; #define PG8_MMA(ai, bj, At, Bt) do { __builtin_amdgcn_s_setprio(1); _Pragma("unroll") for (int m = 0; m < 4; ++m) _Pragma("unroll") for (int n = 0; n < 2; ++n) _Pragma("unroll") for (int k = 0; k < 2; ++k) \
;         acc[ai][bj][m][n] = __builtin_amdgcn_mfma_f32_16x16x32_bf16(Bt[n][k], At[m][k], acc[ai][bj][m][n], 0, 0, 0); __builtin_amdgcn_s_setprio(0); } while (0)
; #define PG8_BAR __builtin_amdgcn_s_barrier()
; template <class Epi, class Sched, bool ALIGN_EPI = false, bool SP2 = false>
; __device__ __forceinline__ void gemm_phase(PG8_LAS unsigned char* lds, const Gemm g, const Sched& S, const Epi& E) {
;     ...
;         const bool has_next = S.next(ui + 1, nxt);
;         const char* nA = has_next ? (const char*)g.A + (size_t)nxt.pm * tstep : cA; const char* nB = has_next ? (const char*)g.Bt + (size_t)nxt.pn * tstep : cB;
;         for (int t = 0; t < nt; t += 2) {
;             const bool last = (t == nt - 2);
;             const char* a1 = cA + (size_t)(t + 1) * kstep;
;             const char* a2 = last ? nA : cA + (size_t)(t + 2) * kstep; const char* b2 = last ? nB : cB + (size_t)(t + 2) * kstep;
;             const char* a3 = a2 + kstep; const char* b3 = b2 + kstep;
;             if (last && has_next) S.a_ready(nxt);
;             if constexpr (SP2) {
;             PG8_LDB(B0, 0, 0); PG8_LDB(B1, 0, 1); PG8_SCHED; PG8_LDA(At, 0, 0); PG8_STAGE(PG8_SA(1, 1), a1 + hstep, voffA);
;             PG8_WAIT_V(8); PG8_WAIT_L(0); PG8_BAR; PG8_MMA(0, 0, At, B0); PG8_MMA(0, 1, At, B1); PG8_BAR; PG8_SCHED;
;             PG8_LDA(At, 0, 1); PG8_STAGE(PG8_SB(0, 0), b2, voffB); PG8_STAGE(PG8_SB(0, 1), b2 + hstep, voffB); PG8_STAGE(PG8_SA(0, 0), a2, voffA);
.LBB0_170:
	s_ashr_i32 s29, s28, 31
	s_lshl_b64 s[30:31], s[28:29], 20
	s_add_u32 s30, s13, s30
	s_addc_u32 s31, s47, s31
	s_and_b64 s[34:35], s[38:39], exec
	s_cselect_b32 s29, s31, s41
	s_cselect_b32 s37, s30, s40
	s_ashr_i32 s27, s26, 31
	s_lshl_b64 s[34:35], s[26:27], 20
	s_add_u32 s34, s48, s34
	s_addc_u32 s35, s49, s35
	s_and_b64 s[44:45], s[38:39], exec
	s_cselect_b32 s27, s35, s43
	s_cselect_b32 s65, s34, s42
	s_add_u32 s40, s40, 0x80080
	s_addc_u32 s41, s41, 0
	s_add_u32 s67, s42, 0x100
	s_addc_u32 s68, s43, 0
	s_mov_b32 s69, -2
	ds_read_b128 v[128:131], v175
	ds_read_b128 v[132:135], v175 offset:1024
	ds_read_b128 v[136:139], v175 offset:2048
	ds_read_b128 v[140:143], v175 offset:3072
	ds_read_b128 v[164:167], v176
	ds_read_b128 v[168:171], v176 offset:1024
	ds_read_b128 v[178:181], v176 offset:2048
	ds_read_b128 v[182:185], v176 offset:3072
	s_add_u32 s42, s40, 0xfff80080
	s_addc_u32 s43, s41, -1
	s_cmp_eq_u32 s69, 28
	s_cselect_b32 s45, s29, s43
	s_cselect_b32 s44, s37, s42
	s_cselect_b32 s43, s27, s68
	s_cselect_b32 s42, s65, s67
	v_lshl_add_u64 v[190:191], s[40:41], 0, v[156:157]
	s_add_i32 m0, s52, 0xc000
	ds_read_b128 v[186:189], v177
	ds_read_b128 v[194:197], v177 offset:1024
	ds_read_b128 v[198:201], v177 offset:2048
	ds_read_b128 v[202:205], v177 offset:3072
	ds_read_b128 v[206:209], v177 offset:4096
	ds_read_b128 v[210:213], v177 offset:5120
	ds_read_b128 v[218:221], v177 offset:6144
	ds_read_b128 v[222:225], v177 offset:7168
	global_load_lds_dwordx4 v[190:191], off
	v_lshl_add_u64 v[190:191], s[40:41], 0, v[158:159]
	s_add_i32 m0, s52, 0xe000
	s_nop 0
	global_load_lds_dwordx4 v[190:191], off
	s_waitcnt vmcnt(8)
	s_waitcnt lgkmcnt(0)
	s_setprio 1
	s_barrier
	v_mfma_f32_16x16x32_bf16 v[124:127], v[128:131], v[186:189], 0
	v_mfma_f32_16x16x32_bf16 v[120:123], v[136:139], v[186:189], 0
	v_mfma_f32_16x16x32_bf16 v[116:119], v[128:131], v[198:201], 0
	v_mfma_f32_16x16x32_bf16 v[112:115], v[136:139], v[198:201], 0
	v_mfma_f32_16x16x32_bf16 v[100:103], v[128:131], v[206:209], 0
	v_mfma_f32_16x16x32_bf16 v[96:99], v[136:139], v[206:209], 0
	v_mfma_f32_16x16x32_bf16 v[84:87], v[128:131], v[218:221], 0
	v_mfma_f32_16x16x32_bf16 v[80:83], v[136:139], v[218:221], 0
	v_mfma_f32_16x16x32_bf16 v[124:127], v[132:135], v[194:197], v[124:127]
	v_mfma_f32_16x16x32_bf16 v[120:123], v[140:143], v[194:197], v[120:123]
	v_mfma_f32_16x16x32_bf16 v[116:119], v[132:135], v[202:205], v[116:119]
	v_mfma_f32_16x16x32_bf16 v[112:115], v[140:143], v[202:205], v[112:115]
	v_mfma_f32_16x16x32_bf16 v[100:103], v[132:135], v[210:213], v[100:103]
	v_mfma_f32_16x16x32_bf16 v[96:99], v[140:143], v[210:213], v[96:99]
	v_mfma_f32_16x16x32_bf16 v[84:87], v[132:135], v[222:225], v[84:87]
	v_mfma_f32_16x16x32_bf16 v[80:83], v[140:143], v[222:225], v[80:83]
	v_mfma_f32_16x16x32_bf16 v[108:111], v[164:167], v[186:189], 0
	v_mfma_f32_16x16x32_bf16 v[104:107], v[178:181], v[186:189], 0
	v_mfma_f32_16x16x32_bf16 v[92:95], v[164:167], v[198:201], 0
	v_mfma_f32_16x16x32_bf16 v[88:91], v[178:181], v[198:201], 0
	v_mfma_f32_16x16x32_bf16 v[76:79], v[164:167], v[206:209], 0
	v_mfma_f32_16x16x32_bf16 v[72:75], v[178:181], v[206:209], 0
	v_mfma_f32_16x16x32_bf16 v[68:71], v[164:167], v[218:221], 0
	v_mfma_f32_16x16x32_bf16 v[64:67], v[178:181], v[218:221], 0
	v_mfma_f32_16x16x32_bf16 v[108:111], v[168:171], v[194:197], v[108:111]
	v_mfma_f32_16x16x32_bf16 v[104:107], v[182:185], v[194:197], v[104:107]
	v_mfma_f32_16x16x32_bf16 v[92:95], v[168:171], v[202:205], v[92:95]
	v_mfma_f32_16x16x32_bf16 v[88:91], v[182:185], v[202:205], v[88:91]
	v_mfma_f32_16x16x32_bf16 v[76:79], v[168:171], v[210:213], v[76:79]
	v_mfma_f32_16x16x32_bf16 v[72:75], v[182:185], v[210:213], v[72:75]
	v_mfma_f32_16x16x32_bf16 v[68:71], v[168:171], v[222:225], v[68:71]
	v_mfma_f32_16x16x32_bf16 v[64:67], v[182:185], v[222:225], v[64:67]
	s_barrier
	s_setprio 0
	s_add_i32 s70, s61, s50
	v_lshl_add_u64 v[190:191], s[42:43], 0, v[148:149]
	s_mov_b32 m0, s70
	ds_read_b128 v[186:189], v177 offset:16384
	ds_read_b128 v[194:197], v177 offset:17408
	ds_read_b128 v[198:201], v177 offset:18432
	ds_read_b128 v[202:205], v177 offset:19456
	ds_read_b128 v[206:209], v177 offset:20480
	ds_read_b128 v[210:213], v177 offset:21504
	ds_read_b128 v[218:221], v177 offset:22528
	ds_read_b128 v[222:225], v177 offset:23552
	global_load_lds_dwordx4 v[190:191], off
	s_add_i32 m0, s70, 0x2000
	s_add_u32 s70, s42, 0x80000
	v_lshl_add_u64 v[214:215], s[42:43], 0, v[144:145]
	s_addc_u32 s71, s43, 0
	s_add_i32 s72, s62, s50
	global_load_lds_dwordx4 v[214:215], off
	v_lshl_add_u64 v[226:227], s[70:71], 0, v[148:149]
	s_mov_b32 m0, s72
	v_lshl_add_u64 v[228:229], s[44:45], 0, v[146:147]
	global_load_lds_dwordx4 v[226:227], off
	v_lshl_add_u64 v[226:227], s[70:71], 0, v[144:145]
	s_add_i32 m0, s72, 0x2000
	s_nop 0
	global_load_lds_dwordx4 v[226:227], off
	v_lshl_add_u64 v[226:227], s[44:45], 0, v[150:151]
	s_mov_b32 m0, s52
	s_nop 0
	global_load_lds_dwordx4 v[226:227], off
	s_mov_b32 m0, s53
	s_nop 0
	global_load_lds_dwordx4 v[228:229], off
	s_waitcnt vmcnt(8)
	s_waitcnt lgkmcnt(0)
	s_setprio 1
	s_barrier
; #define PG8_STAGE(bufoff, gbase, voff) do { _Pragma("unroll") for (int _i = 0; _i < 2; ++_i) \
;         __builtin_amdgcn_global_load_lds((const unsigned*)((const char*)(gbase) + (voff)[_i]), (PG8_LAS unsigned*)(lds + (bufoff) + ldsw + _i * 8192), 16, 0, 0); } while (0)
; #define PG8_LDA(dst, b, h) do { _Pragma("unroll") for (int m = 0; m < 4; ++m) _Pragma("unroll") for (int k = 0; k < 2; ++k) dst[m][k] = *(const PG8_LAS bf16x8*)(lds + PG8_SA(b, h) + aoff + m * 2048 + k * 1024); } while (0)
; #define PG8_LDB(dst, b, h) do { _Pragma("unroll") for (int n = 0; n < 2; ++n) _Pragma("unroll") for (int k = 0; k < 2; ++k) dst[n][k] = *(const PG8_LAS bf16x8*)(lds + PG8_SB(b, h) + boff + n * 2048 + k * 1024); } while (0)
; #define PG8_MMA(ai, bj, At, Bt) do { __builtin_amdgcn_s_setprio(1); _Pragma("unroll") for (int m = 0; m < 4; ++m) _Pragma("unroll") for (int n = 0; n < 2; ++n) _Pragma("unroll") for (int k = 0; k < 2; ++k) \
;         acc[ai][bj][m][n] = __builtin_amdgcn_mfma_f32_16x16x32_bf16(Bt[n][k], At[m][k], acc[ai][bj][m][n], 0, 0, 0); __builtin_amdgcn_s_setprio(0); } while (0)
; #define PG8_WAIT_V(n) asm volatile("s_waitcnt vmcnt(" #n ")" ::: "memory")
; #define PG8_WAIT_L(n) asm volatile("s_waitcnt lgkmcnt(" #n ")" ::: "memory")
; #define PG8_BAR __builtin_amdgcn_s_barrier()
; #define PG8_SCHED __builtin_amdgcn_sched_barrier(0)
; template <class Epi, class Sched, bool ALIGN_EPI = false, bool SP2 = false>
; __device__ __forceinline__ void gemm_phase(PG8_LAS unsigned char* lds, const Gemm g, const Sched& S, const Epi& E) {
;     ...
;             PG8_WAIT_V(8); PG8_WAIT_L(0); PG8_BAR; PG8_MMA(1, 0, At, B0); PG8_MMA(1, 1, At, B1); PG8_BAR; PG8_SCHED;
;             PG8_LDB(B0, 1, 0); PG8_LDB(B1, 1, 1); PG8_SCHED; PG8_LDA(At, 1, 0); PG8_STAGE(PG8_SA(0, 1), a2 + hstep, voffA);
;             PG8_WAIT_V(8); PG8_WAIT_L(0); PG8_BAR; PG8_MMA(0, 0, At, B0); PG8_MMA(0, 1, At, B1); PG8_BAR; PG8_SCHED;
	v_mfma_f32_16x16x32_bf16 v[60:63], v[128:131], v[186:189], 0
	v_mfma_f32_16x16x32_bf16 v[56:59], v[136:139], v[186:189], 0
	v_mfma_f32_16x16x32_bf16 v[52:55], v[128:131], v[198:201], 0
	v_mfma_f32_16x16x32_bf16 v[48:51], v[136:139], v[198:201], 0
	v_mfma_f32_16x16x32_bf16 v[36:39], v[128:131], v[206:209], 0
	v_mfma_f32_16x16x32_bf16 v[32:35], v[136:139], v[206:209], 0
	v_mfma_f32_16x16x32_bf16 v[20:23], v[128:131], v[218:221], 0
	v_mfma_f32_16x16x32_bf16 v[16:19], v[136:139], v[218:221], 0
	v_mfma_f32_16x16x32_bf16 v[60:63], v[132:135], v[194:197], v[60:63]
	v_mfma_f32_16x16x32_bf16 v[56:59], v[140:143], v[194:197], v[56:59]
	v_mfma_f32_16x16x32_bf16 v[52:55], v[132:135], v[202:205], v[52:55]
	v_mfma_f32_16x16x32_bf16 v[48:51], v[140:143], v[202:205], v[48:51]
	v_mfma_f32_16x16x32_bf16 v[36:39], v[132:135], v[210:213], v[36:39]
	v_mfma_f32_16x16x32_bf16 v[32:35], v[140:143], v[210:213], v[32:35]
	v_mfma_f32_16x16x32_bf16 v[20:23], v[132:135], v[222:225], v[20:23]
	v_mfma_f32_16x16x32_bf16 v[16:19], v[140:143], v[222:225], v[16:19]
	v_mfma_f32_16x16x32_bf16 v[44:47], v[164:167], v[186:189], 0
	v_mfma_f32_16x16x32_bf16 v[40:43], v[178:181], v[186:189], 0
	v_mfma_f32_16x16x32_bf16 v[28:31], v[164:167], v[198:201], 0
	v_mfma_f32_16x16x32_bf16 v[24:27], v[178:181], v[198:201], 0
	v_mfma_f32_16x16x32_bf16 v[12:15], v[164:167], v[206:209], 0
	v_mfma_f32_16x16x32_bf16 v[8:11], v[178:181], v[206:209], 0
	v_mfma_f32_16x16x32_bf16 v[4:7], v[164:167], v[218:221], 0
	v_mfma_f32_16x16x32_bf16 v[0:3], v[178:181], v[218:221], 0
	v_mfma_f32_16x16x32_bf16 v[44:47], v[168:171], v[194:197], v[44:47]
	v_mfma_f32_16x16x32_bf16 v[40:43], v[182:185], v[194:197], v[40:43]
	v_mfma_f32_16x16x32_bf16 v[28:31], v[168:171], v[202:205], v[28:31]
	v_mfma_f32_16x16x32_bf16 v[24:27], v[182:185], v[202:205], v[24:27]
	v_mfma_f32_16x16x32_bf16 v[12:15], v[168:171], v[210:213], v[12:15]
	v_mfma_f32_16x16x32_bf16 v[8:11], v[182:185], v[210:213], v[8:11]
	v_mfma_f32_16x16x32_bf16 v[4:7], v[168:171], v[222:225], v[4:7]
	v_mfma_f32_16x16x32_bf16 v[0:3], v[182:185], v[222:225], v[0:3]
	s_barrier
	s_setprio 0
	s_add_i32 s70, 0, 0x18000
	s_add_i32 s71, 0, 0x1c000
	v_add_u32_e32 v140, s70, v173
	v_add_u32_e32 v182, s71, v173
	ds_read_b128 v[128:131], v140
	ds_read_b128 v[132:135], v140 offset:1024
	ds_read_b128 v[136:139], v140 offset:2048
	ds_read_b128 v[140:143], v140 offset:3072
	ds_read_b128 v[164:167], v182
	ds_read_b128 v[168:171], v182 offset:1024
	ds_read_b128 v[178:181], v182 offset:2048
	ds_read_b128 v[182:185], v182 offset:3072
	s_add_u32 s44, s44, 0x80000
	s_addc_u32 s45, s45, 0
	s_mov_b32 m0, s54
	v_lshl_add_u64 v[230:231], s[44:45], 0, v[150:151]
	ds_read_b128 v[186:189], v177 offset:32768
	ds_read_b128 v[194:197], v177 offset:33792
	ds_read_b128 v[198:201], v177 offset:34816
	ds_read_b128 v[202:205], v177 offset:35840
	ds_read_b128 v[206:209], v177 offset:36864
	ds_read_b128 v[210:213], v177 offset:37888
	ds_read_b128 v[218:221], v177 offset:38912
	ds_read_b128 v[222:225], v177 offset:39936
	global_load_lds_dwordx4 v[230:231], off
	v_lshl_add_u64 v[230:231], s[44:45], 0, v[146:147]
	s_mov_b32 m0, s55
	s_nop 0
	global_load_lds_dwordx4 v[230:231], off
	s_waitcnt vmcnt(8)
	s_waitcnt lgkmcnt(0)
	s_setprio 1
	s_barrier
	v_mfma_f32_16x16x32_bf16 v[124:127], v[128:131], v[186:189], v[124:127]
	v_mfma_f32_16x16x32_bf16 v[120:123], v[136:139], v[186:189], v[120:123]
	v_mfma_f32_16x16x32_bf16 v[116:119], v[128:131], v[198:201], v[116:119]
	v_mfma_f32_16x16x32_bf16 v[112:115], v[136:139], v[198:201], v[112:115]
	v_mfma_f32_16x16x32_bf16 v[100:103], v[128:131], v[206:209], v[100:103]
	v_mfma_f32_16x16x32_bf16 v[96:99], v[136:139], v[206:209], v[96:99]
	v_mfma_f32_16x16x32_bf16 v[84:87], v[128:131], v[218:221], v[84:87]
	v_mfma_f32_16x16x32_bf16 v[80:83], v[136:139], v[218:221], v[80:83]
	v_mfma_f32_16x16x32_bf16 v[124:127], v[132:135], v[194:197], v[124:127]
	v_mfma_f32_16x16x32_bf16 v[120:123], v[140:143], v[194:197], v[120:123]
	v_mfma_f32_16x16x32_bf16 v[116:119], v[132:135], v[202:205], v[116:119]
	v_mfma_f32_16x16x32_bf16 v[112:115], v[140:143], v[202:205], v[112:115]
	v_mfma_f32_16x16x32_bf16 v[100:103], v[132:135], v[210:213], v[100:103]
	v_mfma_f32_16x16x32_bf16 v[96:99], v[140:143], v[210:213], v[96:99]
	v_mfma_f32_16x16x32_bf16 v[84:87], v[132:135], v[222:225], v[84:87]
	v_mfma_f32_16x16x32_bf16 v[80:83], v[140:143], v[222:225], v[80:83]
	v_mfma_f32_16x16x32_bf16 v[108:111], v[164:167], v[186:189], v[108:111]
	v_mfma_f32_16x16x32_bf16 v[104:107], v[178:181], v[186:189], v[104:107]
	v_mfma_f32_16x16x32_bf16 v[92:95], v[164:167], v[198:201], v[92:95]
	v_mfma_f32_16x16x32_bf16 v[88:91], v[178:181], v[198:201], v[88:91]
	v_mfma_f32_16x16x32_bf16 v[76:79], v[164:167], v[206:209], v[76:79]
	v_mfma_f32_16x16x32_bf16 v[72:75], v[178:181], v[206:209], v[72:75]
	v_mfma_f32_16x16x32_bf16 v[68:71], v[164:167], v[218:221], v[68:71]
	v_mfma_f32_16x16x32_bf16 v[64:67], v[178:181], v[218:221], v[64:67]
	v_mfma_f32_16x16x32_bf16 v[108:111], v[168:171], v[194:197], v[108:111]
	v_mfma_f32_16x16x32_bf16 v[104:107], v[182:185], v[194:197], v[104:107]
	v_mfma_f32_16x16x32_bf16 v[92:95], v[168:171], v[202:205], v[92:95]
	v_mfma_f32_16x16x32_bf16 v[88:91], v[182:185], v[202:205], v[88:91]
	v_mfma_f32_16x16x32_bf16 v[76:79], v[168:171], v[210:213], v[76:79]
	v_mfma_f32_16x16x32_bf16 v[72:75], v[182:185], v[210:213], v[72:75]
	v_mfma_f32_16x16x32_bf16 v[68:71], v[168:171], v[222:225], v[68:71]
	v_mfma_f32_16x16x32_bf16 v[64:67], v[182:185], v[222:225], v[64:67]
	s_barrier
; #define PG8_STAGE(bufoff, gbase, voff) do { _Pragma("unroll") for (int _i = 0; _i < 2; ++_i) \
;         __builtin_amdgcn_global_load_lds((const unsigned*)((const char*)(gbase) + (voff)[_i]), (PG8_LAS unsigned*)(lds + (bufoff) + ldsw + _i * 8192), 16, 0, 0); } while (0)
; #define PG8_LDA(dst, b, h) do { _Pragma("unroll") for (int m = 0; m < 4; ++m) _Pragma("unroll") for (int k = 0; k < 2; ++k) dst[m][k] = *(const PG8_LAS bf16x8*)(lds + PG8_SA(b, h) + aoff + m * 2048 + k * 1024); } while (0)
; #define PG8_LDB(dst, b, h) do { _Pragma("unroll") for (int n = 0; n < 2; ++n) _Pragma("unroll") for (int k = 0; k < 2; ++k) dst[n][k] = *(const PG8_LAS bf16x8*)(lds + PG8_SB(b, h) + boff + n * 2048 + k * 1024); } while (0)
; #define PG8_MMA(ai, bj, At, Bt) do { __builtin_amdgcn_s_setprio(1); _Pragma("unroll") for (int m = 0; m < 4; ++m) _Pragma("unroll") for (int n = 0; n < 2; ++n) _Pragma("unroll") for (int k = 0; k < 2; ++k) \
;         acc[ai][bj][m][n] = __builtin_amdgcn_mfma_f32_16x16x32_bf16(Bt[n][k], At[m][k], acc[ai][bj][m][n], 0, 0, 0); __builtin_amdgcn_s_setprio(0); } while (0)
; #define PG8_WAIT_V(n) asm volatile("s_waitcnt vmcnt(" #n ")" ::: "memory")
; #define PG8_WAIT_L(n) asm volatile("s_waitcnt lgkmcnt(" #n ")" ::: "memory")
; #define PG8_BAR __builtin_amdgcn_s_barrier()
; #define PG8_SCHED __builtin_amdgcn_sched_barrier(0)
; template <class Epi, class Sched, bool ALIGN_EPI = false, bool SP2 = false>
; __device__ __forceinline__ void gemm_phase(PG8_LAS unsigned char* lds, const Gemm g, const Sched& S, const Epi& E) {
;     ...
;             PG8_LDB(B0, 0, 0); PG8_LDB(B1, 0, 1); PG8_SCHED; PG8_LDA(At, 0, 0); PG8_STAGE(PG8_SA(1, 1), a1 + hstep, voffA);
;             PG8_WAIT_V(8); PG8_WAIT_L(0); PG8_BAR; PG8_MMA(0, 0, At, B0); PG8_MMA(0, 1, At, B1); PG8_BAR; PG8_SCHED;
;     ...
;             PG8_LDA(At, 1, 1); PG8_STAGE(PG8_SB(1, 0), b3, voffB); PG8_STAGE(PG8_SB(1, 1), b3 + hstep, voffB); PG8_STAGE(PG8_SA(1, 0), a3, voffA);
;             PG8_WAIT_V(8); PG8_WAIT_L(0); PG8_BAR; PG8_MMA(1, 0, At, B0); PG8_MMA(1, 1, At, B1); PG8_BAR; PG8_SCHED;
	s_setprio 0
	s_add_i32 s44, s70, s50
	v_lshl_add_u64 v[190:191], v[190:191], 0, s[22:23]
	s_mov_b32 m0, s44
	ds_read_b128 v[186:189], v177 offset:49152
	ds_read_b128 v[194:197], v177 offset:50176
	ds_read_b128 v[198:201], v177 offset:51200
	ds_read_b128 v[202:205], v177 offset:52224
	ds_read_b128 v[206:209], v177 offset:53248
	ds_read_b128 v[210:213], v177 offset:54272
	ds_read_b128 v[218:221], v177 offset:55296
	ds_read_b128 v[222:225], v177 offset:56320
	global_load_lds_dwordx4 v[190:191], off
	s_add_i32 m0, s44, 0x2000
	s_add_u32 s42, s42, 0x80080
	v_lshl_add_u64 v[190:191], v[214:215], 0, s[22:23]
	s_addc_u32 s43, s43, 0
	s_add_i32 s44, s71, s50
	global_load_lds_dwordx4 v[190:191], off
	v_lshl_add_u64 v[190:191], s[42:43], 0, v[148:149]
	s_mov_b32 m0, s44
	s_nop 0
	global_load_lds_dwordx4 v[190:191], off
	v_lshl_add_u64 v[190:191], s[42:43], 0, v[144:145]
	s_add_i32 m0, s44, 0x2000
	s_nop 0
	global_load_lds_dwordx4 v[190:191], off
	v_lshl_add_u64 v[190:191], v[226:227], 0, s[22:23]
	s_mov_b32 m0, s59
	s_nop 0
	global_load_lds_dwordx4 v[190:191], off
	v_lshl_add_u64 v[190:191], v[228:229], 0, s[22:23]
	s_mov_b32 m0, s60
	s_nop 0
	global_load_lds_dwordx4 v[190:191], off
	s_waitcnt vmcnt(8)
	s_waitcnt lgkmcnt(0)
	s_setprio 1
	s_barrier
	v_mfma_f32_16x16x32_bf16 v[60:63], v[128:131], v[186:189], v[60:63]
	v_mfma_f32_16x16x32_bf16 v[56:59], v[136:139], v[186:189], v[56:59]
	v_mfma_f32_16x16x32_bf16 v[52:55], v[128:131], v[198:201], v[52:55]
	v_mfma_f32_16x16x32_bf16 v[48:51], v[136:139], v[198:201], v[48:51]
	v_mfma_f32_16x16x32_bf16 v[36:39], v[128:131], v[206:209], v[36:39]
	v_mfma_f32_16x16x32_bf16 v[32:35], v[136:139], v[206:209], v[32:35]
	v_mfma_f32_16x16x32_bf16 v[20:23], v[128:131], v[218:221], v[20:23]
	v_mfma_f32_16x16x32_bf16 v[16:19], v[136:139], v[218:221], v[16:19]
	v_mfma_f32_16x16x32_bf16 v[60:63], v[132:135], v[194:197], v[60:63]
	v_mfma_f32_16x16x32_bf16 v[56:59], v[140:143], v[194:197], v[56:59]
	v_mfma_f32_16x16x32_bf16 v[52:55], v[132:135], v[202:205], v[52:55]
	v_mfma_f32_16x16x32_bf16 v[48:51], v[140:143], v[202:205], v[48:51]
	v_mfma_f32_16x16x32_bf16 v[36:39], v[132:135], v[210:213], v[36:39]
	v_mfma_f32_16x16x32_bf16 v[32:35], v[140:143], v[210:213], v[32:35]
	v_mfma_f32_16x16x32_bf16 v[20:23], v[132:135], v[222:225], v[20:23]
	v_mfma_f32_16x16x32_bf16 v[16:19], v[140:143], v[222:225], v[16:19]
	v_mfma_f32_16x16x32_bf16 v[44:47], v[164:167], v[186:189], v[44:47]
	v_mfma_f32_16x16x32_bf16 v[40:43], v[178:181], v[186:189], v[40:43]
	v_mfma_f32_16x16x32_bf16 v[28:31], v[164:167], v[198:201], v[28:31]
	v_mfma_f32_16x16x32_bf16 v[24:27], v[178:181], v[198:201], v[24:27]
	v_mfma_f32_16x16x32_bf16 v[12:15], v[164:167], v[206:209], v[12:15]
	v_mfma_f32_16x16x32_bf16 v[8:11], v[178:181], v[206:209], v[8:11]
	v_mfma_f32_16x16x32_bf16 v[4:7], v[164:167], v[218:221], v[4:7]
	v_mfma_f32_16x16x32_bf16 v[0:3], v[178:181], v[218:221], v[0:3]
	v_mfma_f32_16x16x32_bf16 v[44:47], v[168:171], v[194:197], v[44:47]
	v_mfma_f32_16x16x32_bf16 v[40:43], v[182:185], v[194:197], v[40:43]
	v_mfma_f32_16x16x32_bf16 v[28:31], v[168:171], v[202:205], v[28:31]
	v_mfma_f32_16x16x32_bf16 v[24:27], v[182:185], v[202:205], v[24:27]
	v_mfma_f32_16x16x32_bf16 v[12:15], v[168:171], v[210:213], v[12:15]
	v_mfma_f32_16x16x32_bf16 v[8:11], v[182:185], v[210:213], v[8:11]
	v_mfma_f32_16x16x32_bf16 v[4:7], v[168:171], v[222:225], v[4:7]
	v_mfma_f32_16x16x32_bf16 v[0:3], v[182:185], v[222:225], v[0:3]
	s_barrier
	s_setprio 0
	s_add_i32 s69, s69, 2
	s_add_u32 s40, s40, 0x100
	s_addc_u32 s41, s41, 0
	s_add_u32 s67, s67, 0x100
	s_addc_u32 s68, s68, 0
	s_cmp_gt_u32 s69, 29
.LBB0_171:
	ds_read_b128 v[128:131], v175
	ds_read_b128 v[132:135], v175 offset:1024
	ds_read_b128 v[136:139], v175 offset:2048
	ds_read_b128 v[140:143], v175 offset:3072
	ds_read_b128 v[164:167], v176
	ds_read_b128 v[168:171], v176 offset:1024
	ds_read_b128 v[178:181], v176 offset:2048
	ds_read_b128 v[182:185], v176 offset:3072
	s_add_u32 s42, s40, 0xfff80080
	s_addc_u32 s43, s41, -1
	s_cmp_eq_u32 s69, 28
	s_cselect_b32 s45, s29, s43
	s_cselect_b32 s44, s37, s42
	s_cselect_b32 s43, s27, s68
	s_cselect_b32 s42, s65, s67
	v_lshl_add_u64 v[190:191], s[40:41], 0, v[156:157]
	s_add_i32 m0, s52, 0xc000
	ds_read_b128 v[186:189], v177
	ds_read_b128 v[194:197], v177 offset:1024
	ds_read_b128 v[198:201], v177 offset:2048
	ds_read_b128 v[202:205], v177 offset:3072
	ds_read_b128 v[206:209], v177 offset:4096
	ds_read_b128 v[210:213], v177 offset:5120
	ds_read_b128 v[218:221], v177 offset:6144
	ds_read_b128 v[222:225], v177 offset:7168
	global_load_lds_dwordx4 v[190:191], off
	v_lshl_add_u64 v[190:191], s[40:41], 0, v[158:159]
	s_add_i32 m0, s52, 0xe000
	s_nop 0
	global_load_lds_dwordx4 v[190:191], off
	s_waitcnt vmcnt(8)
	s_waitcnt lgkmcnt(0)
	s_setprio 1
	s_barrier
; #define PG8_STAGE(bufoff, gbase, voff) do { _Pragma("unroll") for (int _i = 0; _i < 2; ++_i) \
;         __builtin_amdgcn_global_load_lds((const unsigned*)((const char*)(gbase) + (voff)[_i]), (PG8_LAS unsigned*)(lds + (bufoff) + ldsw + _i * 8192), 16, 0, 0); } while (0)
; #define PG8_LDA(dst, b, h) do { _Pragma("unroll") for (int m = 0; m < 4; ++m) _Pragma("unroll") for (int k = 0; k < 2; ++k) dst[m][k] = *(const PG8_LAS bf16x8*)(lds + PG8_SA(b, h) + aoff + m * 2048 + k * 1024); } while (0)
; #define PG8_MMA(ai, bj, At, Bt) do { __builtin_amdgcn_s_setprio(1); _Pragma("unroll") for (int m = 0; m < 4; ++m) _Pragma("unroll") for (int n = 0; n < 2; ++n) _Pragma("unroll") for (int k = 0; k < 2; ++k) \
;         acc[ai][bj][m][n] = __builtin_amdgcn_mfma_f32_16x16x32_bf16(Bt[n][k], At[m][k], acc[ai][bj][m][n], 0, 0, 0); __builtin_amdgcn_s_setprio(0); } while (0)
; #define PG8_WAIT_V(n) asm volatile("s_waitcnt vmcnt(" #n ")" ::: "memory")
; #define PG8_WAIT_L(n) asm volatile("s_waitcnt lgkmcnt(" #n ")" ::: "memory")
; #define PG8_BAR __builtin_amdgcn_s_barrier()
; #define PG8_SCHED __builtin_amdgcn_sched_barrier(0)
; template <class Epi, class Sched, bool ALIGN_EPI = false, bool SP2 = false>
; __device__ __forceinline__ void gemm_phase(PG8_LAS unsigned char* lds, const Gemm g, const Sched& S, const Epi& E) {
;     ...
;             PG8_WAIT_V(8); PG8_WAIT_L(0); PG8_BAR; PG8_MMA(0, 0, At, B0); PG8_MMA(0, 1, At, B1); PG8_BAR; PG8_SCHED;
;             PG8_LDA(At, 0, 1); PG8_STAGE(PG8_SB(0, 0), b2, voffB); PG8_STAGE(PG8_SB(0, 1), b2 + hstep, voffB); PG8_STAGE(PG8_SA(0, 0), a2, voffA);
;             PG8_WAIT_V(8); PG8_WAIT_L(0); PG8_BAR; PG8_MMA(1, 0, At, B0); PG8_MMA(1, 1, At, B1); PG8_BAR; PG8_SCHED;
	v_mfma_f32_16x16x32_bf16 v[124:127], v[128:131], v[186:189], v[124:127]
	v_mfma_f32_16x16x32_bf16 v[120:123], v[136:139], v[186:189], v[120:123]
	v_mfma_f32_16x16x32_bf16 v[116:119], v[128:131], v[198:201], v[116:119]
	v_mfma_f32_16x16x32_bf16 v[112:115], v[136:139], v[198:201], v[112:115]
	v_mfma_f32_16x16x32_bf16 v[100:103], v[128:131], v[206:209], v[100:103]
	v_mfma_f32_16x16x32_bf16 v[96:99], v[136:139], v[206:209], v[96:99]
	v_mfma_f32_16x16x32_bf16 v[84:87], v[128:131], v[218:221], v[84:87]
	v_mfma_f32_16x16x32_bf16 v[80:83], v[136:139], v[218:221], v[80:83]
	v_mfma_f32_16x16x32_bf16 v[124:127], v[132:135], v[194:197], v[124:127]
	v_mfma_f32_16x16x32_bf16 v[120:123], v[140:143], v[194:197], v[120:123]
	v_mfma_f32_16x16x32_bf16 v[116:119], v[132:135], v[202:205], v[116:119]
	v_mfma_f32_16x16x32_bf16 v[112:115], v[140:143], v[202:205], v[112:115]
	v_mfma_f32_16x16x32_bf16 v[100:103], v[132:135], v[210:213], v[100:103]
	v_mfma_f32_16x16x32_bf16 v[96:99], v[140:143], v[210:213], v[96:99]
	v_mfma_f32_16x16x32_bf16 v[84:87], v[132:135], v[222:225], v[84:87]
	v_mfma_f32_16x16x32_bf16 v[80:83], v[140:143], v[222:225], v[80:83]
	v_mfma_f32_16x16x32_bf16 v[108:111], v[164:167], v[186:189], v[108:111]
	v_mfma_f32_16x16x32_bf16 v[104:107], v[178:181], v[186:189], v[104:107]
	v_mfma_f32_16x16x32_bf16 v[92:95], v[164:167], v[198:201], v[92:95]
	v_mfma_f32_16x16x32_bf16 v[88:91], v[178:181], v[198:201], v[88:91]
	v_mfma_f32_16x16x32_bf16 v[76:79], v[164:167], v[206:209], v[76:79]
	v_mfma_f32_16x16x32_bf16 v[72:75], v[178:181], v[206:209], v[72:75]
	v_mfma_f32_16x16x32_bf16 v[68:71], v[164:167], v[218:221], v[68:71]
	v_mfma_f32_16x16x32_bf16 v[64:67], v[178:181], v[218:221], v[64:67]
	v_mfma_f32_16x16x32_bf16 v[108:111], v[168:171], v[194:197], v[108:111]
	v_mfma_f32_16x16x32_bf16 v[104:107], v[182:185], v[194:197], v[104:107]
	v_mfma_f32_16x16x32_bf16 v[92:95], v[168:171], v[202:205], v[92:95]
	v_mfma_f32_16x16x32_bf16 v[88:91], v[182:185], v[202:205], v[88:91]
	v_mfma_f32_16x16x32_bf16 v[76:79], v[168:171], v[210:213], v[76:79]
	v_mfma_f32_16x16x32_bf16 v[72:75], v[182:185], v[210:213], v[72:75]
	v_mfma_f32_16x16x32_bf16 v[68:71], v[168:171], v[222:225], v[68:71]
	v_mfma_f32_16x16x32_bf16 v[64:67], v[182:185], v[222:225], v[64:67]
	s_barrier
	s_setprio 0
	s_add_i32 s70, s61, s50
	v_lshl_add_u64 v[190:191], s[42:43], 0, v[148:149]
	s_mov_b32 m0, s70
	ds_read_b128 v[186:189], v177 offset:16384
	ds_read_b128 v[194:197], v177 offset:17408
	ds_read_b128 v[198:201], v177 offset:18432
	ds_read_b128 v[202:205], v177 offset:19456
	ds_read_b128 v[206:209], v177 offset:20480
	ds_read_b128 v[210:213], v177 offset:21504
	ds_read_b128 v[218:221], v177 offset:22528
	ds_read_b128 v[222:225], v177 offset:23552
	global_load_lds_dwordx4 v[190:191], off
	s_add_i32 m0, s70, 0x2000
	s_add_u32 s70, s42, 0x80000
	v_lshl_add_u64 v[214:215], s[42:43], 0, v[144:145]
	s_addc_u32 s71, s43, 0
	s_add_i32 s72, s62, s50
	global_load_lds_dwordx4 v[214:215], off
	v_lshl_add_u64 v[226:227], s[70:71], 0, v[148:149]
	s_mov_b32 m0, s72
	v_lshl_add_u64 v[228:229], s[44:45], 0, v[146:147]
	global_load_lds_dwordx4 v[226:227], off
	v_lshl_add_u64 v[226:227], s[70:71], 0, v[144:145]
	s_add_i32 m0, s72, 0x2000
	s_nop 0
	global_load_lds_dwordx4 v[226:227], off
	v_lshl_add_u64 v[226:227], s[44:45], 0, v[150:151]
	s_mov_b32 m0, s52
	s_nop 0
	global_load_lds_dwordx4 v[226:227], off
	s_mov_b32 m0, s53
	s_nop 0
	global_load_lds_dwordx4 v[228:229], off
	s_waitcnt vmcnt(8)
	s_waitcnt lgkmcnt(0)
	s_setprio 1
	s_barrier
	v_mfma_f32_16x16x32_bf16 v[60:63], v[128:131], v[186:189], v[60:63]
	v_mfma_f32_16x16x32_bf16 v[56:59], v[136:139], v[186:189], v[56:59]
	v_mfma_f32_16x16x32_bf16 v[52:55], v[128:131], v[198:201], v[52:55]
	v_mfma_f32_16x16x32_bf16 v[48:51], v[136:139], v[198:201], v[48:51]
	v_mfma_f32_16x16x32_bf16 v[36:39], v[128:131], v[206:209], v[36:39]
	v_mfma_f32_16x16x32_bf16 v[32:35], v[136:139], v[206:209], v[32:35]
	v_mfma_f32_16x16x32_bf16 v[20:23], v[128:131], v[218:221], v[20:23]
	v_mfma_f32_16x16x32_bf16 v[16:19], v[136:139], v[218:221], v[16:19]
	v_mfma_f32_16x16x32_bf16 v[60:63], v[132:135], v[194:197], v[60:63]
	v_mfma_f32_16x16x32_bf16 v[56:59], v[140:143], v[194:197], v[56:59]
	v_mfma_f32_16x16x32_bf16 v[52:55], v[132:135], v[202:205], v[52:55]
	v_mfma_f32_16x16x32_bf16 v[48:51], v[140:143], v[202:205], v[48:51]
	v_mfma_f32_16x16x32_bf16 v[36:39], v[132:135], v[210:213], v[36:39]
	v_mfma_f32_16x16x32_bf16 v[32:35], v[140:143], v[210:213], v[32:35]
	v_mfma_f32_16x16x32_bf16 v[20:23], v[132:135], v[222:225], v[20:23]
	v_mfma_f32_16x16x32_bf16 v[16:19], v[140:143], v[222:225], v[16:19]
	v_mfma_f32_16x16x32_bf16 v[44:47], v[164:167], v[186:189], v[44:47]
	v_mfma_f32_16x16x32_bf16 v[40:43], v[178:181], v[186:189], v[40:43]
	v_mfma_f32_16x16x32_bf16 v[28:31], v[164:167], v[198:201], v[28:31]
	v_mfma_f32_16x16x32_bf16 v[24:27], v[178:181], v[198:201], v[24:27]
	v_mfma_f32_16x16x32_bf16 v[12:15], v[164:167], v[206:209], v[12:15]
	v_mfma_f32_16x16x32_bf16 v[8:11], v[178:181], v[206:209], v[8:11]
	v_mfma_f32_16x16x32_bf16 v[4:7], v[164:167], v[218:221], v[4:7]
	v_mfma_f32_16x16x32_bf16 v[0:3], v[178:181], v[218:221], v[0:3]
	v_mfma_f32_16x16x32_bf16 v[44:47], v[168:171], v[194:197], v[44:47]
	v_mfma_f32_16x16x32_bf16 v[40:43], v[182:185], v[194:197], v[40:43]
	v_mfma_f32_16x16x32_bf16 v[28:31], v[168:171], v[202:205], v[28:31]
	v_mfma_f32_16x16x32_bf16 v[24:27], v[182:185], v[202:205], v[24:27]
	v_mfma_f32_16x16x32_bf16 v[12:15], v[168:171], v[210:213], v[12:15]
	v_mfma_f32_16x16x32_bf16 v[8:11], v[182:185], v[210:213], v[8:11]
	v_mfma_f32_16x16x32_bf16 v[4:7], v[168:171], v[222:225], v[4:7]
	v_mfma_f32_16x16x32_bf16 v[0:3], v[182:185], v[222:225], v[0:3]
	s_barrier
; #define PG8_STAGE(bufoff, gbase, voff) do { _Pragma("unroll") for (int _i = 0; _i < 2; ++_i) \
;         __builtin_amdgcn_global_load_lds((const unsigned*)((const char*)(gbase) + (voff)[_i]), (PG8_LAS unsigned*)(lds + (bufoff) + ldsw + _i * 8192), 16, 0, 0); } while (0)
; #define PG8_LDA(dst, b, h) do { _Pragma("unroll") for (int m = 0; m < 4; ++m) _Pragma("unroll") for (int k = 0; k < 2; ++k) dst[m][k] = *(const PG8_LAS bf16x8*)(lds + PG8_SA(b, h) + aoff + m * 2048 + k * 1024); } while (0)
; #define PG8_LDB(dst, b, h) do { _Pragma("unroll") for (int n = 0; n < 2; ++n) _Pragma("unroll") for (int k = 0; k < 2; ++k) dst[n][k] = *(const PG8_LAS bf16x8*)(lds + PG8_SB(b, h) + boff + n * 2048 + k * 1024); } while (0)
; #define PG8_MMA(ai, bj, At, Bt) do { __builtin_amdgcn_s_setprio(1); _Pragma("unroll") for (int m = 0; m < 4; ++m) _Pragma("unroll") for (int n = 0; n < 2; ++n) _Pragma("unroll") for (int k = 0; k < 2; ++k) \
;         acc[ai][bj][m][n] = __builtin_amdgcn_mfma_f32_16x16x32_bf16(Bt[n][k], At[m][k], acc[ai][bj][m][n], 0, 0, 0); __builtin_amdgcn_s_setprio(0); } while (0)
; #define PG8_WAIT_V(n) asm volatile("s_waitcnt vmcnt(" #n ")" ::: "memory")
; #define PG8_WAIT_L(n) asm volatile("s_waitcnt lgkmcnt(" #n ")" ::: "memory")
; #define PG8_BAR __builtin_amdgcn_s_barrier()
; #define PG8_SCHED __builtin_amdgcn_sched_barrier(0)
; template <class Epi, class Sched, bool ALIGN_EPI = false, bool SP2 = false>
; __device__ __forceinline__ void gemm_phase(PG8_LAS unsigned char* lds, const Gemm g, const Sched& S, const Epi& E) {
;     ...
;             PG8_LDB(B0, 1, 0); PG8_LDB(B1, 1, 1); PG8_SCHED; PG8_LDA(At, 1, 0); PG8_STAGE(PG8_SA(0, 1), a2 + hstep, voffA);
;             PG8_WAIT_V(8); PG8_WAIT_L(0); PG8_BAR; PG8_MMA(0, 0, At, B0); PG8_MMA(0, 1, At, B1); PG8_BAR; PG8_SCHED;
	s_setprio 0
	s_add_i32 s70, 0, 0x18000
	s_add_i32 s71, 0, 0x1c000
	v_add_u32_e32 v140, s70, v173
	v_add_u32_e32 v182, s71, v173
	ds_read_b128 v[128:131], v140
	ds_read_b128 v[132:135], v140 offset:1024
	ds_read_b128 v[136:139], v140 offset:2048
	ds_read_b128 v[140:143], v140 offset:3072
	ds_read_b128 v[164:167], v182
	ds_read_b128 v[168:171], v182 offset:1024
	ds_read_b128 v[178:181], v182 offset:2048
	ds_read_b128 v[182:185], v182 offset:3072
	s_add_u32 s44, s44, 0x80000
	s_addc_u32 s45, s45, 0
	s_mov_b32 m0, s54
	v_lshl_add_u64 v[230:231], s[44:45], 0, v[150:151]
	ds_read_b128 v[186:189], v177 offset:32768
	ds_read_b128 v[194:197], v177 offset:33792
	ds_read_b128 v[198:201], v177 offset:34816
	ds_read_b128 v[202:205], v177 offset:35840
	ds_read_b128 v[206:209], v177 offset:36864
	ds_read_b128 v[210:213], v177 offset:37888
	ds_read_b128 v[218:221], v177 offset:38912
	ds_read_b128 v[222:225], v177 offset:39936
	global_load_lds_dwordx4 v[230:231], off
	v_lshl_add_u64 v[230:231], s[44:45], 0, v[146:147]
	s_mov_b32 m0, s55
	s_nop 0
	global_load_lds_dwordx4 v[230:231], off
	s_waitcnt vmcnt(8)
	s_waitcnt lgkmcnt(0)
	s_setprio 1
	s_barrier
	v_mfma_f32_16x16x32_bf16 v[124:127], v[128:131], v[186:189], v[124:127]
	v_mfma_f32_16x16x32_bf16 v[120:123], v[136:139], v[186:189], v[120:123]
	v_mfma_f32_16x16x32_bf16 v[116:119], v[128:131], v[198:201], v[116:119]
	v_mfma_f32_16x16x32_bf16 v[112:115], v[136:139], v[198:201], v[112:115]
	v_mfma_f32_16x16x32_bf16 v[100:103], v[128:131], v[206:209], v[100:103]
	v_mfma_f32_16x16x32_bf16 v[96:99], v[136:139], v[206:209], v[96:99]
	v_mfma_f32_16x16x32_bf16 v[84:87], v[128:131], v[218:221], v[84:87]
	v_mfma_f32_16x16x32_bf16 v[80:83], v[136:139], v[218:221], v[80:83]
	v_mfma_f32_16x16x32_bf16 v[124:127], v[132:135], v[194:197], v[124:127]
	v_mfma_f32_16x16x32_bf16 v[120:123], v[140:143], v[194:197], v[120:123]
	v_mfma_f32_16x16x32_bf16 v[116:119], v[132:135], v[202:205], v[116:119]
	v_mfma_f32_16x16x32_bf16 v[112:115], v[140:143], v[202:205], v[112:115]
	v_mfma_f32_16x16x32_bf16 v[100:103], v[132:135], v[210:213], v[100:103]
	v_mfma_f32_16x16x32_bf16 v[96:99], v[140:143], v[210:213], v[96:99]
	v_mfma_f32_16x16x32_bf16 v[84:87], v[132:135], v[222:225], v[84:87]
	v_mfma_f32_16x16x32_bf16 v[80:83], v[140:143], v[222:225], v[80:83]
	v_mfma_f32_16x16x32_bf16 v[108:111], v[164:167], v[186:189], v[108:111]
	v_mfma_f32_16x16x32_bf16 v[104:107], v[178:181], v[186:189], v[104:107]
	v_mfma_f32_16x16x32_bf16 v[92:95], v[164:167], v[198:201], v[92:95]
	v_mfma_f32_16x16x32_bf16 v[88:91], v[178:181], v[198:201], v[88:91]
	v_mfma_f32_16x16x32_bf16 v[76:79], v[164:167], v[206:209], v[76:79]
	v_mfma_f32_16x16x32_bf16 v[72:75], v[178:181], v[206:209], v[72:75]
	v_mfma_f32_16x16x32_bf16 v[68:71], v[164:167], v[218:221], v[68:71]
	v_mfma_f32_16x16x32_bf16 v[64:67], v[178:181], v[218:221], v[64:67]
	v_mfma_f32_16x16x32_bf16 v[108:111], v[168:171], v[194:197], v[108:111]
	v_mfma_f32_16x16x32_bf16 v[104:107], v[182:185], v[194:197], v[104:107]
	v_mfma_f32_16x16x32_bf16 v[92:95], v[168:171], v[202:205], v[92:95]
	v_mfma_f32_16x16x32_bf16 v[88:91], v[182:185], v[202:205], v[88:91]
	v_mfma_f32_16x16x32_bf16 v[76:79], v[168:171], v[210:213], v[76:79]
	v_mfma_f32_16x16x32_bf16 v[72:75], v[182:185], v[210:213], v[72:75]
	v_mfma_f32_16x16x32_bf16 v[68:71], v[168:171], v[222:225], v[68:71]
	v_mfma_f32_16x16x32_bf16 v[64:67], v[182:185], v[222:225], v[64:67]
	s_barrier
; #define PG8_STAGE(bufoff, gbase, voff) do { _Pragma("unroll") for (int _i = 0; _i < 2; ++_i) \
;         __builtin_amdgcn_global_load_lds((const unsigned*)((const char*)(gbase) + (voff)[_i]), (PG8_LAS unsigned*)(lds + (bufoff) + ldsw + _i * 8192), 16, 0, 0); } while (0)
; #define PG8_LDA(dst, b, h) do { _Pragma("unroll") for (int m = 0; m < 4; ++m) _Pragma("unroll") for (int k = 0; k < 2; ++k) dst[m][k] = *(const PG8_LAS bf16x8*)(lds + PG8_SA(b, h) + aoff + m * 2048 + k * 1024); } while (0)
; #define PG8_MMA(ai, bj, At, Bt) do { __builtin_amdgcn_s_setprio(1); _Pragma("unroll") for (int m = 0; m < 4; ++m) _Pragma("unroll") for (int n = 0; n < 2; ++n) _Pragma("unroll") for (int k = 0; k < 2; ++k) \
;         acc[ai][bj][m][n] = __builtin_amdgcn_mfma_f32_16x16x32_bf16(Bt[n][k], At[m][k], acc[ai][bj][m][n], 0, 0, 0); __builtin_amdgcn_s_setprio(0); } while (0)
; #define PG8_WAIT_V(n) asm volatile("s_waitcnt vmcnt(" #n ")" ::: "memory")
; #define PG8_WAIT_L(n) asm volatile("s_waitcnt lgkmcnt(" #n ")" ::: "memory")
; #define PG8_BAR __builtin_amdgcn_s_barrier()
; #define PG8_SCHED __builtin_amdgcn_sched_barrier(0)
; template <class Epi, class Sched, bool ALIGN_EPI = false, bool SP2 = false>
; __device__ __forceinline__ void gemm_phase(PG8_LAS unsigned char* lds, const Gemm g, const Sched& S, const Epi& E) {
;     ...
;             PG8_LDA(At, 1, 1); PG8_STAGE(PG8_SB(1, 0), b3, voffB); PG8_STAGE(PG8_SB(1, 1), b3 + hstep, voffB); PG8_STAGE(PG8_SA(1, 0), a3, voffA);
;             PG8_WAIT_V(8); PG8_WAIT_L(0); PG8_BAR; PG8_MMA(1, 0, At, B0); PG8_MMA(1, 1, At, B1); PG8_BAR; PG8_SCHED;
;     ...
;         if constexpr (ALIGN_EPI) { if (wr == 0) PG8_BAR; }
	s_setprio 0
	s_add_i32 s44, s70, s50
	v_lshl_add_u64 v[190:191], v[190:191], 0, s[22:23]
	s_mov_b32 m0, s44
	ds_read_b128 v[186:189], v177 offset:49152
	ds_read_b128 v[194:197], v177 offset:50176
	ds_read_b128 v[198:201], v177 offset:51200
	ds_read_b128 v[202:205], v177 offset:52224
	ds_read_b128 v[206:209], v177 offset:53248
	ds_read_b128 v[210:213], v177 offset:54272
	ds_read_b128 v[218:221], v177 offset:55296
	ds_read_b128 v[222:225], v177 offset:56320
	global_load_lds_dwordx4 v[190:191], off
	s_add_i32 m0, s44, 0x2000
	s_add_u32 s42, s42, 0x80080
	v_lshl_add_u64 v[190:191], v[214:215], 0, s[22:23]
	s_addc_u32 s43, s43, 0
	s_add_i32 s44, s71, s50
	global_load_lds_dwordx4 v[190:191], off
	v_lshl_add_u64 v[190:191], s[42:43], 0, v[148:149]
	s_mov_b32 m0, s44
	s_nop 0
	global_load_lds_dwordx4 v[190:191], off
	v_lshl_add_u64 v[190:191], s[42:43], 0, v[144:145]
	s_add_i32 m0, s44, 0x2000
	s_nop 0
	global_load_lds_dwordx4 v[190:191], off
	v_lshl_add_u64 v[190:191], v[226:227], 0, s[22:23]
	s_mov_b32 m0, s59
	s_nop 0
	global_load_lds_dwordx4 v[190:191], off
	v_lshl_add_u64 v[190:191], v[228:229], 0, s[22:23]
	s_mov_b32 m0, s60
	s_nop 0
	global_load_lds_dwordx4 v[190:191], off
	s_waitcnt vmcnt(8)
	s_waitcnt lgkmcnt(0)
	s_setprio 1
	s_barrier
	v_mfma_f32_16x16x32_bf16 v[60:63], v[128:131], v[186:189], v[60:63]
	v_mfma_f32_16x16x32_bf16 v[56:59], v[136:139], v[186:189], v[56:59]
	v_mfma_f32_16x16x32_bf16 v[52:55], v[128:131], v[198:201], v[52:55]
	v_mfma_f32_16x16x32_bf16 v[48:51], v[136:139], v[198:201], v[48:51]
	v_mfma_f32_16x16x32_bf16 v[36:39], v[128:131], v[206:209], v[36:39]
	v_mfma_f32_16x16x32_bf16 v[32:35], v[136:139], v[206:209], v[32:35]
	v_mfma_f32_16x16x32_bf16 v[20:23], v[128:131], v[218:221], v[20:23]
	v_mfma_f32_16x16x32_bf16 v[16:19], v[136:139], v[218:221], v[16:19]
	v_mfma_f32_16x16x32_bf16 v[60:63], v[132:135], v[194:197], v[60:63]
	v_mfma_f32_16x16x32_bf16 v[56:59], v[140:143], v[194:197], v[56:59]
	v_mfma_f32_16x16x32_bf16 v[52:55], v[132:135], v[202:205], v[52:55]
	v_mfma_f32_16x16x32_bf16 v[48:51], v[140:143], v[202:205], v[48:51]
	v_mfma_f32_16x16x32_bf16 v[36:39], v[132:135], v[210:213], v[36:39]
	v_mfma_f32_16x16x32_bf16 v[32:35], v[140:143], v[210:213], v[32:35]
	v_mfma_f32_16x16x32_bf16 v[20:23], v[132:135], v[222:225], v[20:23]
	v_mfma_f32_16x16x32_bf16 v[16:19], v[140:143], v[222:225], v[16:19]
	v_mfma_f32_16x16x32_bf16 v[44:47], v[164:167], v[186:189], v[44:47]
	v_mfma_f32_16x16x32_bf16 v[40:43], v[178:181], v[186:189], v[40:43]
	v_mfma_f32_16x16x32_bf16 v[28:31], v[164:167], v[198:201], v[28:31]
	v_mfma_f32_16x16x32_bf16 v[24:27], v[178:181], v[198:201], v[24:27]
	v_mfma_f32_16x16x32_bf16 v[12:15], v[164:167], v[206:209], v[12:15]
	v_mfma_f32_16x16x32_bf16 v[8:11], v[178:181], v[206:209], v[8:11]
	v_mfma_f32_16x16x32_bf16 v[4:7], v[164:167], v[218:221], v[4:7]
	v_mfma_f32_16x16x32_bf16 v[0:3], v[178:181], v[218:221], v[0:3]
	v_mfma_f32_16x16x32_bf16 v[44:47], v[168:171], v[194:197], v[44:47]
	v_mfma_f32_16x16x32_bf16 v[40:43], v[182:185], v[194:197], v[40:43]
	v_mfma_f32_16x16x32_bf16 v[28:31], v[168:171], v[202:205], v[28:31]
	v_mfma_f32_16x16x32_bf16 v[24:27], v[182:185], v[202:205], v[24:27]
	v_mfma_f32_16x16x32_bf16 v[12:15], v[168:171], v[210:213], v[12:15]
	v_mfma_f32_16x16x32_bf16 v[8:11], v[182:185], v[210:213], v[8:11]
	v_mfma_f32_16x16x32_bf16 v[4:7], v[168:171], v[222:225], v[4:7]
	v_mfma_f32_16x16x32_bf16 v[0:3], v[182:185], v[222:225], v[0:3]
	s_barrier
	s_setprio 0
	s_add_i32 s69, s69, 2
	s_add_u32 s40, s40, 0x100
	s_addc_u32 s41, s41, 0
	s_add_u32 s67, s67, 0x100
	s_addc_u32 s68, s68, 0
	s_cmp_gt_u32 s69, 29
	s_cbranch_scc0 .LBB0_171
	s_and_b64 vcc, exec, s[24:25]
	s_cbranch_vccz .LBB0_174
	s_barrier

; #define PG8_STAGE(bufoff, gbase, voff) do { _Pragma("unroll") for (int _i = 0; _i < 2; ++_i) \
;         __builtin_amdgcn_global_load_lds((const unsigned*)((const char*)(gbase) + (voff)[_i]), (PG8_LAS unsigned*)(lds + (bufoff) + ldsw + _i * 8192), 16, 0, 0); } while (0)
; #define PG8_LDA(dst, b, h) do { _Pragma("unroll") for (int m = 0; m < 4; ++m) _Pragma("unroll") for (int k = 0; k < 2; ++k) dst[m][k] = *(const PG8_LAS bf16x8*)(lds + PG8_SA(b, h) + aoff + m * 2048 + k * 1024); } while (0)
; #define PG8_LDB(dst, b, h) do { _Pragma("unroll") for (int n = 0; n < 2; ++n) _Pragma("unroll") for (int k = 0; k < 2; ++k) dst[n][k] = *(const PG8_LAS bf16x8*)(lds + PG8_SB(b, h) + boff + n * 2048 + k * 1024); } while (0)
; #define PG8_MMA(ai, bj, At, Bt) do { __builtin_amdgcn_s_setprio(1); _Pragma("unroll") for (int m = 0; m < 4; ++m) _Pragma("unroll") for (int n = 0; n < 2; ++n) _Pragma("unroll") for (int k = 0; k < 2; ++k) \
;         acc[ai][bj][m][n] = __builtin_amdgcn_mfma_f32_16x16x32_bf16(Bt[n][k], At[m][k], acc[ai][bj][m][n], 0, 0, 0); __builtin_amdgcn_s_setprio(0); } while (0)
; #define PG8_BAR __builtin_amdgcn_s_barrier()
; template <class Epi, class Sched, bool ALIGN_EPI = false, bool SP2 = false>
; __device__ __forceinline__ void gemm_phase(PG8_LAS unsigned char* lds, const Gemm g, const Sched& S, const Epi& E) {
;     ...
;         const bool has_next = S.next(ui + 1, nxt);
;         const char* nA = has_next ? (const char*)g.A + (size_t)nxt.pm * tstep : cA; const char* nB = has_next ? (const char*)g.Bt + (size_t)nxt.pn * tstep : cB;
;         for (int t = 0; t < nt; t += 2) {
;             const bool last = (t == nt - 2);
;             const char* a1 = cA + (size_t)(t + 1) * kstep;
;             const char* a2 = last ? nA : cA + (size_t)(t + 2) * kstep; const char* b2 = last ? nB : cB + (size_t)(t + 2) * kstep;
;             const char* a3 = a2 + kstep; const char* b3 = b2 + kstep;
;             if (last && has_next) S.a_ready(nxt);
;             if constexpr (SP2) {
;             PG8_LDB(B0, 0, 0); PG8_LDB(B1, 0, 1); PG8_SCHED; PG8_LDA(At, 0, 0); PG8_STAGE(PG8_SA(1, 1), a1 + hstep, voffA);
;             PG8_WAIT_V(8); PG8_WAIT_L(0); PG8_BAR; PG8_MMA(0, 0, At, B0); PG8_MMA(0, 1, At, B1); PG8_BAR; PG8_SCHED;
;             PG8_LDA(At, 0, 1); PG8_STAGE(PG8_SB(0, 0), b2, voffB); PG8_STAGE(PG8_SB(0, 1), b2 + hstep, voffB); PG8_STAGE(PG8_SA(0, 0), a2, voffA);
.LBB0_552:
	s_ashr_i32 s35, s34, 31
	s_lshl_b64 s[36:37], s[34:35], 19
	s_add_u32 s36, s13, s36
	s_addc_u32 s37, s47, s37
	s_and_b64 s[40:41], s[38:39], exec
	s_cselect_b32 s35, s37, s51
	s_cselect_b32 s72, s36, s50
	s_ashr_i32 s31, s30, 31
	s_lshl_b64 s[40:41], s[30:31], 19
	s_add_u32 s40, s60, s40
	s_addc_u32 s41, s61, s41
	s_and_b64 s[54:55], s[38:39], exec
	s_cselect_b32 s31, s41, s53
	s_cselect_b32 s73, s40, s52
	s_add_u32 s50, s50, 0x40080
	s_addc_u32 s51, s51, 0
	s_add_u32 s74, s52, 0x100
	s_addc_u32 s75, s53, 0
	s_mov_b32 s76, -2
	s_waitcnt vmcnt(0)
	ds_read_b128 v[128:131], v181
	ds_read_b128 v[132:135], v181 offset:1024
	ds_read_b128 v[136:139], v181 offset:2048
	ds_read_b128 v[140:143], v181 offset:3072
	ds_read_b128 v[144:147], v182
	ds_read_b128 v[148:151], v182 offset:1024
	ds_read_b128 v[168:171], v182 offset:2048
	ds_read_b128 v[172:175], v182 offset:3072
	s_add_u32 s52, s50, 0xfffc0080
	s_addc_u32 s53, s51, -1
	s_cmp_eq_u32 s76, 12
	s_cselect_b32 s55, s35, s53
	s_cselect_b32 s54, s72, s52
	s_cselect_b32 s53, s31, s75
	s_cselect_b32 s52, s73, s74
	v_lshl_add_u64 v[176:177], s[50:51], 0, v[160:161]
	s_add_i32 m0, s63, 0xc000
	ds_read_b128 v[184:187], v183
	ds_read_b128 v[188:191], v183 offset:1024
	ds_read_b128 v[194:197], v183 offset:2048
	ds_read_b128 v[198:201], v183 offset:3072
	ds_read_b128 v[202:205], v183 offset:4096
	ds_read_b128 v[206:209], v183 offset:5120
	ds_read_b128 v[210:213], v183 offset:6144
	ds_read_b128 v[218:221], v183 offset:7168
	global_load_lds_dwordx4 v[176:177], off
	v_lshl_add_u64 v[176:177], s[50:51], 0, v[162:163]
	s_add_i32 m0, s63, 0xe000
	s_nop 0
	global_load_lds_dwordx4 v[176:177], off
	s_waitcnt vmcnt(8)
	s_waitcnt lgkmcnt(0)
	s_setprio 1
	s_barrier
	v_mfma_f32_16x16x32_bf16 v[124:127], v[128:131], v[184:187], 0
	v_mfma_f32_16x16x32_bf16 v[120:123], v[136:139], v[184:187], 0
	v_mfma_f32_16x16x32_bf16 v[108:111], v[128:131], v[194:197], 0
	v_mfma_f32_16x16x32_bf16 v[104:107], v[136:139], v[194:197], 0
	v_mfma_f32_16x16x32_bf16 v[96:99], v[128:131], v[202:205], 0
	v_mfma_f32_16x16x32_bf16 v[88:91], v[136:139], v[202:205], 0
	v_mfma_f32_16x16x32_bf16 v[80:83], v[128:131], v[210:213], 0
	v_mfma_f32_16x16x32_bf16 v[72:75], v[136:139], v[210:213], 0
	v_mfma_f32_16x16x32_bf16 v[124:127], v[132:135], v[188:191], v[124:127]
	v_mfma_f32_16x16x32_bf16 v[120:123], v[140:143], v[188:191], v[120:123]
	v_mfma_f32_16x16x32_bf16 v[108:111], v[132:135], v[198:201], v[108:111]
	v_mfma_f32_16x16x32_bf16 v[104:107], v[140:143], v[198:201], v[104:107]
	v_mfma_f32_16x16x32_bf16 v[96:99], v[132:135], v[206:209], v[96:99]
	v_mfma_f32_16x16x32_bf16 v[88:91], v[140:143], v[206:209], v[88:91]
	v_mfma_f32_16x16x32_bf16 v[80:83], v[132:135], v[218:221], v[80:83]
	v_mfma_f32_16x16x32_bf16 v[72:75], v[140:143], v[218:221], v[72:75]
	v_mfma_f32_16x16x32_bf16 v[116:119], v[144:147], v[184:187], 0
	v_mfma_f32_16x16x32_bf16 v[112:115], v[168:171], v[184:187], 0
	v_mfma_f32_16x16x32_bf16 v[100:103], v[144:147], v[194:197], 0
	v_mfma_f32_16x16x32_bf16 v[92:95], v[168:171], v[194:197], 0
	v_mfma_f32_16x16x32_bf16 v[84:87], v[144:147], v[202:205], 0
	v_mfma_f32_16x16x32_bf16 v[76:79], v[168:171], v[202:205], 0
	v_mfma_f32_16x16x32_bf16 v[68:71], v[144:147], v[210:213], 0
	v_mfma_f32_16x16x32_bf16 v[64:67], v[168:171], v[210:213], 0
	v_mfma_f32_16x16x32_bf16 v[116:119], v[148:151], v[188:191], v[116:119]
	v_mfma_f32_16x16x32_bf16 v[112:115], v[172:175], v[188:191], v[112:115]
	v_mfma_f32_16x16x32_bf16 v[100:103], v[148:151], v[198:201], v[100:103]
	v_mfma_f32_16x16x32_bf16 v[92:95], v[172:175], v[198:201], v[92:95]
	v_mfma_f32_16x16x32_bf16 v[84:87], v[148:151], v[206:209], v[84:87]
	v_mfma_f32_16x16x32_bf16 v[76:79], v[172:175], v[206:209], v[76:79]
	v_mfma_f32_16x16x32_bf16 v[68:71], v[148:151], v[218:221], v[68:71]
	v_mfma_f32_16x16x32_bf16 v[64:67], v[172:175], v[218:221], v[64:67]
	s_barrier
	s_setprio 0
	s_add_i32 s77, s70, s62
	v_lshl_add_u64 v[176:177], s[52:53], 0, v[156:157]
	s_mov_b32 m0, s77
	ds_read_b128 v[184:187], v183 offset:16384
	ds_read_b128 v[188:191], v183 offset:17408
	ds_read_b128 v[194:197], v183 offset:18432
	ds_read_b128 v[198:201], v183 offset:19456
	ds_read_b128 v[202:205], v183 offset:20480
	ds_read_b128 v[206:209], v183 offset:21504
	ds_read_b128 v[210:213], v183 offset:22528
	ds_read_b128 v[218:221], v183 offset:23552
	global_load_lds_dwordx4 v[176:177], off
	s_add_i32 m0, s77, 0x2000
	s_add_u32 s78, s52, 0x40000
	v_lshl_add_u64 v[214:215], s[52:53], 0, v[152:153]
	s_addc_u32 s79, s53, 0
	s_add_i32 s77, s71, s62
	global_load_lds_dwordx4 v[214:215], off
	v_lshl_add_u64 v[222:223], s[78:79], 0, v[156:157]
	s_mov_b32 m0, s77
	v_lshl_add_u64 v[224:225], s[54:55], 0, v[154:155]
	global_load_lds_dwordx4 v[222:223], off
	v_lshl_add_u64 v[222:223], s[78:79], 0, v[152:153]
	s_add_i32 m0, s77, 0x2000
	s_nop 0
	global_load_lds_dwordx4 v[222:223], off
	v_lshl_add_u64 v[222:223], s[54:55], 0, v[158:159]
	s_mov_b32 m0, s63
	s_nop 0
	global_load_lds_dwordx4 v[222:223], off
	s_mov_b32 m0, s64
	s_nop 0
	global_load_lds_dwordx4 v[224:225], off
	s_waitcnt vmcnt(8)
	s_waitcnt lgkmcnt(0)
	s_setprio 1
	s_barrier
; #define PG8_STAGE(bufoff, gbase, voff) do { _Pragma("unroll") for (int _i = 0; _i < 2; ++_i) \
;         __builtin_amdgcn_global_load_lds((const unsigned*)((const char*)(gbase) + (voff)[_i]), (PG8_LAS unsigned*)(lds + (bufoff) + ldsw + _i * 8192), 16, 0, 0); } while (0)
; #define PG8_LDA(dst, b, h) do { _Pragma("unroll") for (int m = 0; m < 4; ++m) _Pragma("unroll") for (int k = 0; k < 2; ++k) dst[m][k] = *(const PG8_LAS bf16x8*)(lds + PG8_SA(b, h) + aoff + m * 2048 + k * 1024); } while (0)
; #define PG8_LDB(dst, b, h) do { _Pragma("unroll") for (int n = 0; n < 2; ++n) _Pragma("unroll") for (int k = 0; k < 2; ++k) dst[n][k] = *(const PG8_LAS bf16x8*)(lds + PG8_SB(b, h) + boff + n * 2048 + k * 1024); } while (0)
; #define PG8_MMA(ai, bj, At, Bt) do { __builtin_amdgcn_s_setprio(1); _Pragma("unroll") for (int m = 0; m < 4; ++m) _Pragma("unroll") for (int n = 0; n < 2; ++n) _Pragma("unroll") for (int k = 0; k < 2; ++k) \
;         acc[ai][bj][m][n] = __builtin_amdgcn_mfma_f32_16x16x32_bf16(Bt[n][k], At[m][k], acc[ai][bj][m][n], 0, 0, 0); __builtin_amdgcn_s_setprio(0); } while (0)
; #define PG8_WAIT_V(n) asm volatile("s_waitcnt vmcnt(" #n ")" ::: "memory")
; #define PG8_WAIT_L(n) asm volatile("s_waitcnt lgkmcnt(" #n ")" ::: "memory")
; #define PG8_BAR __builtin_amdgcn_s_barrier()
; #define PG8_SCHED __builtin_amdgcn_sched_barrier(0)
; template <class Epi, class Sched, bool ALIGN_EPI = false, bool SP2 = false>
; __device__ __forceinline__ void gemm_phase(PG8_LAS unsigned char* lds, const Gemm g, const Sched& S, const Epi& E) {
;     ...
;             PG8_WAIT_V(8); PG8_WAIT_L(0); PG8_BAR; PG8_MMA(1, 0, At, B0); PG8_MMA(1, 1, At, B1); PG8_BAR; PG8_SCHED;
;             PG8_LDB(B0, 1, 0); PG8_LDB(B1, 1, 1); PG8_SCHED; PG8_LDA(At, 1, 0); PG8_STAGE(PG8_SA(0, 1), a2 + hstep, voffA);
;             PG8_WAIT_V(8); PG8_WAIT_L(0); PG8_BAR; PG8_MMA(0, 0, At, B0); PG8_MMA(0, 1, At, B1); PG8_BAR; PG8_SCHED;
	v_mfma_f32_16x16x32_bf16 v[60:63], v[128:131], v[184:187], 0
	v_mfma_f32_16x16x32_bf16 v[56:59], v[136:139], v[184:187], 0
	v_mfma_f32_16x16x32_bf16 v[48:51], v[128:131], v[194:197], 0
	v_mfma_f32_16x16x32_bf16 v[40:43], v[136:139], v[194:197], 0
	v_mfma_f32_16x16x32_bf16 v[32:35], v[128:131], v[202:205], 0
	v_mfma_f32_16x16x32_bf16 v[24:27], v[136:139], v[202:205], 0
	v_mfma_f32_16x16x32_bf16 v[16:19], v[128:131], v[210:213], 0
	v_mfma_f32_16x16x32_bf16 v[8:11], v[136:139], v[210:213], 0
	v_mfma_f32_16x16x32_bf16 v[60:63], v[132:135], v[188:191], v[60:63]
	v_mfma_f32_16x16x32_bf16 v[56:59], v[140:143], v[188:191], v[56:59]
	v_mfma_f32_16x16x32_bf16 v[48:51], v[132:135], v[198:201], v[48:51]
	v_mfma_f32_16x16x32_bf16 v[40:43], v[140:143], v[198:201], v[40:43]
	v_mfma_f32_16x16x32_bf16 v[32:35], v[132:135], v[206:209], v[32:35]
	v_mfma_f32_16x16x32_bf16 v[24:27], v[140:143], v[206:209], v[24:27]
	v_mfma_f32_16x16x32_bf16 v[16:19], v[132:135], v[218:221], v[16:19]
	v_mfma_f32_16x16x32_bf16 v[8:11], v[140:143], v[218:221], v[8:11]
	v_mfma_f32_16x16x32_bf16 v[52:55], v[144:147], v[184:187], 0
	v_mfma_f32_16x16x32_bf16 v[44:47], v[168:171], v[184:187], 0
	v_mfma_f32_16x16x32_bf16 v[36:39], v[144:147], v[194:197], 0
	v_mfma_f32_16x16x32_bf16 v[28:31], v[168:171], v[194:197], 0
	v_mfma_f32_16x16x32_bf16 v[20:23], v[144:147], v[202:205], 0
	v_mfma_f32_16x16x32_bf16 v[12:15], v[168:171], v[202:205], 0
	v_mfma_f32_16x16x32_bf16 v[4:7], v[144:147], v[210:213], 0
	v_mfma_f32_16x16x32_bf16 v[0:3], v[168:171], v[210:213], 0
	v_mfma_f32_16x16x32_bf16 v[52:55], v[148:151], v[188:191], v[52:55]
	v_mfma_f32_16x16x32_bf16 v[44:47], v[172:175], v[188:191], v[44:47]
	v_mfma_f32_16x16x32_bf16 v[36:39], v[148:151], v[198:201], v[36:39]
	v_mfma_f32_16x16x32_bf16 v[28:31], v[172:175], v[198:201], v[28:31]
	v_mfma_f32_16x16x32_bf16 v[20:23], v[148:151], v[206:209], v[20:23]
	v_mfma_f32_16x16x32_bf16 v[12:15], v[172:175], v[206:209], v[12:15]
	v_mfma_f32_16x16x32_bf16 v[4:7], v[148:151], v[218:221], v[4:7]
	v_mfma_f32_16x16x32_bf16 v[0:3], v[172:175], v[218:221], v[0:3]
	s_barrier
	s_setprio 0
	s_add_i32 s77, 0, 0x18000
	s_add_i32 s78, 0, 0x1c000
	v_add_u32_e32 v140, s77, v179
	v_add_u32_e32 v172, s78, v179
	ds_read_b128 v[128:131], v140
	ds_read_b128 v[132:135], v140 offset:1024
	ds_read_b128 v[136:139], v140 offset:2048
	ds_read_b128 v[140:143], v140 offset:3072
	ds_read_b128 v[144:147], v172
	ds_read_b128 v[148:151], v172 offset:1024
	ds_read_b128 v[168:171], v172 offset:2048
	ds_read_b128 v[172:175], v172 offset:3072
	s_add_u32 s54, s54, 0x40000
	s_addc_u32 s55, s55, 0
	s_mov_b32 m0, s65
	v_lshl_add_u64 v[226:227], s[54:55], 0, v[158:159]
	ds_read_b128 v[184:187], v183 offset:32768
	ds_read_b128 v[188:191], v183 offset:33792
	ds_read_b128 v[194:197], v183 offset:34816
	ds_read_b128 v[198:201], v183 offset:35840
	ds_read_b128 v[202:205], v183 offset:36864
	ds_read_b128 v[206:209], v183 offset:37888
	ds_read_b128 v[210:213], v183 offset:38912
	ds_read_b128 v[218:221], v183 offset:39936
	global_load_lds_dwordx4 v[226:227], off
	v_lshl_add_u64 v[226:227], s[54:55], 0, v[154:155]
	s_mov_b32 m0, s66
	s_nop 0
	global_load_lds_dwordx4 v[226:227], off
	s_waitcnt vmcnt(8)
	s_waitcnt lgkmcnt(0)
	s_setprio 1
	s_barrier
	v_mfma_f32_16x16x32_bf16 v[124:127], v[128:131], v[184:187], v[124:127]
	v_mfma_f32_16x16x32_bf16 v[120:123], v[136:139], v[184:187], v[120:123]
	v_mfma_f32_16x16x32_bf16 v[108:111], v[128:131], v[194:197], v[108:111]
	v_mfma_f32_16x16x32_bf16 v[104:107], v[136:139], v[194:197], v[104:107]
	v_mfma_f32_16x16x32_bf16 v[96:99], v[128:131], v[202:205], v[96:99]
	v_mfma_f32_16x16x32_bf16 v[88:91], v[136:139], v[202:205], v[88:91]
	v_mfma_f32_16x16x32_bf16 v[80:83], v[128:131], v[210:213], v[80:83]
	v_mfma_f32_16x16x32_bf16 v[72:75], v[136:139], v[210:213], v[72:75]
	v_mfma_f32_16x16x32_bf16 v[124:127], v[132:135], v[188:191], v[124:127]
	v_mfma_f32_16x16x32_bf16 v[120:123], v[140:143], v[188:191], v[120:123]
	v_mfma_f32_16x16x32_bf16 v[108:111], v[132:135], v[198:201], v[108:111]
	v_mfma_f32_16x16x32_bf16 v[104:107], v[140:143], v[198:201], v[104:107]
	v_mfma_f32_16x16x32_bf16 v[96:99], v[132:135], v[206:209], v[96:99]
	v_mfma_f32_16x16x32_bf16 v[88:91], v[140:143], v[206:209], v[88:91]
	v_mfma_f32_16x16x32_bf16 v[80:83], v[132:135], v[218:221], v[80:83]
	v_mfma_f32_16x16x32_bf16 v[72:75], v[140:143], v[218:221], v[72:75]
	v_mfma_f32_16x16x32_bf16 v[116:119], v[144:147], v[184:187], v[116:119]
	v_mfma_f32_16x16x32_bf16 v[112:115], v[168:171], v[184:187], v[112:115]
	v_mfma_f32_16x16x32_bf16 v[100:103], v[144:147], v[194:197], v[100:103]
	v_mfma_f32_16x16x32_bf16 v[92:95], v[168:171], v[194:197], v[92:95]
	v_mfma_f32_16x16x32_bf16 v[84:87], v[144:147], v[202:205], v[84:87]
	v_mfma_f32_16x16x32_bf16 v[76:79], v[168:171], v[202:205], v[76:79]
	v_mfma_f32_16x16x32_bf16 v[68:71], v[144:147], v[210:213], v[68:71]
	v_mfma_f32_16x16x32_bf16 v[64:67], v[168:171], v[210:213], v[64:67]
	v_mfma_f32_16x16x32_bf16 v[116:119], v[148:151], v[188:191], v[116:119]
	v_mfma_f32_16x16x32_bf16 v[112:115], v[172:175], v[188:191], v[112:115]
	v_mfma_f32_16x16x32_bf16 v[100:103], v[148:151], v[198:201], v[100:103]
	v_mfma_f32_16x16x32_bf16 v[92:95], v[172:175], v[198:201], v[92:95]
	v_mfma_f32_16x16x32_bf16 v[84:87], v[148:151], v[206:209], v[84:87]
	v_mfma_f32_16x16x32_bf16 v[76:79], v[172:175], v[206:209], v[76:79]
	v_mfma_f32_16x16x32_bf16 v[68:71], v[148:151], v[218:221], v[68:71]
	v_mfma_f32_16x16x32_bf16 v[64:67], v[172:175], v[218:221], v[64:67]
	s_barrier
; #define PG8_STAGE(bufoff, gbase, voff) do { _Pragma("unroll") for (int _i = 0; _i < 2; ++_i) \
;         __builtin_amdgcn_global_load_lds((const unsigned*)((const char*)(gbase) + (voff)[_i]), (PG8_LAS unsigned*)(lds + (bufoff) + ldsw + _i * 8192), 16, 0, 0); } while (0)
; #define PG8_LDA(dst, b, h) do { _Pragma("unroll") for (int m = 0; m < 4; ++m) _Pragma("unroll") for (int k = 0; k < 2; ++k) dst[m][k] = *(const PG8_LAS bf16x8*)(lds + PG8_SA(b, h) + aoff + m * 2048 + k * 1024); } while (0)
; #define PG8_LDB(dst, b, h) do { _Pragma("unroll") for (int n = 0; n < 2; ++n) _Pragma("unroll") for (int k = 0; k < 2; ++k) dst[n][k] = *(const PG8_LAS bf16x8*)(lds + PG8_SB(b, h) + boff + n * 2048 + k * 1024); } while (0)
; #define PG8_MMA(ai, bj, At, Bt) do { __builtin_amdgcn_s_setprio(1); _Pragma("unroll") for (int m = 0; m < 4; ++m) _Pragma("unroll") for (int n = 0; n < 2; ++n) _Pragma("unroll") for (int k = 0; k < 2; ++k) \
;         acc[ai][bj][m][n] = __builtin_amdgcn_mfma_f32_16x16x32_bf16(Bt[n][k], At[m][k], acc[ai][bj][m][n], 0, 0, 0); __builtin_amdgcn_s_setprio(0); } while (0)
; #define PG8_WAIT_V(n) asm volatile("s_waitcnt vmcnt(" #n ")" ::: "memory")
; #define PG8_WAIT_L(n) asm volatile("s_waitcnt lgkmcnt(" #n ")" ::: "memory")
; #define PG8_BAR __builtin_amdgcn_s_barrier()
; #define PG8_SCHED __builtin_amdgcn_sched_barrier(0)
; template <class Epi, class Sched, bool ALIGN_EPI = false, bool SP2 = false>
; __device__ __forceinline__ void gemm_phase(PG8_LAS unsigned char* lds, const Gemm g, const Sched& S, const Epi& E) {
;     ...
;             PG8_LDB(B0, 0, 0); PG8_LDB(B1, 0, 1); PG8_SCHED; PG8_LDA(At, 0, 0); PG8_STAGE(PG8_SA(1, 1), a1 + hstep, voffA);
;             PG8_WAIT_V(8); PG8_WAIT_L(0); PG8_BAR; PG8_MMA(0, 0, At, B0); PG8_MMA(0, 1, At, B1); PG8_BAR; PG8_SCHED;
;     ...
;             PG8_LDA(At, 1, 1); PG8_STAGE(PG8_SB(1, 0), b3, voffB); PG8_STAGE(PG8_SB(1, 1), b3 + hstep, voffB); PG8_STAGE(PG8_SA(1, 0), a3, voffA);
;             PG8_WAIT_V(8); PG8_WAIT_L(0); PG8_BAR; PG8_MMA(1, 0, At, B0); PG8_MMA(1, 1, At, B1); PG8_BAR; PG8_SCHED;
	s_setprio 0
	s_add_i32 s54, s77, s62
	v_lshl_add_u64 v[176:177], v[176:177], 0, s[26:27]
	s_mov_b32 m0, s54
	ds_read_b128 v[184:187], v183 offset:49152
	ds_read_b128 v[188:191], v183 offset:50176
	ds_read_b128 v[194:197], v183 offset:51200
	ds_read_b128 v[198:201], v183 offset:52224
	ds_read_b128 v[202:205], v183 offset:53248
	ds_read_b128 v[206:209], v183 offset:54272
	ds_read_b128 v[210:213], v183 offset:55296
	ds_read_b128 v[218:221], v183 offset:56320
	global_load_lds_dwordx4 v[176:177], off
	s_add_i32 m0, s54, 0x2000
	s_add_u32 s52, s52, 0x40080
	v_lshl_add_u64 v[176:177], v[214:215], 0, s[26:27]
	s_addc_u32 s53, s53, 0
	s_add_i32 s54, s78, s62
	global_load_lds_dwordx4 v[176:177], off
	v_lshl_add_u64 v[176:177], s[52:53], 0, v[156:157]
	s_mov_b32 m0, s54
	s_nop 0
	global_load_lds_dwordx4 v[176:177], off
	v_lshl_add_u64 v[176:177], s[52:53], 0, v[152:153]
	s_add_i32 m0, s54, 0x2000
	s_nop 0
	global_load_lds_dwordx4 v[176:177], off
	v_lshl_add_u64 v[176:177], v[222:223], 0, s[26:27]
	s_mov_b32 m0, s68
	s_nop 0
	global_load_lds_dwordx4 v[176:177], off
	v_lshl_add_u64 v[176:177], v[224:225], 0, s[26:27]
	s_mov_b32 m0, s69
	s_nop 0
	global_load_lds_dwordx4 v[176:177], off
	s_waitcnt vmcnt(8)
	s_waitcnt lgkmcnt(0)
	s_setprio 1
	s_barrier
	v_mfma_f32_16x16x32_bf16 v[60:63], v[128:131], v[184:187], v[60:63]
	v_mfma_f32_16x16x32_bf16 v[56:59], v[136:139], v[184:187], v[56:59]
	v_mfma_f32_16x16x32_bf16 v[48:51], v[128:131], v[194:197], v[48:51]
	v_mfma_f32_16x16x32_bf16 v[40:43], v[136:139], v[194:197], v[40:43]
	v_mfma_f32_16x16x32_bf16 v[32:35], v[128:131], v[202:205], v[32:35]
	v_mfma_f32_16x16x32_bf16 v[24:27], v[136:139], v[202:205], v[24:27]
	v_mfma_f32_16x16x32_bf16 v[16:19], v[128:131], v[210:213], v[16:19]
	v_mfma_f32_16x16x32_bf16 v[8:11], v[136:139], v[210:213], v[8:11]
	v_mfma_f32_16x16x32_bf16 v[60:63], v[132:135], v[188:191], v[60:63]
	v_mfma_f32_16x16x32_bf16 v[56:59], v[140:143], v[188:191], v[56:59]
	v_mfma_f32_16x16x32_bf16 v[48:51], v[132:135], v[198:201], v[48:51]
	v_mfma_f32_16x16x32_bf16 v[40:43], v[140:143], v[198:201], v[40:43]
	v_mfma_f32_16x16x32_bf16 v[32:35], v[132:135], v[206:209], v[32:35]
	v_mfma_f32_16x16x32_bf16 v[24:27], v[140:143], v[206:209], v[24:27]
	v_mfma_f32_16x16x32_bf16 v[16:19], v[132:135], v[218:221], v[16:19]
	v_mfma_f32_16x16x32_bf16 v[8:11], v[140:143], v[218:221], v[8:11]
	v_mfma_f32_16x16x32_bf16 v[52:55], v[144:147], v[184:187], v[52:55]
	v_mfma_f32_16x16x32_bf16 v[44:47], v[168:171], v[184:187], v[44:47]
	v_mfma_f32_16x16x32_bf16 v[36:39], v[144:147], v[194:197], v[36:39]
	v_mfma_f32_16x16x32_bf16 v[28:31], v[168:171], v[194:197], v[28:31]
	v_mfma_f32_16x16x32_bf16 v[20:23], v[144:147], v[202:205], v[20:23]
	v_mfma_f32_16x16x32_bf16 v[12:15], v[168:171], v[202:205], v[12:15]
	v_mfma_f32_16x16x32_bf16 v[4:7], v[144:147], v[210:213], v[4:7]
	v_mfma_f32_16x16x32_bf16 v[0:3], v[168:171], v[210:213], v[0:3]
	v_mfma_f32_16x16x32_bf16 v[52:55], v[148:151], v[188:191], v[52:55]
	v_mfma_f32_16x16x32_bf16 v[44:47], v[172:175], v[188:191], v[44:47]
	v_mfma_f32_16x16x32_bf16 v[36:39], v[148:151], v[198:201], v[36:39]
	v_mfma_f32_16x16x32_bf16 v[28:31], v[172:175], v[198:201], v[28:31]
	v_mfma_f32_16x16x32_bf16 v[20:23], v[148:151], v[206:209], v[20:23]
	v_mfma_f32_16x16x32_bf16 v[12:15], v[172:175], v[206:209], v[12:15]
	v_mfma_f32_16x16x32_bf16 v[4:7], v[148:151], v[218:221], v[4:7]
	v_mfma_f32_16x16x32_bf16 v[0:3], v[172:175], v[218:221], v[0:3]
	s_barrier
	s_setprio 0
	s_add_i32 s76, s76, 2
	s_add_u32 s50, s50, 0x100
	s_addc_u32 s51, s51, 0
	s_add_u32 s74, s74, 0x100
	s_addc_u32 s75, s75, 0
	s_cmp_gt_u32 s76, 13
.LBB0_553:
	ds_read_b128 v[128:131], v181
	ds_read_b128 v[132:135], v181 offset:1024
	ds_read_b128 v[136:139], v181 offset:2048
	ds_read_b128 v[140:143], v181 offset:3072
	ds_read_b128 v[144:147], v182
	ds_read_b128 v[148:151], v182 offset:1024
	ds_read_b128 v[168:171], v182 offset:2048
	ds_read_b128 v[172:175], v182 offset:3072
	s_add_u32 s52, s50, 0xfffc0080
	s_addc_u32 s53, s51, -1
	s_cmp_eq_u32 s76, 12
	s_cselect_b32 s55, s35, s53
	s_cselect_b32 s54, s72, s52
	s_cselect_b32 s53, s31, s75
	s_cselect_b32 s52, s73, s74
	v_lshl_add_u64 v[176:177], s[50:51], 0, v[160:161]
	s_add_i32 m0, s63, 0xc000
	ds_read_b128 v[184:187], v183
	ds_read_b128 v[188:191], v183 offset:1024
	ds_read_b128 v[194:197], v183 offset:2048
	ds_read_b128 v[198:201], v183 offset:3072
	ds_read_b128 v[202:205], v183 offset:4096
	ds_read_b128 v[206:209], v183 offset:5120
	ds_read_b128 v[210:213], v183 offset:6144
	ds_read_b128 v[218:221], v183 offset:7168
	global_load_lds_dwordx4 v[176:177], off
	v_lshl_add_u64 v[176:177], s[50:51], 0, v[162:163]
	s_add_i32 m0, s63, 0xe000
	s_nop 0
	global_load_lds_dwordx4 v[176:177], off
	s_waitcnt vmcnt(8)
	s_waitcnt lgkmcnt(0)
	s_setprio 1
	s_barrier
; #define PG8_STAGE(bufoff, gbase, voff) do { _Pragma("unroll") for (int _i = 0; _i < 2; ++_i) \
;         __builtin_amdgcn_global_load_lds((const unsigned*)((const char*)(gbase) + (voff)[_i]), (PG8_LAS unsigned*)(lds + (bufoff) + ldsw + _i * 8192), 16, 0, 0); } while (0)
; #define PG8_LDA(dst, b, h) do { _Pragma("unroll") for (int m = 0; m < 4; ++m) _Pragma("unroll") for (int k = 0; k < 2; ++k) dst[m][k] = *(const PG8_LAS bf16x8*)(lds + PG8_SA(b, h) + aoff + m * 2048 + k * 1024); } while (0)
; #define PG8_MMA(ai, bj, At, Bt) do { __builtin_amdgcn_s_setprio(1); _Pragma("unroll") for (int m = 0; m < 4; ++m) _Pragma("unroll") for (int n = 0; n < 2; ++n) _Pragma("unroll") for (int k = 0; k < 2; ++k) \
;         acc[ai][bj][m][n] = __builtin_amdgcn_mfma_f32_16x16x32_bf16(Bt[n][k], At[m][k], acc[ai][bj][m][n], 0, 0, 0); __builtin_amdgcn_s_setprio(0); } while (0)
; #define PG8_WAIT_V(n) asm volatile("s_waitcnt vmcnt(" #n ")" ::: "memory")
; #define PG8_WAIT_L(n) asm volatile("s_waitcnt lgkmcnt(" #n ")" ::: "memory")
; #define PG8_BAR __builtin_amdgcn_s_barrier()
; #define PG8_SCHED __builtin_amdgcn_sched_barrier(0)
; template <class Epi, class Sched, bool ALIGN_EPI = false, bool SP2 = false>
; __device__ __forceinline__ void gemm_phase(PG8_LAS unsigned char* lds, const Gemm g, const Sched& S, const Epi& E) {
;     ...
;             PG8_WAIT_V(8); PG8_WAIT_L(0); PG8_BAR; PG8_MMA(0, 0, At, B0); PG8_MMA(0, 1, At, B1); PG8_BAR; PG8_SCHED;
;             PG8_LDA(At, 0, 1); PG8_STAGE(PG8_SB(0, 0), b2, voffB); PG8_STAGE(PG8_SB(0, 1), b2 + hstep, voffB); PG8_STAGE(PG8_SA(0, 0), a2, voffA);
;             PG8_WAIT_V(8); PG8_WAIT_L(0); PG8_BAR; PG8_MMA(1, 0, At, B0); PG8_MMA(1, 1, At, B1); PG8_BAR; PG8_SCHED;
	v_mfma_f32_16x16x32_bf16 v[124:127], v[128:131], v[184:187], v[124:127]
	v_mfma_f32_16x16x32_bf16 v[120:123], v[136:139], v[184:187], v[120:123]
	v_mfma_f32_16x16x32_bf16 v[108:111], v[128:131], v[194:197], v[108:111]
	v_mfma_f32_16x16x32_bf16 v[104:107], v[136:139], v[194:197], v[104:107]
	v_mfma_f32_16x16x32_bf16 v[96:99], v[128:131], v[202:205], v[96:99]
	v_mfma_f32_16x16x32_bf16 v[88:91], v[136:139], v[202:205], v[88:91]
	v_mfma_f32_16x16x32_bf16 v[80:83], v[128:131], v[210:213], v[80:83]
	v_mfma_f32_16x16x32_bf16 v[72:75], v[136:139], v[210:213], v[72:75]
	v_mfma_f32_16x16x32_bf16 v[124:127], v[132:135], v[188:191], v[124:127]
	v_mfma_f32_16x16x32_bf16 v[120:123], v[140:143], v[188:191], v[120:123]
	v_mfma_f32_16x16x32_bf16 v[108:111], v[132:135], v[198:201], v[108:111]
	v_mfma_f32_16x16x32_bf16 v[104:107], v[140:143], v[198:201], v[104:107]
	v_mfma_f32_16x16x32_bf16 v[96:99], v[132:135], v[206:209], v[96:99]
	v_mfma_f32_16x16x32_bf16 v[88:91], v[140:143], v[206:209], v[88:91]
	v_mfma_f32_16x16x32_bf16 v[80:83], v[132:135], v[218:221], v[80:83]
	v_mfma_f32_16x16x32_bf16 v[72:75], v[140:143], v[218:221], v[72:75]
	v_mfma_f32_16x16x32_bf16 v[116:119], v[144:147], v[184:187], v[116:119]
	v_mfma_f32_16x16x32_bf16 v[112:115], v[168:171], v[184:187], v[112:115]
	v_mfma_f32_16x16x32_bf16 v[100:103], v[144:147], v[194:197], v[100:103]
	v_mfma_f32_16x16x32_bf16 v[92:95], v[168:171], v[194:197], v[92:95]
	v_mfma_f32_16x16x32_bf16 v[84:87], v[144:147], v[202:205], v[84:87]
	v_mfma_f32_16x16x32_bf16 v[76:79], v[168:171], v[202:205], v[76:79]
	v_mfma_f32_16x16x32_bf16 v[68:71], v[144:147], v[210:213], v[68:71]
	v_mfma_f32_16x16x32_bf16 v[64:67], v[168:171], v[210:213], v[64:67]
	v_mfma_f32_16x16x32_bf16 v[116:119], v[148:151], v[188:191], v[116:119]
	v_mfma_f32_16x16x32_bf16 v[112:115], v[172:175], v[188:191], v[112:115]
	v_mfma_f32_16x16x32_bf16 v[100:103], v[148:151], v[198:201], v[100:103]
	v_mfma_f32_16x16x32_bf16 v[92:95], v[172:175], v[198:201], v[92:95]
	v_mfma_f32_16x16x32_bf16 v[84:87], v[148:151], v[206:209], v[84:87]
	v_mfma_f32_16x16x32_bf16 v[76:79], v[172:175], v[206:209], v[76:79]
	v_mfma_f32_16x16x32_bf16 v[68:71], v[148:151], v[218:221], v[68:71]
	v_mfma_f32_16x16x32_bf16 v[64:67], v[172:175], v[218:221], v[64:67]
	s_barrier
	s_setprio 0
	s_add_i32 s77, s70, s62
	v_lshl_add_u64 v[176:177], s[52:53], 0, v[156:157]
	s_mov_b32 m0, s77
	ds_read_b128 v[184:187], v183 offset:16384
	ds_read_b128 v[188:191], v183 offset:17408
	ds_read_b128 v[194:197], v183 offset:18432
	ds_read_b128 v[198:201], v183 offset:19456
	ds_read_b128 v[202:205], v183 offset:20480
	ds_read_b128 v[206:209], v183 offset:21504
	ds_read_b128 v[210:213], v183 offset:22528
	ds_read_b128 v[218:221], v183 offset:23552
	global_load_lds_dwordx4 v[176:177], off
	s_add_i32 m0, s77, 0x2000
	s_add_u32 s78, s52, 0x40000
	v_lshl_add_u64 v[214:215], s[52:53], 0, v[152:153]
	s_addc_u32 s79, s53, 0
	s_add_i32 s77, s71, s62
	global_load_lds_dwordx4 v[214:215], off
	v_lshl_add_u64 v[222:223], s[78:79], 0, v[156:157]
	s_mov_b32 m0, s77
	v_lshl_add_u64 v[224:225], s[54:55], 0, v[154:155]
	global_load_lds_dwordx4 v[222:223], off
	v_lshl_add_u64 v[222:223], s[78:79], 0, v[152:153]
	s_add_i32 m0, s77, 0x2000
	s_nop 0
	global_load_lds_dwordx4 v[222:223], off
	v_lshl_add_u64 v[222:223], s[54:55], 0, v[158:159]
	s_mov_b32 m0, s63
	s_nop 0
	global_load_lds_dwordx4 v[222:223], off
	s_mov_b32 m0, s64
	s_nop 0
	global_load_lds_dwordx4 v[224:225], off
	s_waitcnt vmcnt(8)
	s_waitcnt lgkmcnt(0)
	s_setprio 1
	s_barrier
	v_mfma_f32_16x16x32_bf16 v[60:63], v[128:131], v[184:187], v[60:63]
	v_mfma_f32_16x16x32_bf16 v[56:59], v[136:139], v[184:187], v[56:59]
	v_mfma_f32_16x16x32_bf16 v[48:51], v[128:131], v[194:197], v[48:51]
	v_mfma_f32_16x16x32_bf16 v[40:43], v[136:139], v[194:197], v[40:43]
	v_mfma_f32_16x16x32_bf16 v[32:35], v[128:131], v[202:205], v[32:35]
	v_mfma_f32_16x16x32_bf16 v[24:27], v[136:139], v[202:205], v[24:27]
	v_mfma_f32_16x16x32_bf16 v[16:19], v[128:131], v[210:213], v[16:19]
	v_mfma_f32_16x16x32_bf16 v[8:11], v[136:139], v[210:213], v[8:11]
	v_mfma_f32_16x16x32_bf16 v[60:63], v[132:135], v[188:191], v[60:63]
	v_mfma_f32_16x16x32_bf16 v[56:59], v[140:143], v[188:191], v[56:59]
	v_mfma_f32_16x16x32_bf16 v[48:51], v[132:135], v[198:201], v[48:51]
	v_mfma_f32_16x16x32_bf16 v[40:43], v[140:143], v[198:201], v[40:43]
	v_mfma_f32_16x16x32_bf16 v[32:35], v[132:135], v[206:209], v[32:35]
	v_mfma_f32_16x16x32_bf16 v[24:27], v[140:143], v[206:209], v[24:27]
	v_mfma_f32_16x16x32_bf16 v[16:19], v[132:135], v[218:221], v[16:19]
	v_mfma_f32_16x16x32_bf16 v[8:11], v[140:143], v[218:221], v[8:11]
	v_mfma_f32_16x16x32_bf16 v[52:55], v[144:147], v[184:187], v[52:55]
	v_mfma_f32_16x16x32_bf16 v[44:47], v[168:171], v[184:187], v[44:47]
	v_mfma_f32_16x16x32_bf16 v[36:39], v[144:147], v[194:197], v[36:39]
	v_mfma_f32_16x16x32_bf16 v[28:31], v[168:171], v[194:197], v[28:31]
	v_mfma_f32_16x16x32_bf16 v[20:23], v[144:147], v[202:205], v[20:23]
	v_mfma_f32_16x16x32_bf16 v[12:15], v[168:171], v[202:205], v[12:15]
	v_mfma_f32_16x16x32_bf16 v[4:7], v[144:147], v[210:213], v[4:7]
	v_mfma_f32_16x16x32_bf16 v[0:3], v[168:171], v[210:213], v[0:3]
	v_mfma_f32_16x16x32_bf16 v[52:55], v[148:151], v[188:191], v[52:55]
	v_mfma_f32_16x16x32_bf16 v[44:47], v[172:175], v[188:191], v[44:47]
	v_mfma_f32_16x16x32_bf16 v[36:39], v[148:151], v[198:201], v[36:39]
	v_mfma_f32_16x16x32_bf16 v[28:31], v[172:175], v[198:201], v[28:31]
	v_mfma_f32_16x16x32_bf16 v[20:23], v[148:151], v[206:209], v[20:23]
	v_mfma_f32_16x16x32_bf16 v[12:15], v[172:175], v[206:209], v[12:15]
	v_mfma_f32_16x16x32_bf16 v[4:7], v[148:151], v[218:221], v[4:7]
	v_mfma_f32_16x16x32_bf16 v[0:3], v[172:175], v[218:221], v[0:3]
	s_barrier
; #define PG8_STAGE(bufoff, gbase, voff) do { _Pragma("unroll") for (int _i = 0; _i < 2; ++_i) \
;         __builtin_amdgcn_global_load_lds((const unsigned*)((const char*)(gbase) + (voff)[_i]), (PG8_LAS unsigned*)(lds + (bufoff) + ldsw + _i * 8192), 16, 0, 0); } while (0)
; #define PG8_LDA(dst, b, h) do { _Pragma("unroll") for (int m = 0; m < 4; ++m) _Pragma("unroll") for (int k = 0; k < 2; ++k) dst[m][k] = *(const PG8_LAS bf16x8*)(lds + PG8_SA(b, h) + aoff + m * 2048 + k * 1024); } while (0)
; #define PG8_LDB(dst, b, h) do { _Pragma("unroll") for (int n = 0; n < 2; ++n) _Pragma("unroll") for (int k = 0; k < 2; ++k) dst[n][k] = *(const PG8_LAS bf16x8*)(lds + PG8_SB(b, h) + boff + n * 2048 + k * 1024); } while (0)
; #define PG8_MMA(ai, bj, At, Bt) do { __builtin_amdgcn_s_setprio(1); _Pragma("unroll") for (int m = 0; m < 4; ++m) _Pragma("unroll") for (int n = 0; n < 2; ++n) _Pragma("unroll") for (int k = 0; k < 2; ++k) \
;         acc[ai][bj][m][n] = __builtin_amdgcn_mfma_f32_16x16x32_bf16(Bt[n][k], At[m][k], acc[ai][bj][m][n], 0, 0, 0); __builtin_amdgcn_s_setprio(0); } while (0)
; #define PG8_WAIT_V(n) asm volatile("s_waitcnt vmcnt(" #n ")" ::: "memory")
; #define PG8_WAIT_L(n) asm volatile("s_waitcnt lgkmcnt(" #n ")" ::: "memory")
; #define PG8_BAR __builtin_amdgcn_s_barrier()
; #define PG8_SCHED __builtin_amdgcn_sched_barrier(0)
; template <class Epi, class Sched, bool ALIGN_EPI = false, bool SP2 = false>
; __device__ __forceinline__ void gemm_phase(PG8_LAS unsigned char* lds, const Gemm g, const Sched& S, const Epi& E) {
;     ...
;             PG8_LDB(B0, 1, 0); PG8_LDB(B1, 1, 1); PG8_SCHED; PG8_LDA(At, 1, 0); PG8_STAGE(PG8_SA(0, 1), a2 + hstep, voffA);
;             PG8_WAIT_V(8); PG8_WAIT_L(0); PG8_BAR; PG8_MMA(0, 0, At, B0); PG8_MMA(0, 1, At, B1); PG8_BAR; PG8_SCHED;
	s_setprio 0
	s_add_i32 s77, 0, 0x18000
	s_add_i32 s78, 0, 0x1c000
	v_add_u32_e32 v140, s77, v179
	v_add_u32_e32 v172, s78, v179
	ds_read_b128 v[128:131], v140
	ds_read_b128 v[132:135], v140 offset:1024
	ds_read_b128 v[136:139], v140 offset:2048
	ds_read_b128 v[140:143], v140 offset:3072
	ds_read_b128 v[144:147], v172
	ds_read_b128 v[148:151], v172 offset:1024
	ds_read_b128 v[168:171], v172 offset:2048
	ds_read_b128 v[172:175], v172 offset:3072
	s_add_u32 s54, s54, 0x40000
	s_addc_u32 s55, s55, 0
	s_mov_b32 m0, s65
	v_lshl_add_u64 v[226:227], s[54:55], 0, v[158:159]
	ds_read_b128 v[184:187], v183 offset:32768
	ds_read_b128 v[188:191], v183 offset:33792
	ds_read_b128 v[194:197], v183 offset:34816
	ds_read_b128 v[198:201], v183 offset:35840
	ds_read_b128 v[202:205], v183 offset:36864
	ds_read_b128 v[206:209], v183 offset:37888
	ds_read_b128 v[210:213], v183 offset:38912
	ds_read_b128 v[218:221], v183 offset:39936
	global_load_lds_dwordx4 v[226:227], off
	v_lshl_add_u64 v[226:227], s[54:55], 0, v[154:155]
	s_mov_b32 m0, s66
	s_nop 0
	global_load_lds_dwordx4 v[226:227], off
	s_waitcnt vmcnt(8)
	s_waitcnt lgkmcnt(0)
	s_setprio 1
	s_barrier
	v_mfma_f32_16x16x32_bf16 v[124:127], v[128:131], v[184:187], v[124:127]
	v_mfma_f32_16x16x32_bf16 v[120:123], v[136:139], v[184:187], v[120:123]
	v_mfma_f32_16x16x32_bf16 v[108:111], v[128:131], v[194:197], v[108:111]
	v_mfma_f32_16x16x32_bf16 v[104:107], v[136:139], v[194:197], v[104:107]
	v_mfma_f32_16x16x32_bf16 v[96:99], v[128:131], v[202:205], v[96:99]
	v_mfma_f32_16x16x32_bf16 v[88:91], v[136:139], v[202:205], v[88:91]
	v_mfma_f32_16x16x32_bf16 v[80:83], v[128:131], v[210:213], v[80:83]
	v_mfma_f32_16x16x32_bf16 v[72:75], v[136:139], v[210:213], v[72:75]
	v_mfma_f32_16x16x32_bf16 v[124:127], v[132:135], v[188:191], v[124:127]
	v_mfma_f32_16x16x32_bf16 v[120:123], v[140:143], v[188:191], v[120:123]
	v_mfma_f32_16x16x32_bf16 v[108:111], v[132:135], v[198:201], v[108:111]
	v_mfma_f32_16x16x32_bf16 v[104:107], v[140:143], v[198:201], v[104:107]
	v_mfma_f32_16x16x32_bf16 v[96:99], v[132:135], v[206:209], v[96:99]
	v_mfma_f32_16x16x32_bf16 v[88:91], v[140:143], v[206:209], v[88:91]
	v_mfma_f32_16x16x32_bf16 v[80:83], v[132:135], v[218:221], v[80:83]
	v_mfma_f32_16x16x32_bf16 v[72:75], v[140:143], v[218:221], v[72:75]
	v_mfma_f32_16x16x32_bf16 v[116:119], v[144:147], v[184:187], v[116:119]
	v_mfma_f32_16x16x32_bf16 v[112:115], v[168:171], v[184:187], v[112:115]
	v_mfma_f32_16x16x32_bf16 v[100:103], v[144:147], v[194:197], v[100:103]
	v_mfma_f32_16x16x32_bf16 v[92:95], v[168:171], v[194:197], v[92:95]
	v_mfma_f32_16x16x32_bf16 v[84:87], v[144:147], v[202:205], v[84:87]
	v_mfma_f32_16x16x32_bf16 v[76:79], v[168:171], v[202:205], v[76:79]
	v_mfma_f32_16x16x32_bf16 v[68:71], v[144:147], v[210:213], v[68:71]
	v_mfma_f32_16x16x32_bf16 v[64:67], v[168:171], v[210:213], v[64:67]
	v_mfma_f32_16x16x32_bf16 v[116:119], v[148:151], v[188:191], v[116:119]
	v_mfma_f32_16x16x32_bf16 v[112:115], v[172:175], v[188:191], v[112:115]
	v_mfma_f32_16x16x32_bf16 v[100:103], v[148:151], v[198:201], v[100:103]
	v_mfma_f32_16x16x32_bf16 v[92:95], v[172:175], v[198:201], v[92:95]
	v_mfma_f32_16x16x32_bf16 v[84:87], v[148:151], v[206:209], v[84:87]
	v_mfma_f32_16x16x32_bf16 v[76:79], v[172:175], v[206:209], v[76:79]
	v_mfma_f32_16x16x32_bf16 v[68:71], v[148:151], v[218:221], v[68:71]
	v_mfma_f32_16x16x32_bf16 v[64:67], v[172:175], v[218:221], v[64:67]
	s_barrier
; #define PG8_STAGE(bufoff, gbase, voff) do { _Pragma("unroll") for (int _i = 0; _i < 2; ++_i) \
;         __builtin_amdgcn_global_load_lds((const unsigned*)((const char*)(gbase) + (voff)[_i]), (PG8_LAS unsigned*)(lds + (bufoff) + ldsw + _i * 8192), 16, 0, 0); } while (0)
; #define PG8_LDA(dst, b, h) do { _Pragma("unroll") for (int m = 0; m < 4; ++m) _Pragma("unroll") for (int k = 0; k < 2; ++k) dst[m][k] = *(const PG8_LAS bf16x8*)(lds + PG8_SA(b, h) + aoff + m * 2048 + k * 1024); } while (0)
; #define PG8_MMA(ai, bj, At, Bt) do { __builtin_amdgcn_s_setprio(1); _Pragma("unroll") for (int m = 0; m < 4; ++m) _Pragma("unroll") for (int n = 0; n < 2; ++n) _Pragma("unroll") for (int k = 0; k < 2; ++k) \
;         acc[ai][bj][m][n] = __builtin_amdgcn_mfma_f32_16x16x32_bf16(Bt[n][k], At[m][k], acc[ai][bj][m][n], 0, 0, 0); __builtin_amdgcn_s_setprio(0); } while (0)
; #define PG8_WAIT_V(n) asm volatile("s_waitcnt vmcnt(" #n ")" ::: "memory")
; #define PG8_WAIT_L(n) asm volatile("s_waitcnt lgkmcnt(" #n ")" ::: "memory")
; #define PG8_BAR __builtin_amdgcn_s_barrier()
; #define PG8_SCHED __builtin_amdgcn_sched_barrier(0)
; template <class Epi, class Sched, bool ALIGN_EPI = false, bool SP2 = false>
; __device__ __forceinline__ void gemm_phase(PG8_LAS unsigned char* lds, const Gemm g, const Sched& S, const Epi& E) {
;     ...
;             PG8_LDA(At, 1, 1); PG8_STAGE(PG8_SB(1, 0), b3, voffB); PG8_STAGE(PG8_SB(1, 1), b3 + hstep, voffB); PG8_STAGE(PG8_SA(1, 0), a3, voffA);
;             PG8_WAIT_V(8); PG8_WAIT_L(0); PG8_BAR; PG8_MMA(1, 0, At, B0); PG8_MMA(1, 1, At, B1); PG8_BAR; PG8_SCHED;
;     ...
;         if constexpr (ALIGN_EPI) { if (wr == 0) PG8_BAR; }
	s_setprio 0
	s_add_i32 s54, s77, s62
	v_lshl_add_u64 v[176:177], v[176:177], 0, s[26:27]
	s_mov_b32 m0, s54
	ds_read_b128 v[184:187], v183 offset:49152
	ds_read_b128 v[188:191], v183 offset:50176
	ds_read_b128 v[194:197], v183 offset:51200
	ds_read_b128 v[198:201], v183 offset:52224
	ds_read_b128 v[202:205], v183 offset:53248
	ds_read_b128 v[206:209], v183 offset:54272
	ds_read_b128 v[210:213], v183 offset:55296
	ds_read_b128 v[218:221], v183 offset:56320
	global_load_lds_dwordx4 v[176:177], off
	s_add_i32 m0, s54, 0x2000
	s_add_u32 s52, s52, 0x40080
	v_lshl_add_u64 v[176:177], v[214:215], 0, s[26:27]
	s_addc_u32 s53, s53, 0
	s_add_i32 s54, s78, s62
	global_load_lds_dwordx4 v[176:177], off
	v_lshl_add_u64 v[176:177], s[52:53], 0, v[156:157]
	s_mov_b32 m0, s54
	s_nop 0
	global_load_lds_dwordx4 v[176:177], off
	v_lshl_add_u64 v[176:177], s[52:53], 0, v[152:153]
	s_add_i32 m0, s54, 0x2000
	s_nop 0
	global_load_lds_dwordx4 v[176:177], off
	v_lshl_add_u64 v[176:177], v[222:223], 0, s[26:27]
	s_mov_b32 m0, s68
	s_nop 0
	global_load_lds_dwordx4 v[176:177], off
	v_lshl_add_u64 v[176:177], v[224:225], 0, s[26:27]
	s_mov_b32 m0, s69
	s_nop 0
	global_load_lds_dwordx4 v[176:177], off
	s_waitcnt vmcnt(8)
	s_waitcnt lgkmcnt(0)
	s_setprio 1
	s_barrier
	v_mfma_f32_16x16x32_bf16 v[60:63], v[128:131], v[184:187], v[60:63]
	v_mfma_f32_16x16x32_bf16 v[56:59], v[136:139], v[184:187], v[56:59]
	v_mfma_f32_16x16x32_bf16 v[48:51], v[128:131], v[194:197], v[48:51]
	v_mfma_f32_16x16x32_bf16 v[40:43], v[136:139], v[194:197], v[40:43]
	v_mfma_f32_16x16x32_bf16 v[32:35], v[128:131], v[202:205], v[32:35]
	v_mfma_f32_16x16x32_bf16 v[24:27], v[136:139], v[202:205], v[24:27]
	v_mfma_f32_16x16x32_bf16 v[16:19], v[128:131], v[210:213], v[16:19]
	v_mfma_f32_16x16x32_bf16 v[8:11], v[136:139], v[210:213], v[8:11]
	v_mfma_f32_16x16x32_bf16 v[60:63], v[132:135], v[188:191], v[60:63]
	v_mfma_f32_16x16x32_bf16 v[56:59], v[140:143], v[188:191], v[56:59]
	v_mfma_f32_16x16x32_bf16 v[48:51], v[132:135], v[198:201], v[48:51]
	v_mfma_f32_16x16x32_bf16 v[40:43], v[140:143], v[198:201], v[40:43]
	v_mfma_f32_16x16x32_bf16 v[32:35], v[132:135], v[206:209], v[32:35]
	v_mfma_f32_16x16x32_bf16 v[24:27], v[140:143], v[206:209], v[24:27]
	v_mfma_f32_16x16x32_bf16 v[16:19], v[132:135], v[218:221], v[16:19]
	v_mfma_f32_16x16x32_bf16 v[8:11], v[140:143], v[218:221], v[8:11]
	v_mfma_f32_16x16x32_bf16 v[52:55], v[144:147], v[184:187], v[52:55]
	v_mfma_f32_16x16x32_bf16 v[44:47], v[168:171], v[184:187], v[44:47]
	v_mfma_f32_16x16x32_bf16 v[36:39], v[144:147], v[194:197], v[36:39]
	v_mfma_f32_16x16x32_bf16 v[28:31], v[168:171], v[194:197], v[28:31]
	v_mfma_f32_16x16x32_bf16 v[20:23], v[144:147], v[202:205], v[20:23]
	v_mfma_f32_16x16x32_bf16 v[12:15], v[168:171], v[202:205], v[12:15]
	v_mfma_f32_16x16x32_bf16 v[4:7], v[144:147], v[210:213], v[4:7]
	v_mfma_f32_16x16x32_bf16 v[0:3], v[168:171], v[210:213], v[0:3]
	v_mfma_f32_16x16x32_bf16 v[52:55], v[148:151], v[188:191], v[52:55]
	v_mfma_f32_16x16x32_bf16 v[44:47], v[172:175], v[188:191], v[44:47]
	v_mfma_f32_16x16x32_bf16 v[36:39], v[148:151], v[198:201], v[36:39]
	v_mfma_f32_16x16x32_bf16 v[28:31], v[172:175], v[198:201], v[28:31]
	v_mfma_f32_16x16x32_bf16 v[20:23], v[148:151], v[206:209], v[20:23]
	v_mfma_f32_16x16x32_bf16 v[12:15], v[172:175], v[206:209], v[12:15]
	v_mfma_f32_16x16x32_bf16 v[4:7], v[148:151], v[218:221], v[4:7]
	v_mfma_f32_16x16x32_bf16 v[0:3], v[172:175], v[218:221], v[0:3]
	s_barrier
	s_setprio 0
	s_add_i32 s76, s76, 2
	s_add_u32 s50, s50, 0x100
	s_addc_u32 s51, s51, 0
	s_add_u32 s74, s74, 0x100
	s_addc_u32 s75, s75, 0
	s_cmp_gt_u32 s76, 13
	s_cbranch_scc0 .LBB0_553
	s_and_b64 vcc, exec, s[28:29]
	s_cbranch_vccz .LBB0_556
	s_barrier

; #define PG8_STAGE(bufoff, gbase, voff) do { _Pragma("unroll") for (int _i = 0; _i < 2; ++_i) \
;         __builtin_amdgcn_global_load_lds((const unsigned*)((const char*)(gbase) + (voff)[_i]), (PG8_LAS unsigned*)(lds + (bufoff) + ldsw + _i * 8192), 16, 0, 0); } while (0)
; #define PG8_LDA(dst, b, h) do { _Pragma("unroll") for (int m = 0; m < 4; ++m) _Pragma("unroll") for (int k = 0; k < 2; ++k) dst[m][k] = *(const PG8_LAS bf16x8*)(lds + PG8_SA(b, h) + aoff + m * 2048 + k * 1024); } while (0)
; #define PG8_LDB(dst, b, h) do { _Pragma("unroll") for (int n = 0; n < 2; ++n) _Pragma("unroll") for (int k = 0; k < 2; ++k) dst[n][k] = *(const PG8_LAS bf16x8*)(lds + PG8_SB(b, h) + boff + n * 2048 + k * 1024); } while (0)
; #define PG8_MMA(ai, bj, At, Bt) do { __builtin_amdgcn_s_setprio(1); _Pragma("unroll") for (int m = 0; m < 4; ++m) _Pragma("unroll") for (int n = 0; n < 2; ++n) _Pragma("unroll") for (int k = 0; k < 2; ++k) \
;         acc[ai][bj][m][n] = __builtin_amdgcn_mfma_f32_16x16x32_bf16(Bt[n][k], At[m][k], acc[ai][bj][m][n], 0, 0, 0); __builtin_amdgcn_s_setprio(0); } while (0)
; #define PG8_BAR __builtin_amdgcn_s_barrier()
; template <class Epi, class Sched, bool ALIGN_EPI = false, bool SP2 = false>
; __device__ __forceinline__ void gemm_phase(PG8_LAS unsigned char* lds, const Gemm g, const Sched& S, const Epi& E) {
;     ...
;         const bool has_next = S.next(ui + 1, nxt);
;         const char* nA = has_next ? (const char*)g.A + (size_t)nxt.pm * tstep : cA; const char* nB = has_next ? (const char*)g.Bt + (size_t)nxt.pn * tstep : cB;
;         for (int t = 0; t < nt; t += 2) {
;             const bool last = (t == nt - 2);
;             const char* a1 = cA + (size_t)(t + 1) * kstep;
;             const char* a2 = last ? nA : cA + (size_t)(t + 2) * kstep; const char* b2 = last ? nB : cB + (size_t)(t + 2) * kstep;
;             const char* a3 = a2 + kstep; const char* b3 = b2 + kstep;
;             if (last && has_next) S.a_ready(nxt);
;             if constexpr (SP2) {
;             PG8_LDB(B0, 0, 0); PG8_LDB(B1, 0, 1); PG8_SCHED; PG8_LDA(At, 0, 0); PG8_STAGE(PG8_SA(1, 1), a1 + hstep, voffA);
;             PG8_WAIT_V(8); PG8_WAIT_L(0); PG8_BAR; PG8_MMA(0, 0, At, B0); PG8_MMA(0, 1, At, B1); PG8_BAR; PG8_SCHED;
;             PG8_LDA(At, 0, 1); PG8_STAGE(PG8_SB(0, 0), b2, voffB); PG8_STAGE(PG8_SB(0, 1), b2 + hstep, voffB); PG8_STAGE(PG8_SA(0, 0), a2, voffA);
.LBB0_572:
	s_ashr_i32 s27, s26, 31
	s_lshl_b64 s[28:29], s[26:27], 19
	s_add_u32 s28, s47, s28
	s_addc_u32 s29, s52, s29
	s_and_b64 s[30:31], s[40:41], exec
	s_cselect_b32 s27, s29, s37
	s_cselect_b32 s68, s28, s36
	s_ashr_i32 s25, s24, 31
	s_lshl_b64 s[30:31], s[24:25], 19
	s_add_u32 s30, s53, s30
	s_addc_u32 s31, s54, s31
	s_and_b64 s[50:51], s[40:41], exec
	s_cselect_b32 s25, s31, s45
	s_cselect_b32 s69, s30, s44
	s_add_u32 s36, s36, 0x40080
	s_addc_u32 s37, s37, 0
	s_add_u32 s70, s44, 0x100
	s_addc_u32 s71, s45, 0
	s_mov_b32 s72, -2
	ds_read_b128 v[128:131], v220
	ds_read_b128 v[132:135], v220 offset:1024
	ds_read_b128 v[136:139], v220 offset:2048
	ds_read_b128 v[140:143], v220 offset:3072
	ds_read_b128 v[144:147], v221
	ds_read_b128 v[148:151], v221 offset:1024
	ds_read_b128 v[152:155], v221 offset:2048
	ds_read_b128 v[156:159], v221 offset:3072
	s_add_u32 s44, s36, 0xfffc0080
	s_addc_u32 s45, s37, -1
	s_cmp_eq_u32 s72, 12
	s_cselect_b32 s51, s27, s45
	s_cselect_b32 s50, s68, s44
	s_cselect_b32 s45, s25, s71
	s_cselect_b32 s44, s69, s70
	v_lshl_add_u64 v[210:211], s[36:37], 0, v[194:195]
	s_add_i32 m0, s55, 0xc000
	ds_read_b128 v[160:163], v222
	ds_read_b128 v[164:167], v222 offset:1024
	ds_read_b128 v[168:171], v222 offset:2048
	ds_read_b128 v[172:175], v222 offset:3072
	ds_read_b128 v[176:179], v222 offset:4096
	ds_read_b128 v[180:183], v222 offset:5120
	ds_read_b128 v[202:205], v222 offset:6144
	ds_read_b128 v[206:209], v222 offset:7168
	global_load_lds_dwordx4 v[210:211], off
	v_lshl_add_u64 v[210:211], s[36:37], 0, v[196:197]
	s_add_i32 m0, s55, 0xe000
	s_nop 0
	global_load_lds_dwordx4 v[210:211], off
	s_waitcnt vmcnt(8)
	s_waitcnt lgkmcnt(0)
	s_setprio 1
	s_barrier
	v_mfma_f32_16x16x32_bf16 v[124:127], v[128:131], v[160:163], 0
	v_mfma_f32_16x16x32_bf16 v[120:123], v[136:139], v[160:163], 0
	v_mfma_f32_16x16x32_bf16 v[108:111], v[128:131], v[168:171], 0
	v_mfma_f32_16x16x32_bf16 v[104:107], v[136:139], v[168:171], 0
	v_mfma_f32_16x16x32_bf16 v[92:95], v[128:131], v[176:179], 0
	v_mfma_f32_16x16x32_bf16 v[88:91], v[136:139], v[176:179], 0
	v_mfma_f32_16x16x32_bf16 v[76:79], v[128:131], v[202:205], 0
	v_mfma_f32_16x16x32_bf16 v[72:75], v[136:139], v[202:205], 0
	v_mfma_f32_16x16x32_bf16 v[124:127], v[132:135], v[164:167], v[124:127]
	v_mfma_f32_16x16x32_bf16 v[120:123], v[140:143], v[164:167], v[120:123]
	v_mfma_f32_16x16x32_bf16 v[108:111], v[132:135], v[172:175], v[108:111]
	v_mfma_f32_16x16x32_bf16 v[104:107], v[140:143], v[172:175], v[104:107]
	v_mfma_f32_16x16x32_bf16 v[92:95], v[132:135], v[180:183], v[92:95]
	v_mfma_f32_16x16x32_bf16 v[88:91], v[140:143], v[180:183], v[88:91]
	v_mfma_f32_16x16x32_bf16 v[76:79], v[132:135], v[206:209], v[76:79]
	v_mfma_f32_16x16x32_bf16 v[72:75], v[140:143], v[206:209], v[72:75]
	v_mfma_f32_16x16x32_bf16 v[116:119], v[144:147], v[160:163], 0
	v_mfma_f32_16x16x32_bf16 v[112:115], v[152:155], v[160:163], 0
	v_mfma_f32_16x16x32_bf16 v[100:103], v[144:147], v[168:171], 0
	v_mfma_f32_16x16x32_bf16 v[96:99], v[152:155], v[168:171], 0
	v_mfma_f32_16x16x32_bf16 v[84:87], v[144:147], v[176:179], 0
	v_mfma_f32_16x16x32_bf16 v[80:83], v[152:155], v[176:179], 0
	v_mfma_f32_16x16x32_bf16 v[68:71], v[144:147], v[202:205], 0
	v_mfma_f32_16x16x32_bf16 v[64:67], v[152:155], v[202:205], 0
	v_mfma_f32_16x16x32_bf16 v[116:119], v[148:151], v[164:167], v[116:119]
	v_mfma_f32_16x16x32_bf16 v[112:115], v[156:159], v[164:167], v[112:115]
	v_mfma_f32_16x16x32_bf16 v[100:103], v[148:151], v[172:175], v[100:103]
	v_mfma_f32_16x16x32_bf16 v[96:99], v[156:159], v[172:175], v[96:99]
	v_mfma_f32_16x16x32_bf16 v[84:87], v[148:151], v[180:183], v[84:87]
	v_mfma_f32_16x16x32_bf16 v[80:83], v[156:159], v[180:183], v[80:83]
	v_mfma_f32_16x16x32_bf16 v[68:71], v[148:151], v[206:209], v[68:71]
	v_mfma_f32_16x16x32_bf16 v[64:67], v[156:159], v[206:209], v[64:67]
	s_barrier
	s_setprio 0
	s_add_i32 s73, s66, s13
	v_lshl_add_u64 v[210:211], s[44:45], 0, v[188:189]
	s_mov_b32 m0, s73
	ds_read_b128 v[160:163], v222 offset:16384
	ds_read_b128 v[164:167], v222 offset:17408
	ds_read_b128 v[168:171], v222 offset:18432
	ds_read_b128 v[172:175], v222 offset:19456
	ds_read_b128 v[176:179], v222 offset:20480
	ds_read_b128 v[180:183], v222 offset:21504
	ds_read_b128 v[202:205], v222 offset:22528
	ds_read_b128 v[206:209], v222 offset:23552
	global_load_lds_dwordx4 v[210:211], off
	s_add_i32 m0, s73, 0x2000
	s_add_u32 s74, s44, 0x40000
	v_lshl_add_u64 v[212:213], s[44:45], 0, v[184:185]
	s_addc_u32 s75, s45, 0
	s_add_i32 s73, s67, s13
	global_load_lds_dwordx4 v[212:213], off
	v_lshl_add_u64 v[214:215], s[74:75], 0, v[188:189]
	s_mov_b32 m0, s73
	v_lshl_add_u64 v[224:225], s[50:51], 0, v[186:187]
	global_load_lds_dwordx4 v[214:215], off
	v_lshl_add_u64 v[214:215], s[74:75], 0, v[184:185]
	s_add_i32 m0, s73, 0x2000
	s_nop 0
	global_load_lds_dwordx4 v[214:215], off
	v_lshl_add_u64 v[214:215], s[50:51], 0, v[190:191]
	s_mov_b32 m0, s55
	s_nop 0
	global_load_lds_dwordx4 v[214:215], off
	s_mov_b32 m0, s60
	s_nop 0
	global_load_lds_dwordx4 v[224:225], off
	s_waitcnt vmcnt(8)
	s_waitcnt lgkmcnt(0)
	s_setprio 1
	s_barrier
; #define PG8_STAGE(bufoff, gbase, voff) do { _Pragma("unroll") for (int _i = 0; _i < 2; ++_i) \
;         __builtin_amdgcn_global_load_lds((const unsigned*)((const char*)(gbase) + (voff)[_i]), (PG8_LAS unsigned*)(lds + (bufoff) + ldsw + _i * 8192), 16, 0, 0); } while (0)
; #define PG8_LDA(dst, b, h) do { _Pragma("unroll") for (int m = 0; m < 4; ++m) _Pragma("unroll") for (int k = 0; k < 2; ++k) dst[m][k] = *(const PG8_LAS bf16x8*)(lds + PG8_SA(b, h) + aoff + m * 2048 + k * 1024); } while (0)
; #define PG8_LDB(dst, b, h) do { _Pragma("unroll") for (int n = 0; n < 2; ++n) _Pragma("unroll") for (int k = 0; k < 2; ++k) dst[n][k] = *(const PG8_LAS bf16x8*)(lds + PG8_SB(b, h) + boff + n * 2048 + k * 1024); } while (0)
; #define PG8_MMA(ai, bj, At, Bt) do { __builtin_amdgcn_s_setprio(1); _Pragma("unroll") for (int m = 0; m < 4; ++m) _Pragma("unroll") for (int n = 0; n < 2; ++n) _Pragma("unroll") for (int k = 0; k < 2; ++k) \
;         acc[ai][bj][m][n] = __builtin_amdgcn_mfma_f32_16x16x32_bf16(Bt[n][k], At[m][k], acc[ai][bj][m][n], 0, 0, 0); __builtin_amdgcn_s_setprio(0); } while (0)
; #define PG8_WAIT_V(n) asm volatile("s_waitcnt vmcnt(" #n ")" ::: "memory")
; #define PG8_WAIT_L(n) asm volatile("s_waitcnt lgkmcnt(" #n ")" ::: "memory")
; #define PG8_BAR __builtin_amdgcn_s_barrier()
; #define PG8_SCHED __builtin_amdgcn_sched_barrier(0)
; template <class Epi, class Sched, bool ALIGN_EPI = false, bool SP2 = false>
; __device__ __forceinline__ void gemm_phase(PG8_LAS unsigned char* lds, const Gemm g, const Sched& S, const Epi& E) {
;     ...
;             PG8_WAIT_V(8); PG8_WAIT_L(0); PG8_BAR; PG8_MMA(1, 0, At, B0); PG8_MMA(1, 1, At, B1); PG8_BAR; PG8_SCHED;
;             PG8_LDB(B0, 1, 0); PG8_LDB(B1, 1, 1); PG8_SCHED; PG8_LDA(At, 1, 0); PG8_STAGE(PG8_SA(0, 1), a2 + hstep, voffA);
;             PG8_WAIT_V(8); PG8_WAIT_L(0); PG8_BAR; PG8_MMA(0, 0, At, B0); PG8_MMA(0, 1, At, B1); PG8_BAR; PG8_SCHED;
	v_mfma_f32_16x16x32_bf16 v[60:63], v[128:131], v[160:163], 0
	v_mfma_f32_16x16x32_bf16 v[56:59], v[136:139], v[160:163], 0
	v_mfma_f32_16x16x32_bf16 v[44:47], v[128:131], v[168:171], 0
	v_mfma_f32_16x16x32_bf16 v[40:43], v[136:139], v[168:171], 0
	v_mfma_f32_16x16x32_bf16 v[28:31], v[128:131], v[176:179], 0
	v_mfma_f32_16x16x32_bf16 v[24:27], v[136:139], v[176:179], 0
	v_mfma_f32_16x16x32_bf16 v[12:15], v[128:131], v[202:205], 0
	v_mfma_f32_16x16x32_bf16 v[8:11], v[136:139], v[202:205], 0
	v_mfma_f32_16x16x32_bf16 v[60:63], v[132:135], v[164:167], v[60:63]
	v_mfma_f32_16x16x32_bf16 v[56:59], v[140:143], v[164:167], v[56:59]
	v_mfma_f32_16x16x32_bf16 v[44:47], v[132:135], v[172:175], v[44:47]
	v_mfma_f32_16x16x32_bf16 v[40:43], v[140:143], v[172:175], v[40:43]
	v_mfma_f32_16x16x32_bf16 v[28:31], v[132:135], v[180:183], v[28:31]
	v_mfma_f32_16x16x32_bf16 v[24:27], v[140:143], v[180:183], v[24:27]
	v_mfma_f32_16x16x32_bf16 v[12:15], v[132:135], v[206:209], v[12:15]
	v_mfma_f32_16x16x32_bf16 v[8:11], v[140:143], v[206:209], v[8:11]
	v_mfma_f32_16x16x32_bf16 v[52:55], v[144:147], v[160:163], 0
	v_mfma_f32_16x16x32_bf16 v[48:51], v[152:155], v[160:163], 0
	v_mfma_f32_16x16x32_bf16 v[36:39], v[144:147], v[168:171], 0
	v_mfma_f32_16x16x32_bf16 v[32:35], v[152:155], v[168:171], 0
	v_mfma_f32_16x16x32_bf16 v[20:23], v[144:147], v[176:179], 0
	v_mfma_f32_16x16x32_bf16 v[16:19], v[152:155], v[176:179], 0
	v_mfma_f32_16x16x32_bf16 v[4:7], v[144:147], v[202:205], 0
	v_mfma_f32_16x16x32_bf16 v[0:3], v[152:155], v[202:205], 0
	v_mfma_f32_16x16x32_bf16 v[52:55], v[148:151], v[164:167], v[52:55]
	v_mfma_f32_16x16x32_bf16 v[48:51], v[156:159], v[164:167], v[48:51]
	v_mfma_f32_16x16x32_bf16 v[36:39], v[148:151], v[172:175], v[36:39]
	v_mfma_f32_16x16x32_bf16 v[32:35], v[156:159], v[172:175], v[32:35]
	v_mfma_f32_16x16x32_bf16 v[20:23], v[148:151], v[180:183], v[20:23]
	v_mfma_f32_16x16x32_bf16 v[16:19], v[156:159], v[180:183], v[16:19]
	v_mfma_f32_16x16x32_bf16 v[4:7], v[148:151], v[206:209], v[4:7]
	v_mfma_f32_16x16x32_bf16 v[0:3], v[156:159], v[206:209], v[0:3]
	s_barrier
	s_setprio 0
	s_add_i32 s73, 0, 0x18000
	s_add_i32 s74, 0, 0x1c000
	v_add_u32_e32 v140, s73, v218
	v_add_u32_e32 v156, s74, v218
	ds_read_b128 v[128:131], v140
	ds_read_b128 v[132:135], v140 offset:1024
	ds_read_b128 v[136:139], v140 offset:2048
	ds_read_b128 v[140:143], v140 offset:3072
	ds_read_b128 v[144:147], v156
	ds_read_b128 v[148:151], v156 offset:1024
	ds_read_b128 v[152:155], v156 offset:2048
	ds_read_b128 v[156:159], v156 offset:3072
	s_add_u32 s50, s50, 0x40000
	s_addc_u32 s51, s51, 0
	s_mov_b32 m0, s61
	v_lshl_add_u64 v[226:227], s[50:51], 0, v[190:191]
	ds_read_b128 v[160:163], v222 offset:32768
	ds_read_b128 v[164:167], v222 offset:33792
	ds_read_b128 v[168:171], v222 offset:34816
	ds_read_b128 v[172:175], v222 offset:35840
	ds_read_b128 v[176:179], v222 offset:36864
	ds_read_b128 v[180:183], v222 offset:37888
	ds_read_b128 v[202:205], v222 offset:38912
	ds_read_b128 v[206:209], v222 offset:39936
	global_load_lds_dwordx4 v[226:227], off
	v_lshl_add_u64 v[226:227], s[50:51], 0, v[186:187]
	s_mov_b32 m0, s62
	s_nop 0
	global_load_lds_dwordx4 v[226:227], off
	s_waitcnt vmcnt(8)
	s_waitcnt lgkmcnt(0)
	s_setprio 1
	s_barrier
	v_mfma_f32_16x16x32_bf16 v[124:127], v[128:131], v[160:163], v[124:127]
	v_mfma_f32_16x16x32_bf16 v[120:123], v[136:139], v[160:163], v[120:123]
	v_mfma_f32_16x16x32_bf16 v[108:111], v[128:131], v[168:171], v[108:111]
	v_mfma_f32_16x16x32_bf16 v[104:107], v[136:139], v[168:171], v[104:107]
	v_mfma_f32_16x16x32_bf16 v[92:95], v[128:131], v[176:179], v[92:95]
	v_mfma_f32_16x16x32_bf16 v[88:91], v[136:139], v[176:179], v[88:91]
	v_mfma_f32_16x16x32_bf16 v[76:79], v[128:131], v[202:205], v[76:79]
	v_mfma_f32_16x16x32_bf16 v[72:75], v[136:139], v[202:205], v[72:75]
	v_mfma_f32_16x16x32_bf16 v[124:127], v[132:135], v[164:167], v[124:127]
	v_mfma_f32_16x16x32_bf16 v[120:123], v[140:143], v[164:167], v[120:123]
	v_mfma_f32_16x16x32_bf16 v[108:111], v[132:135], v[172:175], v[108:111]
	v_mfma_f32_16x16x32_bf16 v[104:107], v[140:143], v[172:175], v[104:107]
	v_mfma_f32_16x16x32_bf16 v[92:95], v[132:135], v[180:183], v[92:95]
	v_mfma_f32_16x16x32_bf16 v[88:91], v[140:143], v[180:183], v[88:91]
	v_mfma_f32_16x16x32_bf16 v[76:79], v[132:135], v[206:209], v[76:79]
	v_mfma_f32_16x16x32_bf16 v[72:75], v[140:143], v[206:209], v[72:75]
	v_mfma_f32_16x16x32_bf16 v[116:119], v[144:147], v[160:163], v[116:119]
	v_mfma_f32_16x16x32_bf16 v[112:115], v[152:155], v[160:163], v[112:115]
	v_mfma_f32_16x16x32_bf16 v[100:103], v[144:147], v[168:171], v[100:103]
	v_mfma_f32_16x16x32_bf16 v[96:99], v[152:155], v[168:171], v[96:99]
	v_mfma_f32_16x16x32_bf16 v[84:87], v[144:147], v[176:179], v[84:87]
	v_mfma_f32_16x16x32_bf16 v[80:83], v[152:155], v[176:179], v[80:83]
	v_mfma_f32_16x16x32_bf16 v[68:71], v[144:147], v[202:205], v[68:71]
	v_mfma_f32_16x16x32_bf16 v[64:67], v[152:155], v[202:205], v[64:67]
	v_mfma_f32_16x16x32_bf16 v[116:119], v[148:151], v[164:167], v[116:119]
	v_mfma_f32_16x16x32_bf16 v[112:115], v[156:159], v[164:167], v[112:115]
	v_mfma_f32_16x16x32_bf16 v[100:103], v[148:151], v[172:175], v[100:103]
	v_mfma_f32_16x16x32_bf16 v[96:99], v[156:159], v[172:175], v[96:99]
	v_mfma_f32_16x16x32_bf16 v[84:87], v[148:151], v[180:183], v[84:87]
	v_mfma_f32_16x16x32_bf16 v[80:83], v[156:159], v[180:183], v[80:83]
	v_mfma_f32_16x16x32_bf16 v[68:71], v[148:151], v[206:209], v[68:71]
	v_mfma_f32_16x16x32_bf16 v[64:67], v[156:159], v[206:209], v[64:67]
	s_barrier
; #define PG8_STAGE(bufoff, gbase, voff) do { _Pragma("unroll") for (int _i = 0; _i < 2; ++_i) \
;         __builtin_amdgcn_global_load_lds((const unsigned*)((const char*)(gbase) + (voff)[_i]), (PG8_LAS unsigned*)(lds + (bufoff) + ldsw + _i * 8192), 16, 0, 0); } while (0)
; #define PG8_LDA(dst, b, h) do { _Pragma("unroll") for (int m = 0; m < 4; ++m) _Pragma("unroll") for (int k = 0; k < 2; ++k) dst[m][k] = *(const PG8_LAS bf16x8*)(lds + PG8_SA(b, h) + aoff + m * 2048 + k * 1024); } while (0)
; #define PG8_LDB(dst, b, h) do { _Pragma("unroll") for (int n = 0; n < 2; ++n) _Pragma("unroll") for (int k = 0; k < 2; ++k) dst[n][k] = *(const PG8_LAS bf16x8*)(lds + PG8_SB(b, h) + boff + n * 2048 + k * 1024); } while (0)
; #define PG8_MMA(ai, bj, At, Bt) do { __builtin_amdgcn_s_setprio(1); _Pragma("unroll") for (int m = 0; m < 4; ++m) _Pragma("unroll") for (int n = 0; n < 2; ++n) _Pragma("unroll") for (int k = 0; k < 2; ++k) \
;         acc[ai][bj][m][n] = __builtin_amdgcn_mfma_f32_16x16x32_bf16(Bt[n][k], At[m][k], acc[ai][bj][m][n], 0, 0, 0); __builtin_amdgcn_s_setprio(0); } while (0)
; #define PG8_WAIT_V(n) asm volatile("s_waitcnt vmcnt(" #n ")" ::: "memory")
; #define PG8_WAIT_L(n) asm volatile("s_waitcnt lgkmcnt(" #n ")" ::: "memory")
; #define PG8_BAR __builtin_amdgcn_s_barrier()
; #define PG8_SCHED __builtin_amdgcn_sched_barrier(0)
; template <class Epi, class Sched, bool ALIGN_EPI = false, bool SP2 = false>
; __device__ __forceinline__ void gemm_phase(PG8_LAS unsigned char* lds, const Gemm g, const Sched& S, const Epi& E) {
;     ...
;             PG8_LDB(B0, 0, 0); PG8_LDB(B1, 0, 1); PG8_SCHED; PG8_LDA(At, 0, 0); PG8_STAGE(PG8_SA(1, 1), a1 + hstep, voffA);
;             PG8_WAIT_V(8); PG8_WAIT_L(0); PG8_BAR; PG8_MMA(0, 0, At, B0); PG8_MMA(0, 1, At, B1); PG8_BAR; PG8_SCHED;
;     ...
;             PG8_LDA(At, 1, 1); PG8_STAGE(PG8_SB(1, 0), b3, voffB); PG8_STAGE(PG8_SB(1, 1), b3 + hstep, voffB); PG8_STAGE(PG8_SA(1, 0), a3, voffA);
;             PG8_WAIT_V(8); PG8_WAIT_L(0); PG8_BAR; PG8_MMA(1, 0, At, B0); PG8_MMA(1, 1, At, B1); PG8_BAR; PG8_SCHED;
	s_setprio 0
	s_add_i32 s50, s73, s13
	v_lshl_add_u64 v[210:211], v[210:211], 0, s[20:21]
	s_mov_b32 m0, s50
	ds_read_b128 v[160:163], v222 offset:49152
	ds_read_b128 v[164:167], v222 offset:50176
	ds_read_b128 v[168:171], v222 offset:51200
	ds_read_b128 v[172:175], v222 offset:52224
	ds_read_b128 v[176:179], v222 offset:53248
	ds_read_b128 v[180:183], v222 offset:54272
	ds_read_b128 v[202:205], v222 offset:55296
	ds_read_b128 v[206:209], v222 offset:56320
	global_load_lds_dwordx4 v[210:211], off
	s_add_i32 m0, s50, 0x2000
	s_add_u32 s44, s44, 0x40080
	v_lshl_add_u64 v[210:211], v[212:213], 0, s[20:21]
	s_addc_u32 s45, s45, 0
	s_add_i32 s50, s74, s13
	global_load_lds_dwordx4 v[210:211], off
	v_lshl_add_u64 v[210:211], s[44:45], 0, v[188:189]
	s_mov_b32 m0, s50
	s_nop 0
	global_load_lds_dwordx4 v[210:211], off
	v_lshl_add_u64 v[210:211], s[44:45], 0, v[184:185]
	s_add_i32 m0, s50, 0x2000
	s_nop 0
	global_load_lds_dwordx4 v[210:211], off
	v_lshl_add_u64 v[210:211], v[214:215], 0, s[20:21]
	s_mov_b32 m0, s64
	s_nop 0
	global_load_lds_dwordx4 v[210:211], off
	v_lshl_add_u64 v[210:211], v[224:225], 0, s[20:21]
	s_mov_b32 m0, s65
	s_nop 0
	global_load_lds_dwordx4 v[210:211], off
	s_waitcnt vmcnt(8)
	s_waitcnt lgkmcnt(0)
	s_setprio 1
	s_barrier
	v_mfma_f32_16x16x32_bf16 v[60:63], v[128:131], v[160:163], v[60:63]
	v_mfma_f32_16x16x32_bf16 v[56:59], v[136:139], v[160:163], v[56:59]
	v_mfma_f32_16x16x32_bf16 v[44:47], v[128:131], v[168:171], v[44:47]
	v_mfma_f32_16x16x32_bf16 v[40:43], v[136:139], v[168:171], v[40:43]
	v_mfma_f32_16x16x32_bf16 v[28:31], v[128:131], v[176:179], v[28:31]
	v_mfma_f32_16x16x32_bf16 v[24:27], v[136:139], v[176:179], v[24:27]
	v_mfma_f32_16x16x32_bf16 v[12:15], v[128:131], v[202:205], v[12:15]
	v_mfma_f32_16x16x32_bf16 v[8:11], v[136:139], v[202:205], v[8:11]
	v_mfma_f32_16x16x32_bf16 v[60:63], v[132:135], v[164:167], v[60:63]
	v_mfma_f32_16x16x32_bf16 v[56:59], v[140:143], v[164:167], v[56:59]
	v_mfma_f32_16x16x32_bf16 v[44:47], v[132:135], v[172:175], v[44:47]
	v_mfma_f32_16x16x32_bf16 v[40:43], v[140:143], v[172:175], v[40:43]
	v_mfma_f32_16x16x32_bf16 v[28:31], v[132:135], v[180:183], v[28:31]
	v_mfma_f32_16x16x32_bf16 v[24:27], v[140:143], v[180:183], v[24:27]
	v_mfma_f32_16x16x32_bf16 v[12:15], v[132:135], v[206:209], v[12:15]
	v_mfma_f32_16x16x32_bf16 v[8:11], v[140:143], v[206:209], v[8:11]
	v_mfma_f32_16x16x32_bf16 v[52:55], v[144:147], v[160:163], v[52:55]
	v_mfma_f32_16x16x32_bf16 v[48:51], v[152:155], v[160:163], v[48:51]
	v_mfma_f32_16x16x32_bf16 v[36:39], v[144:147], v[168:171], v[36:39]
	v_mfma_f32_16x16x32_bf16 v[32:35], v[152:155], v[168:171], v[32:35]
	v_mfma_f32_16x16x32_bf16 v[20:23], v[144:147], v[176:179], v[20:23]
	v_mfma_f32_16x16x32_bf16 v[16:19], v[152:155], v[176:179], v[16:19]
	v_mfma_f32_16x16x32_bf16 v[4:7], v[144:147], v[202:205], v[4:7]
	v_mfma_f32_16x16x32_bf16 v[0:3], v[152:155], v[202:205], v[0:3]
	v_mfma_f32_16x16x32_bf16 v[52:55], v[148:151], v[164:167], v[52:55]
	v_mfma_f32_16x16x32_bf16 v[48:51], v[156:159], v[164:167], v[48:51]
	v_mfma_f32_16x16x32_bf16 v[36:39], v[148:151], v[172:175], v[36:39]
	v_mfma_f32_16x16x32_bf16 v[32:35], v[156:159], v[172:175], v[32:35]
	v_mfma_f32_16x16x32_bf16 v[20:23], v[148:151], v[180:183], v[20:23]
	v_mfma_f32_16x16x32_bf16 v[16:19], v[156:159], v[180:183], v[16:19]
	v_mfma_f32_16x16x32_bf16 v[4:7], v[148:151], v[206:209], v[4:7]
	v_mfma_f32_16x16x32_bf16 v[0:3], v[156:159], v[206:209], v[0:3]
	s_barrier
	s_setprio 0
	s_add_i32 s72, s72, 2
	s_add_u32 s36, s36, 0x100
	s_addc_u32 s37, s37, 0
	s_add_u32 s70, s70, 0x100
	s_addc_u32 s71, s71, 0
	s_cmp_gt_u32 s72, 13
.LBB0_573:
	ds_read_b128 v[128:131], v220
	ds_read_b128 v[132:135], v220 offset:1024
	ds_read_b128 v[136:139], v220 offset:2048
	ds_read_b128 v[140:143], v220 offset:3072
	ds_read_b128 v[144:147], v221
	ds_read_b128 v[148:151], v221 offset:1024
	ds_read_b128 v[152:155], v221 offset:2048
	ds_read_b128 v[156:159], v221 offset:3072
	s_add_u32 s44, s36, 0xfffc0080
	s_addc_u32 s45, s37, -1
	s_cmp_eq_u32 s72, 12
	s_cselect_b32 s51, s27, s45
	s_cselect_b32 s50, s68, s44
	s_cselect_b32 s45, s25, s71
	s_cselect_b32 s44, s69, s70
	v_lshl_add_u64 v[210:211], s[36:37], 0, v[194:195]
	s_add_i32 m0, s55, 0xc000
	ds_read_b128 v[160:163], v222
	ds_read_b128 v[164:167], v222 offset:1024
	ds_read_b128 v[168:171], v222 offset:2048
	ds_read_b128 v[172:175], v222 offset:3072
	ds_read_b128 v[176:179], v222 offset:4096
	ds_read_b128 v[180:183], v222 offset:5120
	ds_read_b128 v[202:205], v222 offset:6144
	ds_read_b128 v[206:209], v222 offset:7168
	global_load_lds_dwordx4 v[210:211], off
	v_lshl_add_u64 v[210:211], s[36:37], 0, v[196:197]
	s_add_i32 m0, s55, 0xe000
	s_nop 0
	global_load_lds_dwordx4 v[210:211], off
	s_waitcnt vmcnt(8)
	s_waitcnt lgkmcnt(0)
	s_setprio 1
	s_barrier
; #define PG8_STAGE(bufoff, gbase, voff) do { _Pragma("unroll") for (int _i = 0; _i < 2; ++_i) \
;         __builtin_amdgcn_global_load_lds((const unsigned*)((const char*)(gbase) + (voff)[_i]), (PG8_LAS unsigned*)(lds + (bufoff) + ldsw + _i * 8192), 16, 0, 0); } while (0)
; #define PG8_LDA(dst, b, h) do { _Pragma("unroll") for (int m = 0; m < 4; ++m) _Pragma("unroll") for (int k = 0; k < 2; ++k) dst[m][k] = *(const PG8_LAS bf16x8*)(lds + PG8_SA(b, h) + aoff + m * 2048 + k * 1024); } while (0)
; #define PG8_MMA(ai, bj, At, Bt) do { __builtin_amdgcn_s_setprio(1); _Pragma("unroll") for (int m = 0; m < 4; ++m) _Pragma("unroll") for (int n = 0; n < 2; ++n) _Pragma("unroll") for (int k = 0; k < 2; ++k) \
;         acc[ai][bj][m][n] = __builtin_amdgcn_mfma_f32_16x16x32_bf16(Bt[n][k], At[m][k], acc[ai][bj][m][n], 0, 0, 0); __builtin_amdgcn_s_setprio(0); } while (0)
; #define PG8_WAIT_V(n) asm volatile("s_waitcnt vmcnt(" #n ")" ::: "memory")
; #define PG8_WAIT_L(n) asm volatile("s_waitcnt lgkmcnt(" #n ")" ::: "memory")
; #define PG8_BAR __builtin_amdgcn_s_barrier()
; #define PG8_SCHED __builtin_amdgcn_sched_barrier(0)
; template <class Epi, class Sched, bool ALIGN_EPI = false, bool SP2 = false>
; __device__ __forceinline__ void gemm_phase(PG8_LAS unsigned char* lds, const Gemm g, const Sched& S, const Epi& E) {
;     ...
;             PG8_WAIT_V(8); PG8_WAIT_L(0); PG8_BAR; PG8_MMA(0, 0, At, B0); PG8_MMA(0, 1, At, B1); PG8_BAR; PG8_SCHED;
;             PG8_LDA(At, 0, 1); PG8_STAGE(PG8_SB(0, 0), b2, voffB); PG8_STAGE(PG8_SB(0, 1), b2 + hstep, voffB); PG8_STAGE(PG8_SA(0, 0), a2, voffA);
;             PG8_WAIT_V(8); PG8_WAIT_L(0); PG8_BAR; PG8_MMA(1, 0, At, B0); PG8_MMA(1, 1, At, B1); PG8_BAR; PG8_SCHED;
	v_mfma_f32_16x16x32_bf16 v[124:127], v[128:131], v[160:163], v[124:127]
	v_mfma_f32_16x16x32_bf16 v[120:123], v[136:139], v[160:163], v[120:123]
	v_mfma_f32_16x16x32_bf16 v[108:111], v[128:131], v[168:171], v[108:111]
	v_mfma_f32_16x16x32_bf16 v[104:107], v[136:139], v[168:171], v[104:107]
	v_mfma_f32_16x16x32_bf16 v[92:95], v[128:131], v[176:179], v[92:95]
	v_mfma_f32_16x16x32_bf16 v[88:91], v[136:139], v[176:179], v[88:91]
	v_mfma_f32_16x16x32_bf16 v[76:79], v[128:131], v[202:205], v[76:79]
	v_mfma_f32_16x16x32_bf16 v[72:75], v[136:139], v[202:205], v[72:75]
	v_mfma_f32_16x16x32_bf16 v[124:127], v[132:135], v[164:167], v[124:127]
	v_mfma_f32_16x16x32_bf16 v[120:123], v[140:143], v[164:167], v[120:123]
	v_mfma_f32_16x16x32_bf16 v[108:111], v[132:135], v[172:175], v[108:111]
	v_mfma_f32_16x16x32_bf16 v[104:107], v[140:143], v[172:175], v[104:107]
	v_mfma_f32_16x16x32_bf16 v[92:95], v[132:135], v[180:183], v[92:95]
	v_mfma_f32_16x16x32_bf16 v[88:91], v[140:143], v[180:183], v[88:91]
	v_mfma_f32_16x16x32_bf16 v[76:79], v[132:135], v[206:209], v[76:79]
	v_mfma_f32_16x16x32_bf16 v[72:75], v[140:143], v[206:209], v[72:75]
	v_mfma_f32_16x16x32_bf16 v[116:119], v[144:147], v[160:163], v[116:119]
	v_mfma_f32_16x16x32_bf16 v[112:115], v[152:155], v[160:163], v[112:115]
	v_mfma_f32_16x16x32_bf16 v[100:103], v[144:147], v[168:171], v[100:103]
	v_mfma_f32_16x16x32_bf16 v[96:99], v[152:155], v[168:171], v[96:99]
	v_mfma_f32_16x16x32_bf16 v[84:87], v[144:147], v[176:179], v[84:87]
	v_mfma_f32_16x16x32_bf16 v[80:83], v[152:155], v[176:179], v[80:83]
	v_mfma_f32_16x16x32_bf16 v[68:71], v[144:147], v[202:205], v[68:71]
	v_mfma_f32_16x16x32_bf16 v[64:67], v[152:155], v[202:205], v[64:67]
	v_mfma_f32_16x16x32_bf16 v[116:119], v[148:151], v[164:167], v[116:119]
	v_mfma_f32_16x16x32_bf16 v[112:115], v[156:159], v[164:167], v[112:115]
	v_mfma_f32_16x16x32_bf16 v[100:103], v[148:151], v[172:175], v[100:103]
	v_mfma_f32_16x16x32_bf16 v[96:99], v[156:159], v[172:175], v[96:99]
	v_mfma_f32_16x16x32_bf16 v[84:87], v[148:151], v[180:183], v[84:87]
	v_mfma_f32_16x16x32_bf16 v[80:83], v[156:159], v[180:183], v[80:83]
	v_mfma_f32_16x16x32_bf16 v[68:71], v[148:151], v[206:209], v[68:71]
	v_mfma_f32_16x16x32_bf16 v[64:67], v[156:159], v[206:209], v[64:67]
	s_barrier
	s_setprio 0
	s_add_i32 s73, s66, s13
	v_lshl_add_u64 v[210:211], s[44:45], 0, v[188:189]
	s_mov_b32 m0, s73
	ds_read_b128 v[160:163], v222 offset:16384
	ds_read_b128 v[164:167], v222 offset:17408
	ds_read_b128 v[168:171], v222 offset:18432
	ds_read_b128 v[172:175], v222 offset:19456
	ds_read_b128 v[176:179], v222 offset:20480
	ds_read_b128 v[180:183], v222 offset:21504
	ds_read_b128 v[202:205], v222 offset:22528
	ds_read_b128 v[206:209], v222 offset:23552
	global_load_lds_dwordx4 v[210:211], off
	s_add_i32 m0, s73, 0x2000
	s_add_u32 s74, s44, 0x40000
	v_lshl_add_u64 v[212:213], s[44:45], 0, v[184:185]
	s_addc_u32 s75, s45, 0
	s_add_i32 s73, s67, s13
	global_load_lds_dwordx4 v[212:213], off
	v_lshl_add_u64 v[214:215], s[74:75], 0, v[188:189]
	s_mov_b32 m0, s73
	v_lshl_add_u64 v[224:225], s[50:51], 0, v[186:187]
	global_load_lds_dwordx4 v[214:215], off
	v_lshl_add_u64 v[214:215], s[74:75], 0, v[184:185]
	s_add_i32 m0, s73, 0x2000
	s_nop 0
	global_load_lds_dwordx4 v[214:215], off
	v_lshl_add_u64 v[214:215], s[50:51], 0, v[190:191]
	s_mov_b32 m0, s55
	s_nop 0
	global_load_lds_dwordx4 v[214:215], off
	s_mov_b32 m0, s60
	s_nop 0
	global_load_lds_dwordx4 v[224:225], off
	s_waitcnt vmcnt(8)
	s_waitcnt lgkmcnt(0)
	s_setprio 1
	s_barrier
	v_mfma_f32_16x16x32_bf16 v[60:63], v[128:131], v[160:163], v[60:63]
	v_mfma_f32_16x16x32_bf16 v[56:59], v[136:139], v[160:163], v[56:59]
	v_mfma_f32_16x16x32_bf16 v[44:47], v[128:131], v[168:171], v[44:47]
	v_mfma_f32_16x16x32_bf16 v[40:43], v[136:139], v[168:171], v[40:43]
	v_mfma_f32_16x16x32_bf16 v[28:31], v[128:131], v[176:179], v[28:31]
	v_mfma_f32_16x16x32_bf16 v[24:27], v[136:139], v[176:179], v[24:27]
	v_mfma_f32_16x16x32_bf16 v[12:15], v[128:131], v[202:205], v[12:15]
	v_mfma_f32_16x16x32_bf16 v[8:11], v[136:139], v[202:205], v[8:11]
	v_mfma_f32_16x16x32_bf16 v[60:63], v[132:135], v[164:167], v[60:63]
	v_mfma_f32_16x16x32_bf16 v[56:59], v[140:143], v[164:167], v[56:59]
	v_mfma_f32_16x16x32_bf16 v[44:47], v[132:135], v[172:175], v[44:47]
	v_mfma_f32_16x16x32_bf16 v[40:43], v[140:143], v[172:175], v[40:43]
	v_mfma_f32_16x16x32_bf16 v[28:31], v[132:135], v[180:183], v[28:31]
	v_mfma_f32_16x16x32_bf16 v[24:27], v[140:143], v[180:183], v[24:27]
	v_mfma_f32_16x16x32_bf16 v[12:15], v[132:135], v[206:209], v[12:15]
	v_mfma_f32_16x16x32_bf16 v[8:11], v[140:143], v[206:209], v[8:11]
	v_mfma_f32_16x16x32_bf16 v[52:55], v[144:147], v[160:163], v[52:55]
	v_mfma_f32_16x16x32_bf16 v[48:51], v[152:155], v[160:163], v[48:51]
	v_mfma_f32_16x16x32_bf16 v[36:39], v[144:147], v[168:171], v[36:39]
	v_mfma_f32_16x16x32_bf16 v[32:35], v[152:155], v[168:171], v[32:35]
	v_mfma_f32_16x16x32_bf16 v[20:23], v[144:147], v[176:179], v[20:23]
	v_mfma_f32_16x16x32_bf16 v[16:19], v[152:155], v[176:179], v[16:19]
	v_mfma_f32_16x16x32_bf16 v[4:7], v[144:147], v[202:205], v[4:7]
	v_mfma_f32_16x16x32_bf16 v[0:3], v[152:155], v[202:205], v[0:3]
	v_mfma_f32_16x16x32_bf16 v[52:55], v[148:151], v[164:167], v[52:55]
	v_mfma_f32_16x16x32_bf16 v[48:51], v[156:159], v[164:167], v[48:51]
	v_mfma_f32_16x16x32_bf16 v[36:39], v[148:151], v[172:175], v[36:39]
	v_mfma_f32_16x16x32_bf16 v[32:35], v[156:159], v[172:175], v[32:35]
	v_mfma_f32_16x16x32_bf16 v[20:23], v[148:151], v[180:183], v[20:23]
	v_mfma_f32_16x16x32_bf16 v[16:19], v[156:159], v[180:183], v[16:19]
	v_mfma_f32_16x16x32_bf16 v[4:7], v[148:151], v[206:209], v[4:7]
	v_mfma_f32_16x16x32_bf16 v[0:3], v[156:159], v[206:209], v[0:3]
	s_barrier
; #define PG8_STAGE(bufoff, gbase, voff) do { _Pragma("unroll") for (int _i = 0; _i < 2; ++_i) \
;         __builtin_amdgcn_global_load_lds((const unsigned*)((const char*)(gbase) + (voff)[_i]), (PG8_LAS unsigned*)(lds + (bufoff) + ldsw + _i * 8192), 16, 0, 0); } while (0)
; #define PG8_LDA(dst, b, h) do { _Pragma("unroll") for (int m = 0; m < 4; ++m) _Pragma("unroll") for (int k = 0; k < 2; ++k) dst[m][k] = *(const PG8_LAS bf16x8*)(lds + PG8_SA(b, h) + aoff + m * 2048 + k * 1024); } while (0)
; #define PG8_LDB(dst, b, h) do { _Pragma("unroll") for (int n = 0; n < 2; ++n) _Pragma("unroll") for (int k = 0; k < 2; ++k) dst[n][k] = *(const PG8_LAS bf16x8*)(lds + PG8_SB(b, h) + boff + n * 2048 + k * 1024); } while (0)
; #define PG8_MMA(ai, bj, At, Bt) do { __builtin_amdgcn_s_setprio(1); _Pragma("unroll") for (int m = 0; m < 4; ++m) _Pragma("unroll") for (int n = 0; n < 2; ++n) _Pragma("unroll") for (int k = 0; k < 2; ++k) \
;         acc[ai][bj][m][n] = __builtin_amdgcn_mfma_f32_16x16x32_bf16(Bt[n][k], At[m][k], acc[ai][bj][m][n], 0, 0, 0); __builtin_amdgcn_s_setprio(0); } while (0)
; #define PG8_WAIT_V(n) asm volatile("s_waitcnt vmcnt(" #n ")" ::: "memory")
; #define PG8_WAIT_L(n) asm volatile("s_waitcnt lgkmcnt(" #n ")" ::: "memory")
; #define PG8_BAR __builtin_amdgcn_s_barrier()
; #define PG8_SCHED __builtin_amdgcn_sched_barrier(0)
; template <class Epi, class Sched, bool ALIGN_EPI = false, bool SP2 = false>
; __device__ __forceinline__ void gemm_phase(PG8_LAS unsigned char* lds, const Gemm g, const Sched& S, const Epi& E) {
;     ...
;             PG8_LDB(B0, 1, 0); PG8_LDB(B1, 1, 1); PG8_SCHED; PG8_LDA(At, 1, 0); PG8_STAGE(PG8_SA(0, 1), a2 + hstep, voffA);
;             PG8_WAIT_V(8); PG8_WAIT_L(0); PG8_BAR; PG8_MMA(0, 0, At, B0); PG8_MMA(0, 1, At, B1); PG8_BAR; PG8_SCHED;
	s_setprio 0
	s_add_i32 s73, 0, 0x18000
	s_add_i32 s74, 0, 0x1c000
	v_add_u32_e32 v140, s73, v218
	v_add_u32_e32 v156, s74, v218
	ds_read_b128 v[128:131], v140
	ds_read_b128 v[132:135], v140 offset:1024
	ds_read_b128 v[136:139], v140 offset:2048
	ds_read_b128 v[140:143], v140 offset:3072
	ds_read_b128 v[144:147], v156
	ds_read_b128 v[148:151], v156 offset:1024
	ds_read_b128 v[152:155], v156 offset:2048
	ds_read_b128 v[156:159], v156 offset:3072
	s_add_u32 s50, s50, 0x40000
	s_addc_u32 s51, s51, 0
	s_mov_b32 m0, s61
	v_lshl_add_u64 v[226:227], s[50:51], 0, v[190:191]
	ds_read_b128 v[160:163], v222 offset:32768
	ds_read_b128 v[164:167], v222 offset:33792
	ds_read_b128 v[168:171], v222 offset:34816
	ds_read_b128 v[172:175], v222 offset:35840
	ds_read_b128 v[176:179], v222 offset:36864
	ds_read_b128 v[180:183], v222 offset:37888
	ds_read_b128 v[202:205], v222 offset:38912
	ds_read_b128 v[206:209], v222 offset:39936
	global_load_lds_dwordx4 v[226:227], off
	v_lshl_add_u64 v[226:227], s[50:51], 0, v[186:187]
	s_mov_b32 m0, s62
	s_nop 0
	global_load_lds_dwordx4 v[226:227], off
	s_waitcnt vmcnt(8)
	s_waitcnt lgkmcnt(0)
	s_setprio 1
	s_barrier
	v_mfma_f32_16x16x32_bf16 v[124:127], v[128:131], v[160:163], v[124:127]
	v_mfma_f32_16x16x32_bf16 v[120:123], v[136:139], v[160:163], v[120:123]
	v_mfma_f32_16x16x32_bf16 v[108:111], v[128:131], v[168:171], v[108:111]
	v_mfma_f32_16x16x32_bf16 v[104:107], v[136:139], v[168:171], v[104:107]
	v_mfma_f32_16x16x32_bf16 v[92:95], v[128:131], v[176:179], v[92:95]
	v_mfma_f32_16x16x32_bf16 v[88:91], v[136:139], v[176:179], v[88:91]
	v_mfma_f32_16x16x32_bf16 v[76:79], v[128:131], v[202:205], v[76:79]
	v_mfma_f32_16x16x32_bf16 v[72:75], v[136:139], v[202:205], v[72:75]
	v_mfma_f32_16x16x32_bf16 v[124:127], v[132:135], v[164:167], v[124:127]
	v_mfma_f32_16x16x32_bf16 v[120:123], v[140:143], v[164:167], v[120:123]
	v_mfma_f32_16x16x32_bf16 v[108:111], v[132:135], v[172:175], v[108:111]
	v_mfma_f32_16x16x32_bf16 v[104:107], v[140:143], v[172:175], v[104:107]
	v_mfma_f32_16x16x32_bf16 v[92:95], v[132:135], v[180:183], v[92:95]
	v_mfma_f32_16x16x32_bf16 v[88:91], v[140:143], v[180:183], v[88:91]
	v_mfma_f32_16x16x32_bf16 v[76:79], v[132:135], v[206:209], v[76:79]
	v_mfma_f32_16x16x32_bf16 v[72:75], v[140:143], v[206:209], v[72:75]
	v_mfma_f32_16x16x32_bf16 v[116:119], v[144:147], v[160:163], v[116:119]
	v_mfma_f32_16x16x32_bf16 v[112:115], v[152:155], v[160:163], v[112:115]
	v_mfma_f32_16x16x32_bf16 v[100:103], v[144:147], v[168:171], v[100:103]
	v_mfma_f32_16x16x32_bf16 v[96:99], v[152:155], v[168:171], v[96:99]
	v_mfma_f32_16x16x32_bf16 v[84:87], v[144:147], v[176:179], v[84:87]
	v_mfma_f32_16x16x32_bf16 v[80:83], v[152:155], v[176:179], v[80:83]
	v_mfma_f32_16x16x32_bf16 v[68:71], v[144:147], v[202:205], v[68:71]
	v_mfma_f32_16x16x32_bf16 v[64:67], v[152:155], v[202:205], v[64:67]
	v_mfma_f32_16x16x32_bf16 v[116:119], v[148:151], v[164:167], v[116:119]
	v_mfma_f32_16x16x32_bf16 v[112:115], v[156:159], v[164:167], v[112:115]
	v_mfma_f32_16x16x32_bf16 v[100:103], v[148:151], v[172:175], v[100:103]
	v_mfma_f32_16x16x32_bf16 v[96:99], v[156:159], v[172:175], v[96:99]
	v_mfma_f32_16x16x32_bf16 v[84:87], v[148:151], v[180:183], v[84:87]
	v_mfma_f32_16x16x32_bf16 v[80:83], v[156:159], v[180:183], v[80:83]
	v_mfma_f32_16x16x32_bf16 v[68:71], v[148:151], v[206:209], v[68:71]
	v_mfma_f32_16x16x32_bf16 v[64:67], v[156:159], v[206:209], v[64:67]
	s_barrier
; #define PG8_STAGE(bufoff, gbase, voff) do { _Pragma("unroll") for (int _i = 0; _i < 2; ++_i) \
;         __builtin_amdgcn_global_load_lds((const unsigned*)((const char*)(gbase) + (voff)[_i]), (PG8_LAS unsigned*)(lds + (bufoff) + ldsw + _i * 8192), 16, 0, 0); } while (0)
; #define PG8_LDA(dst, b, h) do { _Pragma("unroll") for (int m = 0; m < 4; ++m) _Pragma("unroll") for (int k = 0; k < 2; ++k) dst[m][k] = *(const PG8_LAS bf16x8*)(lds + PG8_SA(b, h) + aoff + m * 2048 + k * 1024); } while (0)
; #define PG8_MMA(ai, bj, At, Bt) do { __builtin_amdgcn_s_setprio(1); _Pragma("unroll") for (int m = 0; m < 4; ++m) _Pragma("unroll") for (int n = 0; n < 2; ++n) _Pragma("unroll") for (int k = 0; k < 2; ++k) \
;         acc[ai][bj][m][n] = __builtin_amdgcn_mfma_f32_16x16x32_bf16(Bt[n][k], At[m][k], acc[ai][bj][m][n], 0, 0, 0); __builtin_amdgcn_s_setprio(0); } while (0)
; #define PG8_WAIT_V(n) asm volatile("s_waitcnt vmcnt(" #n ")" ::: "memory")
; #define PG8_WAIT_L(n) asm volatile("s_waitcnt lgkmcnt(" #n ")" ::: "memory")
; #define PG8_BAR __builtin_amdgcn_s_barrier()
; #define PG8_SCHED __builtin_amdgcn_sched_barrier(0)
; template <class Epi, class Sched, bool ALIGN_EPI = false, bool SP2 = false>
; __device__ __forceinline__ void gemm_phase(PG8_LAS unsigned char* lds, const Gemm g, const Sched& S, const Epi& E) {
;     ...
;             PG8_LDA(At, 1, 1); PG8_STAGE(PG8_SB(1, 0), b3, voffB); PG8_STAGE(PG8_SB(1, 1), b3 + hstep, voffB); PG8_STAGE(PG8_SA(1, 0), a3, voffA);
;             PG8_WAIT_V(8); PG8_WAIT_L(0); PG8_BAR; PG8_MMA(1, 0, At, B0); PG8_MMA(1, 1, At, B1); PG8_BAR; PG8_SCHED;
;     ...
;         if constexpr (ALIGN_EPI) { if (wr == 0) PG8_BAR; }
	s_setprio 0
	s_add_i32 s50, s73, s13
	v_lshl_add_u64 v[210:211], v[210:211], 0, s[20:21]
	s_mov_b32 m0, s50
	ds_read_b128 v[160:163], v222 offset:49152
	ds_read_b128 v[164:167], v222 offset:50176
	ds_read_b128 v[168:171], v222 offset:51200
	ds_read_b128 v[172:175], v222 offset:52224
	ds_read_b128 v[176:179], v222 offset:53248
	ds_read_b128 v[180:183], v222 offset:54272
	ds_read_b128 v[202:205], v222 offset:55296
	ds_read_b128 v[206:209], v222 offset:56320
	global_load_lds_dwordx4 v[210:211], off
	s_add_i32 m0, s50, 0x2000
	s_add_u32 s44, s44, 0x40080
	v_lshl_add_u64 v[210:211], v[212:213], 0, s[20:21]
	s_addc_u32 s45, s45, 0
	s_add_i32 s50, s74, s13
	global_load_lds_dwordx4 v[210:211], off
	v_lshl_add_u64 v[210:211], s[44:45], 0, v[188:189]
	s_mov_b32 m0, s50
	s_nop 0
	global_load_lds_dwordx4 v[210:211], off
	v_lshl_add_u64 v[210:211], s[44:45], 0, v[184:185]
	s_add_i32 m0, s50, 0x2000
	s_nop 0
	global_load_lds_dwordx4 v[210:211], off
	v_lshl_add_u64 v[210:211], v[214:215], 0, s[20:21]
	s_mov_b32 m0, s64
	s_nop 0
	global_load_lds_dwordx4 v[210:211], off
	v_lshl_add_u64 v[210:211], v[224:225], 0, s[20:21]
	s_mov_b32 m0, s65
	s_nop 0
	global_load_lds_dwordx4 v[210:211], off
	s_waitcnt vmcnt(8)
	s_waitcnt lgkmcnt(0)
	s_setprio 1
	s_barrier
	v_mfma_f32_16x16x32_bf16 v[60:63], v[128:131], v[160:163], v[60:63]
	v_mfma_f32_16x16x32_bf16 v[56:59], v[136:139], v[160:163], v[56:59]
	v_mfma_f32_16x16x32_bf16 v[44:47], v[128:131], v[168:171], v[44:47]
	v_mfma_f32_16x16x32_bf16 v[40:43], v[136:139], v[168:171], v[40:43]
	v_mfma_f32_16x16x32_bf16 v[28:31], v[128:131], v[176:179], v[28:31]
	v_mfma_f32_16x16x32_bf16 v[24:27], v[136:139], v[176:179], v[24:27]
	v_mfma_f32_16x16x32_bf16 v[12:15], v[128:131], v[202:205], v[12:15]
	v_mfma_f32_16x16x32_bf16 v[8:11], v[136:139], v[202:205], v[8:11]
	v_mfma_f32_16x16x32_bf16 v[60:63], v[132:135], v[164:167], v[60:63]
	v_mfma_f32_16x16x32_bf16 v[56:59], v[140:143], v[164:167], v[56:59]
	v_mfma_f32_16x16x32_bf16 v[44:47], v[132:135], v[172:175], v[44:47]
	v_mfma_f32_16x16x32_bf16 v[40:43], v[140:143], v[172:175], v[40:43]
	v_mfma_f32_16x16x32_bf16 v[28:31], v[132:135], v[180:183], v[28:31]
	v_mfma_f32_16x16x32_bf16 v[24:27], v[140:143], v[180:183], v[24:27]
	v_mfma_f32_16x16x32_bf16 v[12:15], v[132:135], v[206:209], v[12:15]
	v_mfma_f32_16x16x32_bf16 v[8:11], v[140:143], v[206:209], v[8:11]
	v_mfma_f32_16x16x32_bf16 v[52:55], v[144:147], v[160:163], v[52:55]
	v_mfma_f32_16x16x32_bf16 v[48:51], v[152:155], v[160:163], v[48:51]
	v_mfma_f32_16x16x32_bf16 v[36:39], v[144:147], v[168:171], v[36:39]
	v_mfma_f32_16x16x32_bf16 v[32:35], v[152:155], v[168:171], v[32:35]
	v_mfma_f32_16x16x32_bf16 v[20:23], v[144:147], v[176:179], v[20:23]
	v_mfma_f32_16x16x32_bf16 v[16:19], v[152:155], v[176:179], v[16:19]
	v_mfma_f32_16x16x32_bf16 v[4:7], v[144:147], v[202:205], v[4:7]
	v_mfma_f32_16x16x32_bf16 v[0:3], v[152:155], v[202:205], v[0:3]
	v_mfma_f32_16x16x32_bf16 v[52:55], v[148:151], v[164:167], v[52:55]
	v_mfma_f32_16x16x32_bf16 v[48:51], v[156:159], v[164:167], v[48:51]
	v_mfma_f32_16x16x32_bf16 v[36:39], v[148:151], v[172:175], v[36:39]
	v_mfma_f32_16x16x32_bf16 v[32:35], v[156:159], v[172:175], v[32:35]
	v_mfma_f32_16x16x32_bf16 v[20:23], v[148:151], v[180:183], v[20:23]
	v_mfma_f32_16x16x32_bf16 v[16:19], v[156:159], v[180:183], v[16:19]
	v_mfma_f32_16x16x32_bf16 v[4:7], v[148:151], v[206:209], v[4:7]
	v_mfma_f32_16x16x32_bf16 v[0:3], v[156:159], v[206:209], v[0:3]
	s_barrier
	s_setprio 0
	s_add_i32 s72, s72, 2
	s_add_u32 s36, s36, 0x100
	s_addc_u32 s37, s37, 0
	s_add_u32 s70, s70, 0x100
	s_addc_u32 s71, s71, 0
	s_cmp_gt_u32 s72, 13
	s_cbranch_scc0 .LBB0_573
	s_and_b64 vcc, exec, s[22:23]
	s_cbranch_vccz .LBB0_576
	s_barrier

; #define PG8_STAGE(bufoff, gbase, voff) do { _Pragma("unroll") for (int _i = 0; _i < 2; ++_i) \
;         __builtin_amdgcn_global_load_lds((const unsigned*)((const char*)(gbase) + (voff)[_i]), (PG8_LAS unsigned*)(lds + (bufoff) + ldsw + _i * 8192), 16, 0, 0); } while (0)
; #define PG8_LDA(dst, b, h) do { _Pragma("unroll") for (int m = 0; m < 4; ++m) _Pragma("unroll") for (int k = 0; k < 2; ++k) dst[m][k] = *(const PG8_LAS bf16x8*)(lds + PG8_SA(b, h) + aoff + m * 2048 + k * 1024); } while (0)
; #define PG8_LDB(dst, b, h) do { _Pragma("unroll") for (int n = 0; n < 2; ++n) _Pragma("unroll") for (int k = 0; k < 2; ++k) dst[n][k] = *(const PG8_LAS bf16x8*)(lds + PG8_SB(b, h) + boff + n * 2048 + k * 1024); } while (0)
; #define PG8_WAIT_V(n) asm volatile("s_waitcnt vmcnt(" #n ")" ::: "memory")
; #define PG8_WAIT_L(n) asm volatile("s_waitcnt lgkmcnt(" #n ")" ::: "memory")
; #define PG8_BAR __builtin_amdgcn_s_barrier()
; #define PG8_SCHED __builtin_amdgcn_sched_barrier(0)
; template <class Epi, class Sched, bool ALIGN_EPI = false, bool SP2 = false>
; __device__ __forceinline__ void gemm_phase(PG8_LAS unsigned char* lds, const Gemm g, const Sched& S, const Epi& E) {
;     ...
;         const bool has_next = S.next(ui + 1, nxt);
;         const char* nA = has_next ? (const char*)g.A + (size_t)nxt.pm * tstep : cA; const char* nB = has_next ? (const char*)g.Bt + (size_t)nxt.pn * tstep : cB;
;         for (int t = 0; t < nt; t += 2) {
;             const bool last = (t == nt - 2);
;             const char* a1 = cA + (size_t)(t + 1) * kstep;
;             const char* a2 = last ? nA : cA + (size_t)(t + 2) * kstep; const char* b2 = last ? nB : cB + (size_t)(t + 2) * kstep;
;             const char* a3 = a2 + kstep; const char* b3 = b2 + kstep;
;             if (last && has_next) S.a_ready(nxt);
;             if constexpr (SP2) {
;             PG8_LDB(B0, 0, 0); PG8_LDB(B1, 0, 1); PG8_SCHED; PG8_LDA(At, 0, 0); PG8_STAGE(PG8_SA(1, 1), a1 + hstep, voffA);
;             PG8_WAIT_V(8); PG8_WAIT_L(0); PG8_BAR; PG8_MMA(0, 0, At, B0); PG8_MMA(0, 1, At, B1); PG8_BAR; PG8_SCHED;
;             PG8_LDA(At, 0, 1); PG8_STAGE(PG8_SB(0, 0), b2, voffB); PG8_STAGE(PG8_SB(0, 1), b2 + hstep, voffB); PG8_STAGE(PG8_SA(0, 0), a2, voffA);
;             PG8_WAIT_V(8); PG8_WAIT_L(0); PG8_BAR; PG8_MMA(1, 0, At, B0); PG8_MMA(1, 1, At, B1); PG8_BAR; PG8_SCHED;
.LBB0_644:
	s_ashr_i32 s27, s26, 31
	s_lshl_b64 s[28:29], s[26:27], 20
	s_add_u32 s28, s13, s28
	s_addc_u32 s29, s47, s29
	s_and_b64 s[30:31], s[38:39], exec
	s_cselect_b32 s27, s29, s37
	s_cselect_b32 s70, s28, s36
	s_ashr_i32 s25, s24, 31
	s_lshl_b64 s[30:31], s[24:25], 20
	s_add_u32 s30, s52, s30
	s_addc_u32 s31, s53, s31
	s_and_b64 s[44:45], s[38:39], exec
	s_cselect_b32 s25, s31, s41
	s_cselect_b32 s71, s30, s40
	s_add_u32 s72, s40, 0x100
	s_addc_u32 s73, s41, 0
	s_mov_b32 s74, -2
	ds_read_b128 v[92:95], v196
	ds_read_b128 v[100:103], v196 offset:1024
	ds_read_b128 v[108:111], v196 offset:2048
	ds_read_b128 v[116:119], v196 offset:3072
	ds_read_b128 v[144:147], v197
	ds_read_b128 v[148:151], v197 offset:1024
	ds_read_b128 v[152:155], v197 offset:2048
	ds_read_b128 v[156:159], v197 offset:3072
	s_add_u32 s40, s36, 0x100
	s_addc_u32 s41, s37, 0
	s_cmp_eq_u32 s74, 28
	s_cselect_b32 s51, s27, s41
	s_cselect_b32 s50, s70, s40
	s_cselect_b32 s45, s25, s73
	s_cselect_b32 s44, s71, s72
	v_lshl_add_u64 v[212:213], s[36:37], 0, v[176:177]
	s_add_i32 m0, s55, 0xc000
	ds_read_b128 v[160:163], v198
	ds_read_b128 v[164:167], v198 offset:1024
	ds_read_b128 v[168:171], v198 offset:2048
	ds_read_b128 v[184:187], v198 offset:3072
	ds_read_b128 v[188:191], v198 offset:4096
	ds_read_b128 v[200:203], v198 offset:5120
	ds_read_b128 v[204:207], v198 offset:6144
	ds_read_b128 v[208:211], v198 offset:7168
	global_load_lds_dwordx4 v[212:213], off
	v_lshl_add_u64 v[212:213], s[36:37], 0, v[178:179]
	s_add_i32 m0, s55, 0xe000
	s_nop 0
	global_load_lds_dwordx4 v[212:213], off
	s_waitcnt vmcnt(8)
	s_waitcnt lgkmcnt(0)
	s_setprio 1
	s_barrier
	v_mfma_f32_16x16x32_bf16 v[140:143], v[92:95], v[160:163], 0
	v_mfma_f32_16x16x32_bf16 v[136:139], v[108:111], v[160:163], 0
	v_mfma_f32_16x16x32_bf16 v[132:135], v[92:95], v[168:171], 0
	v_mfma_f32_16x16x32_bf16 v[120:123], v[108:111], v[168:171], 0
	v_mfma_f32_16x16x32_bf16 v[112:115], v[92:95], v[188:191], 0
	v_mfma_f32_16x16x32_bf16 v[88:91], v[108:111], v[188:191], 0
	v_mfma_f32_16x16x32_bf16 v[76:79], v[92:95], v[204:207], 0
	v_mfma_f32_16x16x32_bf16 v[72:75], v[108:111], v[204:207], 0
	v_mfma_f32_16x16x32_bf16 v[140:143], v[100:103], v[164:167], v[140:143]
	v_mfma_f32_16x16x32_bf16 v[136:139], v[116:119], v[164:167], v[136:139]
	v_mfma_f32_16x16x32_bf16 v[132:135], v[100:103], v[184:187], v[132:135]
	v_mfma_f32_16x16x32_bf16 v[120:123], v[116:119], v[184:187], v[120:123]
	v_mfma_f32_16x16x32_bf16 v[112:115], v[100:103], v[200:203], v[112:115]
	v_mfma_f32_16x16x32_bf16 v[88:91], v[116:119], v[200:203], v[88:91]
	v_mfma_f32_16x16x32_bf16 v[76:79], v[100:103], v[208:211], v[76:79]
	v_mfma_f32_16x16x32_bf16 v[72:75], v[116:119], v[208:211], v[72:75]
	v_mfma_f32_16x16x32_bf16 v[128:131], v[144:147], v[160:163], 0
	v_mfma_f32_16x16x32_bf16 v[124:127], v[152:155], v[160:163], 0
	v_mfma_f32_16x16x32_bf16 v[104:107], v[144:147], v[168:171], 0
	v_mfma_f32_16x16x32_bf16 v[96:99], v[152:155], v[168:171], 0
	v_mfma_f32_16x16x32_bf16 v[84:87], v[144:147], v[188:191], 0
	v_mfma_f32_16x16x32_bf16 v[80:83], v[152:155], v[188:191], 0
	v_mfma_f32_16x16x32_bf16 v[68:71], v[144:147], v[204:207], 0
	v_mfma_f32_16x16x32_bf16 v[64:67], v[152:155], v[204:207], 0
	v_mfma_f32_16x16x32_bf16 v[128:131], v[148:151], v[164:167], v[128:131]
	v_mfma_f32_16x16x32_bf16 v[124:127], v[156:159], v[164:167], v[124:127]
	v_mfma_f32_16x16x32_bf16 v[104:107], v[148:151], v[184:187], v[104:107]
	v_mfma_f32_16x16x32_bf16 v[96:99], v[156:159], v[184:187], v[96:99]
	v_mfma_f32_16x16x32_bf16 v[84:87], v[148:151], v[200:203], v[84:87]
	v_mfma_f32_16x16x32_bf16 v[80:83], v[156:159], v[200:203], v[80:83]
	v_mfma_f32_16x16x32_bf16 v[68:71], v[148:151], v[208:211], v[68:71]
	v_mfma_f32_16x16x32_bf16 v[64:67], v[156:159], v[208:211], v[64:67]
	s_barrier
	s_setprio 0
	s_add_i32 s36, s68, s54
	v_lshl_add_u64 v[212:213], s[44:45], 0, v[174:175]
	s_mov_b32 m0, s36
	ds_read_b128 v[160:163], v198 offset:16384
	ds_read_b128 v[164:167], v198 offset:17408
	ds_read_b128 v[168:171], v198 offset:18432
	ds_read_b128 v[184:187], v198 offset:19456
	ds_read_b128 v[188:191], v198 offset:20480
	ds_read_b128 v[200:203], v198 offset:21504
	ds_read_b128 v[204:207], v198 offset:22528
	ds_read_b128 v[208:211], v198 offset:23552
	global_load_lds_dwordx4 v[212:213], off
	s_add_i32 m0, s36, 0x2000
	s_add_u32 s36, s44, 0x80000
	v_lshl_add_u64 v[214:215], s[44:45], 0, v[172:173]
	s_addc_u32 s37, s45, 0
	s_add_i32 s75, s69, s54
	global_load_lds_dwordx4 v[214:215], off
	v_lshl_add_u64 v[218:219], s[36:37], 0, v[174:175]
	s_mov_b32 m0, s75
	v_lshl_add_u64 v[220:221], s[50:51], 0, v[172:173]
	global_load_lds_dwordx4 v[218:219], off
	v_lshl_add_u64 v[218:219], s[36:37], 0, v[172:173]
	s_add_i32 m0, s75, 0x2000
	s_nop 0
	global_load_lds_dwordx4 v[218:219], off
	v_lshl_add_u64 v[218:219], s[50:51], 0, v[174:175]
	s_mov_b32 m0, s55
	s_nop 0
	global_load_lds_dwordx4 v[218:219], off
	s_mov_b32 m0, s60
	s_nop 0
	global_load_lds_dwordx4 v[220:221], off
	s_waitcnt vmcnt(8)
	s_waitcnt lgkmcnt(0)
	s_setprio 1
	s_barrier
; #define PG8_STAGE(bufoff, gbase, voff) do { _Pragma("unroll") for (int _i = 0; _i < 2; ++_i) \
;         __builtin_amdgcn_global_load_lds((const unsigned*)((const char*)(gbase) + (voff)[_i]), (PG8_LAS unsigned*)(lds + (bufoff) + ldsw + _i * 8192), 16, 0, 0); } while (0)
; #define PG8_LDA(dst, b, h) do { _Pragma("unroll") for (int m = 0; m < 4; ++m) _Pragma("unroll") for (int k = 0; k < 2; ++k) dst[m][k] = *(const PG8_LAS bf16x8*)(lds + PG8_SA(b, h) + aoff + m * 2048 + k * 1024); } while (0)
; #define PG8_LDB(dst, b, h) do { _Pragma("unroll") for (int n = 0; n < 2; ++n) _Pragma("unroll") for (int k = 0; k < 2; ++k) dst[n][k] = *(const PG8_LAS bf16x8*)(lds + PG8_SB(b, h) + boff + n * 2048 + k * 1024); } while (0)
; #define PG8_MMA(ai, bj, At, Bt) do { __builtin_amdgcn_s_setprio(1); _Pragma("unroll") for (int m = 0; m < 4; ++m) _Pragma("unroll") for (int n = 0; n < 2; ++n) _Pragma("unroll") for (int k = 0; k < 2; ++k) \
;         acc[ai][bj][m][n] = __builtin_amdgcn_mfma_f32_16x16x32_bf16(Bt[n][k], At[m][k], acc[ai][bj][m][n], 0, 0, 0); __builtin_amdgcn_s_setprio(0); } while (0)
; #define PG8_WAIT_V(n) asm volatile("s_waitcnt vmcnt(" #n ")" ::: "memory")
; #define PG8_WAIT_L(n) asm volatile("s_waitcnt lgkmcnt(" #n ")" ::: "memory")
; #define PG8_BAR __builtin_amdgcn_s_barrier()
; #define PG8_SCHED __builtin_amdgcn_sched_barrier(0)
; template <class Epi, class Sched, bool ALIGN_EPI = false, bool SP2 = false>
; __device__ __forceinline__ void gemm_phase(PG8_LAS unsigned char* lds, const Gemm g, const Sched& S, const Epi& E) {
;     ...
;             PG8_WAIT_V(8); PG8_WAIT_L(0); PG8_BAR; PG8_MMA(0, 0, At, B0); PG8_MMA(0, 1, At, B1); PG8_BAR; PG8_SCHED;
;             PG8_LDA(At, 0, 1); PG8_STAGE(PG8_SB(0, 0), b2, voffB); PG8_STAGE(PG8_SB(0, 1), b2 + hstep, voffB); PG8_STAGE(PG8_SA(0, 0), a2, voffA);
;             PG8_WAIT_V(8); PG8_WAIT_L(0); PG8_BAR; PG8_MMA(1, 0, At, B0); PG8_MMA(1, 1, At, B1); PG8_BAR; PG8_SCHED;
;             PG8_LDB(B0, 1, 0); PG8_LDB(B1, 1, 1); PG8_SCHED; PG8_LDA(At, 1, 0); PG8_STAGE(PG8_SA(0, 1), a2 + hstep, voffA);
;             PG8_WAIT_V(8); PG8_WAIT_L(0); PG8_BAR; PG8_MMA(0, 0, At, B0); PG8_MMA(0, 1, At, B1); PG8_BAR; PG8_SCHED;
	v_mfma_f32_16x16x32_bf16 v[60:63], v[92:95], v[160:163], 0
	v_mfma_f32_16x16x32_bf16 v[56:59], v[108:111], v[160:163], 0
	v_mfma_f32_16x16x32_bf16 v[52:55], v[92:95], v[168:171], 0
	v_mfma_f32_16x16x32_bf16 v[40:43], v[108:111], v[168:171], 0
	v_mfma_f32_16x16x32_bf16 v[36:39], v[92:95], v[188:191], 0
	v_mfma_f32_16x16x32_bf16 v[24:27], v[108:111], v[188:191], 0
	v_mfma_f32_16x16x32_bf16 v[12:15], v[92:95], v[204:207], 0
	v_mfma_f32_16x16x32_bf16 v[8:11], v[108:111], v[204:207], 0
	v_mfma_f32_16x16x32_bf16 v[60:63], v[100:103], v[164:167], v[60:63]
	v_mfma_f32_16x16x32_bf16 v[56:59], v[116:119], v[164:167], v[56:59]
	v_mfma_f32_16x16x32_bf16 v[52:55], v[100:103], v[184:187], v[52:55]
	v_mfma_f32_16x16x32_bf16 v[40:43], v[116:119], v[184:187], v[40:43]
	v_mfma_f32_16x16x32_bf16 v[36:39], v[100:103], v[200:203], v[36:39]
	v_mfma_f32_16x16x32_bf16 v[24:27], v[116:119], v[200:203], v[24:27]
	v_mfma_f32_16x16x32_bf16 v[12:15], v[100:103], v[208:211], v[12:15]
	v_mfma_f32_16x16x32_bf16 v[8:11], v[116:119], v[208:211], v[8:11]
	v_mfma_f32_16x16x32_bf16 v[48:51], v[144:147], v[160:163], 0
	v_mfma_f32_16x16x32_bf16 v[44:47], v[152:155], v[160:163], 0
	v_mfma_f32_16x16x32_bf16 v[32:35], v[144:147], v[168:171], 0
	v_mfma_f32_16x16x32_bf16 v[28:31], v[152:155], v[168:171], 0
	v_mfma_f32_16x16x32_bf16 v[20:23], v[144:147], v[188:191], 0
	v_mfma_f32_16x16x32_bf16 v[16:19], v[152:155], v[188:191], 0
	v_mfma_f32_16x16x32_bf16 v[4:7], v[144:147], v[204:207], 0
	v_mfma_f32_16x16x32_bf16 v[0:3], v[152:155], v[204:207], 0
	v_mfma_f32_16x16x32_bf16 v[48:51], v[148:151], v[164:167], v[48:51]
	v_mfma_f32_16x16x32_bf16 v[44:47], v[156:159], v[164:167], v[44:47]
	v_mfma_f32_16x16x32_bf16 v[32:35], v[148:151], v[184:187], v[32:35]
	v_mfma_f32_16x16x32_bf16 v[28:31], v[156:159], v[184:187], v[28:31]
	v_mfma_f32_16x16x32_bf16 v[20:23], v[148:151], v[200:203], v[20:23]
	v_mfma_f32_16x16x32_bf16 v[16:19], v[156:159], v[200:203], v[16:19]
	v_mfma_f32_16x16x32_bf16 v[4:7], v[148:151], v[208:211], v[4:7]
	v_mfma_f32_16x16x32_bf16 v[0:3], v[156:159], v[208:211], v[0:3]
	s_barrier
	s_setprio 0
	s_add_i32 s75, 0, 0x18000
	s_add_i32 s76, 0, 0x1c000
	v_add_u32_e32 v116, s75, v194
	v_add_u32_e32 v156, s76, v194
	ds_read_b128 v[92:95], v116
	ds_read_b128 v[100:103], v116 offset:1024
	ds_read_b128 v[108:111], v116 offset:2048
	ds_read_b128 v[116:119], v116 offset:3072
	ds_read_b128 v[144:147], v156
	ds_read_b128 v[148:151], v156 offset:1024
	ds_read_b128 v[152:155], v156 offset:2048
	ds_read_b128 v[156:159], v156 offset:3072
	s_add_u32 s36, s50, 0x80000
	s_addc_u32 s37, s51, 0
	s_mov_b32 m0, s61
	v_lshl_add_u64 v[222:223], s[36:37], 0, v[174:175]
	ds_read_b128 v[160:163], v198 offset:32768
	ds_read_b128 v[164:167], v198 offset:33792
	ds_read_b128 v[168:171], v198 offset:34816
	ds_read_b128 v[184:187], v198 offset:35840
	ds_read_b128 v[188:191], v198 offset:36864
	ds_read_b128 v[200:203], v198 offset:37888
	ds_read_b128 v[204:207], v198 offset:38912
	ds_read_b128 v[208:211], v198 offset:39936
	global_load_lds_dwordx4 v[222:223], off
	v_lshl_add_u64 v[222:223], s[36:37], 0, v[172:173]
	s_mov_b32 m0, s62
	s_nop 0
	global_load_lds_dwordx4 v[222:223], off
	s_waitcnt vmcnt(8)
	s_waitcnt lgkmcnt(0)
	s_setprio 1
	s_barrier
	v_mfma_f32_16x16x32_bf16 v[140:143], v[92:95], v[160:163], v[140:143]
	v_mfma_f32_16x16x32_bf16 v[136:139], v[108:111], v[160:163], v[136:139]
	v_mfma_f32_16x16x32_bf16 v[132:135], v[92:95], v[168:171], v[132:135]
	v_mfma_f32_16x16x32_bf16 v[120:123], v[108:111], v[168:171], v[120:123]
	v_mfma_f32_16x16x32_bf16 v[112:115], v[92:95], v[188:191], v[112:115]
	v_mfma_f32_16x16x32_bf16 v[88:91], v[108:111], v[188:191], v[88:91]
	v_mfma_f32_16x16x32_bf16 v[76:79], v[92:95], v[204:207], v[76:79]
	v_mfma_f32_16x16x32_bf16 v[72:75], v[108:111], v[204:207], v[72:75]
	v_mfma_f32_16x16x32_bf16 v[140:143], v[100:103], v[164:167], v[140:143]
	v_mfma_f32_16x16x32_bf16 v[136:139], v[116:119], v[164:167], v[136:139]
	v_mfma_f32_16x16x32_bf16 v[132:135], v[100:103], v[184:187], v[132:135]
	v_mfma_f32_16x16x32_bf16 v[120:123], v[116:119], v[184:187], v[120:123]
	v_mfma_f32_16x16x32_bf16 v[112:115], v[100:103], v[200:203], v[112:115]
	v_mfma_f32_16x16x32_bf16 v[88:91], v[116:119], v[200:203], v[88:91]
	v_mfma_f32_16x16x32_bf16 v[76:79], v[100:103], v[208:211], v[76:79]
	v_mfma_f32_16x16x32_bf16 v[72:75], v[116:119], v[208:211], v[72:75]
	v_mfma_f32_16x16x32_bf16 v[128:131], v[144:147], v[160:163], v[128:131]
	v_mfma_f32_16x16x32_bf16 v[124:127], v[152:155], v[160:163], v[124:127]
	v_mfma_f32_16x16x32_bf16 v[104:107], v[144:147], v[168:171], v[104:107]
	v_mfma_f32_16x16x32_bf16 v[96:99], v[152:155], v[168:171], v[96:99]
	v_mfma_f32_16x16x32_bf16 v[84:87], v[144:147], v[188:191], v[84:87]
	v_mfma_f32_16x16x32_bf16 v[80:83], v[152:155], v[188:191], v[80:83]
	v_mfma_f32_16x16x32_bf16 v[68:71], v[144:147], v[204:207], v[68:71]
	v_mfma_f32_16x16x32_bf16 v[64:67], v[152:155], v[204:207], v[64:67]
	v_mfma_f32_16x16x32_bf16 v[128:131], v[148:151], v[164:167], v[128:131]
	v_mfma_f32_16x16x32_bf16 v[124:127], v[156:159], v[164:167], v[124:127]
	v_mfma_f32_16x16x32_bf16 v[104:107], v[148:151], v[184:187], v[104:107]
	v_mfma_f32_16x16x32_bf16 v[96:99], v[156:159], v[184:187], v[96:99]
	v_mfma_f32_16x16x32_bf16 v[84:87], v[148:151], v[200:203], v[84:87]
	v_mfma_f32_16x16x32_bf16 v[80:83], v[156:159], v[200:203], v[80:83]
	v_mfma_f32_16x16x32_bf16 v[68:71], v[148:151], v[208:211], v[68:71]
	v_mfma_f32_16x16x32_bf16 v[64:67], v[156:159], v[208:211], v[64:67]
	s_barrier
; #define PG8_STAGE(bufoff, gbase, voff) do { _Pragma("unroll") for (int _i = 0; _i < 2; ++_i) \
;         __builtin_amdgcn_global_load_lds((const unsigned*)((const char*)(gbase) + (voff)[_i]), (PG8_LAS unsigned*)(lds + (bufoff) + ldsw + _i * 8192), 16, 0, 0); } while (0)
; #define PG8_LDA(dst, b, h) do { _Pragma("unroll") for (int m = 0; m < 4; ++m) _Pragma("unroll") for (int k = 0; k < 2; ++k) dst[m][k] = *(const PG8_LAS bf16x8*)(lds + PG8_SA(b, h) + aoff + m * 2048 + k * 1024); } while (0)
; #define PG8_LDB(dst, b, h) do { _Pragma("unroll") for (int n = 0; n < 2; ++n) _Pragma("unroll") for (int k = 0; k < 2; ++k) dst[n][k] = *(const PG8_LAS bf16x8*)(lds + PG8_SB(b, h) + boff + n * 2048 + k * 1024); } while (0)
; template <class Epi, class Sched, bool ALIGN_EPI = false, bool SP2 = false>
; __device__ __forceinline__ void gemm_phase(PG8_LAS unsigned char* lds, const Gemm g, const Sched& S, const Epi& E) {
;     ...
;         for (int t = 0; t < nt; t += 2) {
;             const bool last = (t == nt - 2);
;             const char* a1 = cA + (size_t)(t + 1) * kstep;
;             const char* a2 = last ? nA : cA + (size_t)(t + 2) * kstep; const char* b2 = last ? nB : cB + (size_t)(t + 2) * kstep;
;             const char* a3 = a2 + kstep; const char* b3 = b2 + kstep;
;             if (last && has_next) S.a_ready(nxt);
;             if constexpr (SP2) {
;             PG8_LDB(B0, 0, 0); PG8_LDB(B1, 0, 1); PG8_SCHED; PG8_LDA(At, 0, 0); PG8_STAGE(PG8_SA(1, 1), a1 + hstep, voffA);
;             PG8_WAIT_V(8); PG8_WAIT_L(0); PG8_BAR; PG8_MMA(0, 0, At, B0); PG8_MMA(0, 1, At, B1); PG8_BAR; PG8_SCHED;
;             PG8_LDA(At, 0, 1); PG8_STAGE(PG8_SB(0, 0), b2, voffB); PG8_STAGE(PG8_SB(0, 1), b2 + hstep, voffB); PG8_STAGE(PG8_SA(0, 0), a2, voffA);
;             PG8_WAIT_V(8); PG8_WAIT_L(0); PG8_BAR; PG8_MMA(1, 0, At, B0); PG8_MMA(1, 1, At, B1); PG8_BAR; PG8_SCHED;
;             PG8_LDB(B0, 1, 0); PG8_LDB(B1, 1, 1); PG8_SCHED; PG8_LDA(At, 1, 0); PG8_STAGE(PG8_SA(0, 1), a2 + hstep, voffA);
;             PG8_WAIT_V(8); PG8_WAIT_L(0); PG8_BAR; PG8_MMA(0, 0, At, B0); PG8_MMA(0, 1, At, B1); PG8_BAR; PG8_SCHED;
;             PG8_LDA(At, 1, 1); PG8_STAGE(PG8_SB(1, 0), b3, voffB); PG8_STAGE(PG8_SB(1, 1), b3 + hstep, voffB); PG8_STAGE(PG8_SA(1, 0), a3, voffA);
;             PG8_WAIT_V(8); PG8_WAIT_L(0); PG8_BAR; PG8_MMA(1, 0, At, B0); PG8_MMA(1, 1, At, B1); PG8_BAR; PG8_SCHED;
	s_setprio 0
	s_add_i32 s36, s75, s54
	v_lshl_add_u64 v[212:213], v[212:213], 0, s[20:21]
	s_mov_b32 m0, s36
	ds_read_b128 v[160:163], v198 offset:49152
	ds_read_b128 v[164:167], v198 offset:50176
	ds_read_b128 v[168:171], v198 offset:51200
	ds_read_b128 v[184:187], v198 offset:52224
	ds_read_b128 v[188:191], v198 offset:53248
	ds_read_b128 v[200:203], v198 offset:54272
	ds_read_b128 v[204:207], v198 offset:55296
	ds_read_b128 v[208:211], v198 offset:56320
	global_load_lds_dwordx4 v[212:213], off
	s_add_i32 m0, s36, 0x2000
	s_add_u32 s36, s44, 0x80080
	v_lshl_add_u64 v[212:213], v[214:215], 0, s[20:21]
	s_addc_u32 s37, s45, 0
	s_add_i32 s44, s76, s54
	global_load_lds_dwordx4 v[212:213], off
	v_lshl_add_u64 v[212:213], s[36:37], 0, v[174:175]
	s_mov_b32 m0, s44
	s_nop 0
	global_load_lds_dwordx4 v[212:213], off
	v_lshl_add_u64 v[212:213], s[36:37], 0, v[172:173]
	s_add_i32 m0, s44, 0x2000
	s_nop 0
	global_load_lds_dwordx4 v[212:213], off
	v_lshl_add_u64 v[212:213], v[218:219], 0, s[20:21]
	s_mov_b32 m0, s66
	s_nop 0
	global_load_lds_dwordx4 v[212:213], off
	v_lshl_add_u64 v[212:213], v[220:221], 0, s[20:21]
	s_mov_b32 m0, s67
	s_nop 0
	global_load_lds_dwordx4 v[212:213], off
	s_waitcnt vmcnt(8)
	s_waitcnt lgkmcnt(0)
	s_setprio 1
	s_barrier
	v_mfma_f32_16x16x32_bf16 v[60:63], v[92:95], v[160:163], v[60:63]
	v_mfma_f32_16x16x32_bf16 v[56:59], v[108:111], v[160:163], v[56:59]
	v_mfma_f32_16x16x32_bf16 v[52:55], v[92:95], v[168:171], v[52:55]
	v_mfma_f32_16x16x32_bf16 v[40:43], v[108:111], v[168:171], v[40:43]
	v_mfma_f32_16x16x32_bf16 v[36:39], v[92:95], v[188:191], v[36:39]
	v_mfma_f32_16x16x32_bf16 v[24:27], v[108:111], v[188:191], v[24:27]
	v_mfma_f32_16x16x32_bf16 v[12:15], v[92:95], v[204:207], v[12:15]
	v_mfma_f32_16x16x32_bf16 v[8:11], v[108:111], v[204:207], v[8:11]
	v_mfma_f32_16x16x32_bf16 v[60:63], v[100:103], v[164:167], v[60:63]
	v_mfma_f32_16x16x32_bf16 v[56:59], v[116:119], v[164:167], v[56:59]
	v_mfma_f32_16x16x32_bf16 v[52:55], v[100:103], v[184:187], v[52:55]
	v_mfma_f32_16x16x32_bf16 v[40:43], v[116:119], v[184:187], v[40:43]
	v_mfma_f32_16x16x32_bf16 v[36:39], v[100:103], v[200:203], v[36:39]
	v_mfma_f32_16x16x32_bf16 v[24:27], v[116:119], v[200:203], v[24:27]
	v_mfma_f32_16x16x32_bf16 v[12:15], v[100:103], v[208:211], v[12:15]
	v_mfma_f32_16x16x32_bf16 v[8:11], v[116:119], v[208:211], v[8:11]
	v_mfma_f32_16x16x32_bf16 v[48:51], v[144:147], v[160:163], v[48:51]
	v_mfma_f32_16x16x32_bf16 v[44:47], v[152:155], v[160:163], v[44:47]
	v_mfma_f32_16x16x32_bf16 v[32:35], v[144:147], v[168:171], v[32:35]
	v_mfma_f32_16x16x32_bf16 v[28:31], v[152:155], v[168:171], v[28:31]
	v_mfma_f32_16x16x32_bf16 v[20:23], v[144:147], v[188:191], v[20:23]
	v_mfma_f32_16x16x32_bf16 v[16:19], v[152:155], v[188:191], v[16:19]
	v_mfma_f32_16x16x32_bf16 v[4:7], v[144:147], v[204:207], v[4:7]
	v_mfma_f32_16x16x32_bf16 v[0:3], v[152:155], v[204:207], v[0:3]
	v_mfma_f32_16x16x32_bf16 v[48:51], v[148:151], v[164:167], v[48:51]
	v_mfma_f32_16x16x32_bf16 v[44:47], v[156:159], v[164:167], v[44:47]
	v_mfma_f32_16x16x32_bf16 v[32:35], v[148:151], v[184:187], v[32:35]
	v_mfma_f32_16x16x32_bf16 v[28:31], v[156:159], v[184:187], v[28:31]
	v_mfma_f32_16x16x32_bf16 v[20:23], v[148:151], v[200:203], v[20:23]
	v_mfma_f32_16x16x32_bf16 v[16:19], v[156:159], v[200:203], v[16:19]
	v_mfma_f32_16x16x32_bf16 v[4:7], v[148:151], v[208:211], v[4:7]
	v_mfma_f32_16x16x32_bf16 v[0:3], v[156:159], v[208:211], v[0:3]
	s_barrier
	s_setprio 0
	s_add_i32 s74, s74, 2
	s_add_u32 s72, s72, 0x100
	s_addc_u32 s73, s73, 0
	s_cmp_gt_u32 s74, 29
	s_mov_b64 s[36:37], s[40:41]
.LBB0_645:
	ds_read_b128 v[92:95], v196
	ds_read_b128 v[100:103], v196 offset:1024
	ds_read_b128 v[108:111], v196 offset:2048
	ds_read_b128 v[116:119], v196 offset:3072
	ds_read_b128 v[144:147], v197
	ds_read_b128 v[148:151], v197 offset:1024
	ds_read_b128 v[152:155], v197 offset:2048
	ds_read_b128 v[156:159], v197 offset:3072
	s_add_u32 s40, s36, 0x100
	s_addc_u32 s41, s37, 0
	s_cmp_eq_u32 s74, 28
	s_cselect_b32 s51, s27, s41
	s_cselect_b32 s50, s70, s40
	s_cselect_b32 s45, s25, s73
	s_cselect_b32 s44, s71, s72
	v_lshl_add_u64 v[212:213], s[36:37], 0, v[176:177]
	s_add_i32 m0, s55, 0xc000
	ds_read_b128 v[160:163], v198
	ds_read_b128 v[164:167], v198 offset:1024
	ds_read_b128 v[168:171], v198 offset:2048
	ds_read_b128 v[184:187], v198 offset:3072
	ds_read_b128 v[188:191], v198 offset:4096
	ds_read_b128 v[200:203], v198 offset:5120
	ds_read_b128 v[204:207], v198 offset:6144
	ds_read_b128 v[208:211], v198 offset:7168
	global_load_lds_dwordx4 v[212:213], off
	v_lshl_add_u64 v[212:213], s[36:37], 0, v[178:179]
	s_add_i32 m0, s55, 0xe000
	s_nop 0
	global_load_lds_dwordx4 v[212:213], off
	s_waitcnt vmcnt(8)
	s_waitcnt lgkmcnt(0)
	s_setprio 1
	s_barrier
; #define PG8_STAGE(bufoff, gbase, voff) do { _Pragma("unroll") for (int _i = 0; _i < 2; ++_i) \
;         __builtin_amdgcn_global_load_lds((const unsigned*)((const char*)(gbase) + (voff)[_i]), (PG8_LAS unsigned*)(lds + (bufoff) + ldsw + _i * 8192), 16, 0, 0); } while (0)
; #define PG8_LDA(dst, b, h) do { _Pragma("unroll") for (int m = 0; m < 4; ++m) _Pragma("unroll") for (int k = 0; k < 2; ++k) dst[m][k] = *(const PG8_LAS bf16x8*)(lds + PG8_SA(b, h) + aoff + m * 2048 + k * 1024); } while (0)
; #define PG8_MMA(ai, bj, At, Bt) do { __builtin_amdgcn_s_setprio(1); _Pragma("unroll") for (int m = 0; m < 4; ++m) _Pragma("unroll") for (int n = 0; n < 2; ++n) _Pragma("unroll") for (int k = 0; k < 2; ++k) \
;         acc[ai][bj][m][n] = __builtin_amdgcn_mfma_f32_16x16x32_bf16(Bt[n][k], At[m][k], acc[ai][bj][m][n], 0, 0, 0); __builtin_amdgcn_s_setprio(0); } while (0)
; #define PG8_WAIT_V(n) asm volatile("s_waitcnt vmcnt(" #n ")" ::: "memory")
; #define PG8_WAIT_L(n) asm volatile("s_waitcnt lgkmcnt(" #n ")" ::: "memory")
; #define PG8_BAR __builtin_amdgcn_s_barrier()
; #define PG8_SCHED __builtin_amdgcn_sched_barrier(0)
; template <class Epi, class Sched, bool ALIGN_EPI = false, bool SP2 = false>
; __device__ __forceinline__ void gemm_phase(PG8_LAS unsigned char* lds, const Gemm g, const Sched& S, const Epi& E) {
;     ...
;             PG8_WAIT_V(8); PG8_WAIT_L(0); PG8_BAR; PG8_MMA(0, 0, At, B0); PG8_MMA(0, 1, At, B1); PG8_BAR; PG8_SCHED;
;             PG8_LDA(At, 0, 1); PG8_STAGE(PG8_SB(0, 0), b2, voffB); PG8_STAGE(PG8_SB(0, 1), b2 + hstep, voffB); PG8_STAGE(PG8_SA(0, 0), a2, voffA);
;             PG8_WAIT_V(8); PG8_WAIT_L(0); PG8_BAR; PG8_MMA(1, 0, At, B0); PG8_MMA(1, 1, At, B1); PG8_BAR; PG8_SCHED;
	v_mfma_f32_16x16x32_bf16 v[140:143], v[92:95], v[160:163], v[140:143]
	v_mfma_f32_16x16x32_bf16 v[136:139], v[108:111], v[160:163], v[136:139]
	v_mfma_f32_16x16x32_bf16 v[132:135], v[92:95], v[168:171], v[132:135]
	v_mfma_f32_16x16x32_bf16 v[120:123], v[108:111], v[168:171], v[120:123]
	v_mfma_f32_16x16x32_bf16 v[112:115], v[92:95], v[188:191], v[112:115]
	v_mfma_f32_16x16x32_bf16 v[88:91], v[108:111], v[188:191], v[88:91]
	v_mfma_f32_16x16x32_bf16 v[76:79], v[92:95], v[204:207], v[76:79]
	v_mfma_f32_16x16x32_bf16 v[72:75], v[108:111], v[204:207], v[72:75]
	v_mfma_f32_16x16x32_bf16 v[140:143], v[100:103], v[164:167], v[140:143]
	v_mfma_f32_16x16x32_bf16 v[136:139], v[116:119], v[164:167], v[136:139]
	v_mfma_f32_16x16x32_bf16 v[132:135], v[100:103], v[184:187], v[132:135]
	v_mfma_f32_16x16x32_bf16 v[120:123], v[116:119], v[184:187], v[120:123]
	v_mfma_f32_16x16x32_bf16 v[112:115], v[100:103], v[200:203], v[112:115]
	v_mfma_f32_16x16x32_bf16 v[88:91], v[116:119], v[200:203], v[88:91]
	v_mfma_f32_16x16x32_bf16 v[76:79], v[100:103], v[208:211], v[76:79]
	v_mfma_f32_16x16x32_bf16 v[72:75], v[116:119], v[208:211], v[72:75]
	v_mfma_f32_16x16x32_bf16 v[128:131], v[144:147], v[160:163], v[128:131]
	v_mfma_f32_16x16x32_bf16 v[124:127], v[152:155], v[160:163], v[124:127]
	v_mfma_f32_16x16x32_bf16 v[104:107], v[144:147], v[168:171], v[104:107]
	v_mfma_f32_16x16x32_bf16 v[96:99], v[152:155], v[168:171], v[96:99]
	v_mfma_f32_16x16x32_bf16 v[84:87], v[144:147], v[188:191], v[84:87]
	v_mfma_f32_16x16x32_bf16 v[80:83], v[152:155], v[188:191], v[80:83]
	v_mfma_f32_16x16x32_bf16 v[68:71], v[144:147], v[204:207], v[68:71]
	v_mfma_f32_16x16x32_bf16 v[64:67], v[152:155], v[204:207], v[64:67]
	v_mfma_f32_16x16x32_bf16 v[128:131], v[148:151], v[164:167], v[128:131]
	v_mfma_f32_16x16x32_bf16 v[124:127], v[156:159], v[164:167], v[124:127]
	v_mfma_f32_16x16x32_bf16 v[104:107], v[148:151], v[184:187], v[104:107]
	v_mfma_f32_16x16x32_bf16 v[96:99], v[156:159], v[184:187], v[96:99]
	v_mfma_f32_16x16x32_bf16 v[84:87], v[148:151], v[200:203], v[84:87]
	v_mfma_f32_16x16x32_bf16 v[80:83], v[156:159], v[200:203], v[80:83]
	v_mfma_f32_16x16x32_bf16 v[68:71], v[148:151], v[208:211], v[68:71]
	v_mfma_f32_16x16x32_bf16 v[64:67], v[156:159], v[208:211], v[64:67]
	s_barrier
	s_setprio 0
	s_add_i32 s36, s68, s54
	v_lshl_add_u64 v[212:213], s[44:45], 0, v[174:175]
	s_mov_b32 m0, s36
	ds_read_b128 v[160:163], v198 offset:16384
	ds_read_b128 v[164:167], v198 offset:17408
	ds_read_b128 v[168:171], v198 offset:18432
	ds_read_b128 v[184:187], v198 offset:19456
	ds_read_b128 v[188:191], v198 offset:20480
	ds_read_b128 v[200:203], v198 offset:21504
	ds_read_b128 v[204:207], v198 offset:22528
	ds_read_b128 v[208:211], v198 offset:23552
	global_load_lds_dwordx4 v[212:213], off
	s_add_i32 m0, s36, 0x2000
	s_add_u32 s36, s44, 0x80000
	v_lshl_add_u64 v[214:215], s[44:45], 0, v[172:173]
	s_addc_u32 s37, s45, 0
	s_add_i32 s75, s69, s54
	global_load_lds_dwordx4 v[214:215], off
	v_lshl_add_u64 v[218:219], s[36:37], 0, v[174:175]
	s_mov_b32 m0, s75
	v_lshl_add_u64 v[220:221], s[50:51], 0, v[172:173]
	global_load_lds_dwordx4 v[218:219], off
	v_lshl_add_u64 v[218:219], s[36:37], 0, v[172:173]
	s_add_i32 m0, s75, 0x2000
	s_nop 0
	global_load_lds_dwordx4 v[218:219], off
	v_lshl_add_u64 v[218:219], s[50:51], 0, v[174:175]
	s_mov_b32 m0, s55
	s_nop 0
	global_load_lds_dwordx4 v[218:219], off
	s_mov_b32 m0, s60
	s_nop 0
	global_load_lds_dwordx4 v[220:221], off
	s_waitcnt vmcnt(8)
	s_waitcnt lgkmcnt(0)
	s_setprio 1
	s_barrier
	v_mfma_f32_16x16x32_bf16 v[60:63], v[92:95], v[160:163], v[60:63]
	v_mfma_f32_16x16x32_bf16 v[56:59], v[108:111], v[160:163], v[56:59]
	v_mfma_f32_16x16x32_bf16 v[52:55], v[92:95], v[168:171], v[52:55]
	v_mfma_f32_16x16x32_bf16 v[40:43], v[108:111], v[168:171], v[40:43]
	v_mfma_f32_16x16x32_bf16 v[36:39], v[92:95], v[188:191], v[36:39]
	v_mfma_f32_16x16x32_bf16 v[24:27], v[108:111], v[188:191], v[24:27]
	v_mfma_f32_16x16x32_bf16 v[12:15], v[92:95], v[204:207], v[12:15]
	v_mfma_f32_16x16x32_bf16 v[8:11], v[108:111], v[204:207], v[8:11]
	v_mfma_f32_16x16x32_bf16 v[60:63], v[100:103], v[164:167], v[60:63]
	v_mfma_f32_16x16x32_bf16 v[56:59], v[116:119], v[164:167], v[56:59]
	v_mfma_f32_16x16x32_bf16 v[52:55], v[100:103], v[184:187], v[52:55]
	v_mfma_f32_16x16x32_bf16 v[40:43], v[116:119], v[184:187], v[40:43]
	v_mfma_f32_16x16x32_bf16 v[36:39], v[100:103], v[200:203], v[36:39]
	v_mfma_f32_16x16x32_bf16 v[24:27], v[116:119], v[200:203], v[24:27]
	v_mfma_f32_16x16x32_bf16 v[12:15], v[100:103], v[208:211], v[12:15]
	v_mfma_f32_16x16x32_bf16 v[8:11], v[116:119], v[208:211], v[8:11]
	v_mfma_f32_16x16x32_bf16 v[48:51], v[144:147], v[160:163], v[48:51]
	v_mfma_f32_16x16x32_bf16 v[44:47], v[152:155], v[160:163], v[44:47]
	v_mfma_f32_16x16x32_bf16 v[32:35], v[144:147], v[168:171], v[32:35]
	v_mfma_f32_16x16x32_bf16 v[28:31], v[152:155], v[168:171], v[28:31]
	v_mfma_f32_16x16x32_bf16 v[20:23], v[144:147], v[188:191], v[20:23]
	v_mfma_f32_16x16x32_bf16 v[16:19], v[152:155], v[188:191], v[16:19]
	v_mfma_f32_16x16x32_bf16 v[4:7], v[144:147], v[204:207], v[4:7]
	v_mfma_f32_16x16x32_bf16 v[0:3], v[152:155], v[204:207], v[0:3]
	v_mfma_f32_16x16x32_bf16 v[48:51], v[148:151], v[164:167], v[48:51]
	v_mfma_f32_16x16x32_bf16 v[44:47], v[156:159], v[164:167], v[44:47]
	v_mfma_f32_16x16x32_bf16 v[32:35], v[148:151], v[184:187], v[32:35]
	v_mfma_f32_16x16x32_bf16 v[28:31], v[156:159], v[184:187], v[28:31]
	v_mfma_f32_16x16x32_bf16 v[20:23], v[148:151], v[200:203], v[20:23]
	v_mfma_f32_16x16x32_bf16 v[16:19], v[156:159], v[200:203], v[16:19]
	v_mfma_f32_16x16x32_bf16 v[4:7], v[148:151], v[208:211], v[4:7]
	v_mfma_f32_16x16x32_bf16 v[0:3], v[156:159], v[208:211], v[0:3]
	s_barrier
; #define PG8_STAGE(bufoff, gbase, voff) do { _Pragma("unroll") for (int _i = 0; _i < 2; ++_i) \
;         __builtin_amdgcn_global_load_lds((const unsigned*)((const char*)(gbase) + (voff)[_i]), (PG8_LAS unsigned*)(lds + (bufoff) + ldsw + _i * 8192), 16, 0, 0); } while (0)
; #define PG8_LDA(dst, b, h) do { _Pragma("unroll") for (int m = 0; m < 4; ++m) _Pragma("unroll") for (int k = 0; k < 2; ++k) dst[m][k] = *(const PG8_LAS bf16x8*)(lds + PG8_SA(b, h) + aoff + m * 2048 + k * 1024); } while (0)
; #define PG8_LDB(dst, b, h) do { _Pragma("unroll") for (int n = 0; n < 2; ++n) _Pragma("unroll") for (int k = 0; k < 2; ++k) dst[n][k] = *(const PG8_LAS bf16x8*)(lds + PG8_SB(b, h) + boff + n * 2048 + k * 1024); } while (0)
; #define PG8_MMA(ai, bj, At, Bt) do { __builtin_amdgcn_s_setprio(1); _Pragma("unroll") for (int m = 0; m < 4; ++m) _Pragma("unroll") for (int n = 0; n < 2; ++n) _Pragma("unroll") for (int k = 0; k < 2; ++k) \
;         acc[ai][bj][m][n] = __builtin_amdgcn_mfma_f32_16x16x32_bf16(Bt[n][k], At[m][k], acc[ai][bj][m][n], 0, 0, 0); __builtin_amdgcn_s_setprio(0); } while (0)
; #define PG8_WAIT_V(n) asm volatile("s_waitcnt vmcnt(" #n ")" ::: "memory")
; #define PG8_WAIT_L(n) asm volatile("s_waitcnt lgkmcnt(" #n ")" ::: "memory")
; #define PG8_BAR __builtin_amdgcn_s_barrier()
; #define PG8_SCHED __builtin_amdgcn_sched_barrier(0)
; template <class Epi, class Sched, bool ALIGN_EPI = false, bool SP2 = false>
; __device__ __forceinline__ void gemm_phase(PG8_LAS unsigned char* lds, const Gemm g, const Sched& S, const Epi& E) {
;     ...
;             PG8_WAIT_V(8); PG8_WAIT_L(0); PG8_BAR; PG8_MMA(1, 0, At, B0); PG8_MMA(1, 1, At, B1); PG8_BAR; PG8_SCHED;
;             PG8_LDB(B0, 1, 0); PG8_LDB(B1, 1, 1); PG8_SCHED; PG8_LDA(At, 1, 0); PG8_STAGE(PG8_SA(0, 1), a2 + hstep, voffA);
;             PG8_WAIT_V(8); PG8_WAIT_L(0); PG8_BAR; PG8_MMA(0, 0, At, B0); PG8_MMA(0, 1, At, B1); PG8_BAR; PG8_SCHED;
	s_setprio 0
	s_add_i32 s75, 0, 0x18000
	s_add_i32 s76, 0, 0x1c000
	v_add_u32_e32 v116, s75, v194
	v_add_u32_e32 v156, s76, v194
	ds_read_b128 v[92:95], v116
	ds_read_b128 v[100:103], v116 offset:1024
	ds_read_b128 v[108:111], v116 offset:2048
	ds_read_b128 v[116:119], v116 offset:3072
	ds_read_b128 v[144:147], v156
	ds_read_b128 v[148:151], v156 offset:1024
	ds_read_b128 v[152:155], v156 offset:2048
	ds_read_b128 v[156:159], v156 offset:3072
	s_add_u32 s36, s50, 0x80000
	s_addc_u32 s37, s51, 0
	s_mov_b32 m0, s61
	v_lshl_add_u64 v[222:223], s[36:37], 0, v[174:175]
	ds_read_b128 v[160:163], v198 offset:32768
	ds_read_b128 v[164:167], v198 offset:33792
	ds_read_b128 v[168:171], v198 offset:34816
	ds_read_b128 v[184:187], v198 offset:35840
	ds_read_b128 v[188:191], v198 offset:36864
	ds_read_b128 v[200:203], v198 offset:37888
	ds_read_b128 v[204:207], v198 offset:38912
	ds_read_b128 v[208:211], v198 offset:39936
	global_load_lds_dwordx4 v[222:223], off
	v_lshl_add_u64 v[222:223], s[36:37], 0, v[172:173]
	s_mov_b32 m0, s62
	s_nop 0
	global_load_lds_dwordx4 v[222:223], off
	s_waitcnt vmcnt(8)
	s_waitcnt lgkmcnt(0)
	s_setprio 1
	s_barrier
	v_mfma_f32_16x16x32_bf16 v[140:143], v[92:95], v[160:163], v[140:143]
	v_mfma_f32_16x16x32_bf16 v[136:139], v[108:111], v[160:163], v[136:139]
	v_mfma_f32_16x16x32_bf16 v[132:135], v[92:95], v[168:171], v[132:135]
	v_mfma_f32_16x16x32_bf16 v[120:123], v[108:111], v[168:171], v[120:123]
	v_mfma_f32_16x16x32_bf16 v[112:115], v[92:95], v[188:191], v[112:115]
	v_mfma_f32_16x16x32_bf16 v[88:91], v[108:111], v[188:191], v[88:91]
	v_mfma_f32_16x16x32_bf16 v[76:79], v[92:95], v[204:207], v[76:79]
	v_mfma_f32_16x16x32_bf16 v[72:75], v[108:111], v[204:207], v[72:75]
	v_mfma_f32_16x16x32_bf16 v[140:143], v[100:103], v[164:167], v[140:143]
	v_mfma_f32_16x16x32_bf16 v[136:139], v[116:119], v[164:167], v[136:139]
	v_mfma_f32_16x16x32_bf16 v[132:135], v[100:103], v[184:187], v[132:135]
	v_mfma_f32_16x16x32_bf16 v[120:123], v[116:119], v[184:187], v[120:123]
	v_mfma_f32_16x16x32_bf16 v[112:115], v[100:103], v[200:203], v[112:115]
	v_mfma_f32_16x16x32_bf16 v[88:91], v[116:119], v[200:203], v[88:91]
	v_mfma_f32_16x16x32_bf16 v[76:79], v[100:103], v[208:211], v[76:79]
	v_mfma_f32_16x16x32_bf16 v[72:75], v[116:119], v[208:211], v[72:75]
	v_mfma_f32_16x16x32_bf16 v[128:131], v[144:147], v[160:163], v[128:131]
	v_mfma_f32_16x16x32_bf16 v[124:127], v[152:155], v[160:163], v[124:127]
	v_mfma_f32_16x16x32_bf16 v[104:107], v[144:147], v[168:171], v[104:107]
	v_mfma_f32_16x16x32_bf16 v[96:99], v[152:155], v[168:171], v[96:99]
	v_mfma_f32_16x16x32_bf16 v[84:87], v[144:147], v[188:191], v[84:87]
	v_mfma_f32_16x16x32_bf16 v[80:83], v[152:155], v[188:191], v[80:83]
	v_mfma_f32_16x16x32_bf16 v[68:71], v[144:147], v[204:207], v[68:71]
	v_mfma_f32_16x16x32_bf16 v[64:67], v[152:155], v[204:207], v[64:67]
	v_mfma_f32_16x16x32_bf16 v[128:131], v[148:151], v[164:167], v[128:131]
	v_mfma_f32_16x16x32_bf16 v[124:127], v[156:159], v[164:167], v[124:127]
	v_mfma_f32_16x16x32_bf16 v[104:107], v[148:151], v[184:187], v[104:107]
	v_mfma_f32_16x16x32_bf16 v[96:99], v[156:159], v[184:187], v[96:99]
	v_mfma_f32_16x16x32_bf16 v[84:87], v[148:151], v[200:203], v[84:87]
	v_mfma_f32_16x16x32_bf16 v[80:83], v[156:159], v[200:203], v[80:83]
	v_mfma_f32_16x16x32_bf16 v[68:71], v[148:151], v[208:211], v[68:71]
	v_mfma_f32_16x16x32_bf16 v[64:67], v[156:159], v[208:211], v[64:67]
	s_barrier
; #define PG8_STAGE(bufoff, gbase, voff) do { _Pragma("unroll") for (int _i = 0; _i < 2; ++_i) \
;         __builtin_amdgcn_global_load_lds((const unsigned*)((const char*)(gbase) + (voff)[_i]), (PG8_LAS unsigned*)(lds + (bufoff) + ldsw + _i * 8192), 16, 0, 0); } while (0)
; #define PG8_WAIT_V(n) asm volatile("s_waitcnt vmcnt(" #n ")" ::: "memory")
; #define PG8_WAIT_L(n) asm volatile("s_waitcnt lgkmcnt(" #n ")" ::: "memory")
; template <class Epi, class Sched, bool ALIGN_EPI = false, bool SP2 = false>
; __device__ __forceinline__ void gemm_phase(PG8_LAS unsigned char* lds, const Gemm g, const Sched& S, const Epi& E) {
;     ...
;             PG8_WAIT_V(8); PG8_WAIT_L(0); PG8_BAR; PG8_MMA(0, 0, At, B0); PG8_MMA(0, 1, At, B1); PG8_BAR; PG8_SCHED;
;             PG8_LDA(At, 1, 1); PG8_STAGE(PG8_SB(1, 0), b3, voffB); PG8_STAGE(PG8_SB(1, 1), b3 + hstep, voffB); PG8_STAGE(PG8_SA(1, 0), a3, voffA);
;             PG8_WAIT_V(8); PG8_WAIT_L(0); PG8_BAR; PG8_MMA(1, 0, At, B0); PG8_MMA(1, 1, At, B1); PG8_BAR; PG8_SCHED;
;             } else {
;             PG8_LDB(B0, 0, 0); PG8_SCHED; PG8_LDA(At, 0, 0); PG8_STAGE(PG8_SA(1, 1), a1 + hstep, voffA);
;             PG8_WAIT_L(8); PG8_BAR; PG8_WAIT_L(0); PG8_MMA(0, 0, At, B0); PG8_BAR; PG8_SCHED;
;             PG8_LDB(B1, 0, 1); PG8_STAGE(PG8_SB(0, 0), b2, voffB);
;             PG8_BAR; PG8_WAIT_L(0); PG8_MMA(0, 1, At, B1); PG8_BAR;
;             PG8_LDA(At, 0, 1); PG8_STAGE(PG8_SA(0, 0), a2, voffA);
;             PG8_BAR; PG8_WAIT_L(0); PG8_MMA(1, 0, At, B0); PG8_BAR; PG8_SCHED;
;             PG8_STAGE(PG8_SB(0, 1), b2 + hstep, voffB);
;             PG8_WAIT_V(6); PG8_BAR; PG8_MMA(1, 1, At, B1); PG8_BAR;
;             PG8_LDB(B0, 1, 0); PG8_SCHED; PG8_LDA(At, 1, 0); PG8_STAGE(PG8_SA(0, 1), a2 + hstep, voffA);
;             PG8_WAIT_L(8); PG8_BAR; PG8_WAIT_L(0); PG8_MMA(0, 0, At, B0); PG8_BAR; PG8_SCHED;
;             PG8_LDB(B1, 1, 1); PG8_STAGE(PG8_SB(1, 0), b3, voffB);
;             PG8_BAR; PG8_WAIT_L(0); PG8_MMA(0, 1, At, B1); PG8_BAR;
;             PG8_LDA(At, 1, 1); PG8_STAGE(PG8_SA(1, 0), a3, voffA);
;             PG8_BAR; PG8_WAIT_L(0); PG8_MMA(1, 0, At, B0); PG8_BAR; PG8_SCHED;
;             PG8_STAGE(PG8_SB(1, 1), b3 + hstep, voffB);
;             PG8_WAIT_V(6); PG8_BAR; PG8_MMA(1, 1, At, B1); PG8_BAR;
;             }
;         }
;         if constexpr (ALIGN_EPI) { if (wr == 0) PG8_BAR; }
	s_setprio 0
	s_add_i32 s36, s75, s54
	v_lshl_add_u64 v[212:213], v[212:213], 0, s[20:21]
	s_mov_b32 m0, s36
	ds_read_b128 v[160:163], v198 offset:49152
	ds_read_b128 v[164:167], v198 offset:50176
	ds_read_b128 v[168:171], v198 offset:51200
	ds_read_b128 v[184:187], v198 offset:52224
	ds_read_b128 v[188:191], v198 offset:53248
	ds_read_b128 v[200:203], v198 offset:54272
	ds_read_b128 v[204:207], v198 offset:55296
	ds_read_b128 v[208:211], v198 offset:56320
	global_load_lds_dwordx4 v[212:213], off
	s_add_i32 m0, s36, 0x2000
	s_add_u32 s36, s44, 0x80080
	v_lshl_add_u64 v[212:213], v[214:215], 0, s[20:21]
	s_addc_u32 s37, s45, 0
	s_add_i32 s44, s76, s54
	global_load_lds_dwordx4 v[212:213], off
	v_lshl_add_u64 v[212:213], s[36:37], 0, v[174:175]
	s_mov_b32 m0, s44
	s_nop 0
	global_load_lds_dwordx4 v[212:213], off
	v_lshl_add_u64 v[212:213], s[36:37], 0, v[172:173]
	s_add_i32 m0, s44, 0x2000
	s_nop 0
	global_load_lds_dwordx4 v[212:213], off
	v_lshl_add_u64 v[212:213], v[218:219], 0, s[20:21]
	s_mov_b32 m0, s66
	s_nop 0
	global_load_lds_dwordx4 v[212:213], off
	v_lshl_add_u64 v[212:213], v[220:221], 0, s[20:21]
	s_mov_b32 m0, s67
	s_nop 0
	global_load_lds_dwordx4 v[212:213], off
	s_waitcnt vmcnt(8)
	s_waitcnt lgkmcnt(0)
	s_setprio 1
	s_barrier
	v_mfma_f32_16x16x32_bf16 v[60:63], v[92:95], v[160:163], v[60:63]
	v_mfma_f32_16x16x32_bf16 v[56:59], v[108:111], v[160:163], v[56:59]
	v_mfma_f32_16x16x32_bf16 v[52:55], v[92:95], v[168:171], v[52:55]
	v_mfma_f32_16x16x32_bf16 v[40:43], v[108:111], v[168:171], v[40:43]
	v_mfma_f32_16x16x32_bf16 v[36:39], v[92:95], v[188:191], v[36:39]
	v_mfma_f32_16x16x32_bf16 v[24:27], v[108:111], v[188:191], v[24:27]
	v_mfma_f32_16x16x32_bf16 v[12:15], v[92:95], v[204:207], v[12:15]
	v_mfma_f32_16x16x32_bf16 v[8:11], v[108:111], v[204:207], v[8:11]
	v_mfma_f32_16x16x32_bf16 v[60:63], v[100:103], v[164:167], v[60:63]
	v_mfma_f32_16x16x32_bf16 v[56:59], v[116:119], v[164:167], v[56:59]
	v_mfma_f32_16x16x32_bf16 v[52:55], v[100:103], v[184:187], v[52:55]
	v_mfma_f32_16x16x32_bf16 v[40:43], v[116:119], v[184:187], v[40:43]
	v_mfma_f32_16x16x32_bf16 v[36:39], v[100:103], v[200:203], v[36:39]
	v_mfma_f32_16x16x32_bf16 v[24:27], v[116:119], v[200:203], v[24:27]
	v_mfma_f32_16x16x32_bf16 v[12:15], v[100:103], v[208:211], v[12:15]
	v_mfma_f32_16x16x32_bf16 v[8:11], v[116:119], v[208:211], v[8:11]
	v_mfma_f32_16x16x32_bf16 v[48:51], v[144:147], v[160:163], v[48:51]
	v_mfma_f32_16x16x32_bf16 v[44:47], v[152:155], v[160:163], v[44:47]
	v_mfma_f32_16x16x32_bf16 v[32:35], v[144:147], v[168:171], v[32:35]
	v_mfma_f32_16x16x32_bf16 v[28:31], v[152:155], v[168:171], v[28:31]
	v_mfma_f32_16x16x32_bf16 v[20:23], v[144:147], v[188:191], v[20:23]
	v_mfma_f32_16x16x32_bf16 v[16:19], v[152:155], v[188:191], v[16:19]
	v_mfma_f32_16x16x32_bf16 v[4:7], v[144:147], v[204:207], v[4:7]
	v_mfma_f32_16x16x32_bf16 v[0:3], v[152:155], v[204:207], v[0:3]
	v_mfma_f32_16x16x32_bf16 v[48:51], v[148:151], v[164:167], v[48:51]
	v_mfma_f32_16x16x32_bf16 v[44:47], v[156:159], v[164:167], v[44:47]
	v_mfma_f32_16x16x32_bf16 v[32:35], v[148:151], v[184:187], v[32:35]
	v_mfma_f32_16x16x32_bf16 v[28:31], v[156:159], v[184:187], v[28:31]
	v_mfma_f32_16x16x32_bf16 v[20:23], v[148:151], v[200:203], v[20:23]
	v_mfma_f32_16x16x32_bf16 v[16:19], v[156:159], v[200:203], v[16:19]
	v_mfma_f32_16x16x32_bf16 v[4:7], v[148:151], v[208:211], v[4:7]
	v_mfma_f32_16x16x32_bf16 v[0:3], v[156:159], v[208:211], v[0:3]
	s_barrier
	s_setprio 0
	s_add_i32 s74, s74, 2
	s_add_u32 s72, s72, 0x100
	s_addc_u32 s73, s73, 0
	s_cmp_gt_u32 s74, 29
	s_mov_b64 s[36:37], s[40:41]
	s_cbranch_scc0 .LBB0_645
	s_and_b64 vcc, exec, s[22:23]
	s_cbranch_vccz .LBB0_648
	s_barrier

; #define PG8_STAGE(bufoff, gbase, voff) do { _Pragma("unroll") for (int _i = 0; _i < 2; ++_i) \
;         __builtin_amdgcn_global_load_lds((const unsigned*)((const char*)(gbase) + (voff)[_i]), (PG8_LAS unsigned*)(lds + (bufoff) + ldsw + _i * 8192), 16, 0, 0); } while (0)
; #define PG8_LDA(dst, b, h) do { _Pragma("unroll") for (int m = 0; m < 4; ++m) _Pragma("unroll") for (int k = 0; k < 2; ++k) dst[m][k] = *(const PG8_LAS bf16x8*)(lds + PG8_SA(b, h) + aoff + m * 2048 + k * 1024); } while (0)
; #define PG8_LDB(dst, b, h) do { _Pragma("unroll") for (int n = 0; n < 2; ++n) _Pragma("unroll") for (int k = 0; k < 2; ++k) dst[n][k] = *(const PG8_LAS bf16x8*)(lds + PG8_SB(b, h) + boff + n * 2048 + k * 1024); } while (0)
; #define PG8_WAIT_V(n) asm volatile("s_waitcnt vmcnt(" #n ")" ::: "memory")
; #define PG8_WAIT_L(n) asm volatile("s_waitcnt lgkmcnt(" #n ")" ::: "memory")
; #define PG8_BAR __builtin_amdgcn_s_barrier()
; #define PG8_SCHED __builtin_amdgcn_sched_barrier(0)
; template <class Epi, class Sched, bool ALIGN_EPI = false, bool SP2 = false>
; __device__ __forceinline__ void gemm_phase(PG8_LAS unsigned char* lds, const Gemm g, const Sched& S, const Epi& E) {
;     ...
;         const bool has_next = S.next(ui + 1, nxt);
;         const char* nA = has_next ? (const char*)g.A + (size_t)nxt.pm * tstep : cA; const char* nB = has_next ? (const char*)g.Bt + (size_t)nxt.pn * tstep : cB;
;         for (int t = 0; t < nt; t += 2) {
;             const bool last = (t == nt - 2);
;             const char* a1 = cA + (size_t)(t + 1) * kstep;
;             const char* a2 = last ? nA : cA + (size_t)(t + 2) * kstep; const char* b2 = last ? nB : cB + (size_t)(t + 2) * kstep;
;             const char* a3 = a2 + kstep; const char* b3 = b2 + kstep;
;             if (last && has_next) S.a_ready(nxt);
;             if constexpr (SP2) {
;             PG8_LDB(B0, 0, 0); PG8_LDB(B1, 0, 1); PG8_SCHED; PG8_LDA(At, 0, 0); PG8_STAGE(PG8_SA(1, 1), a1 + hstep, voffA);
;             PG8_WAIT_V(8); PG8_WAIT_L(0); PG8_BAR; PG8_MMA(0, 0, At, B0); PG8_MMA(0, 1, At, B1); PG8_BAR; PG8_SCHED;
;             PG8_LDA(At, 0, 1); PG8_STAGE(PG8_SB(0, 0), b2, voffB); PG8_STAGE(PG8_SB(0, 1), b2 + hstep, voffB); PG8_STAGE(PG8_SA(0, 0), a2, voffA);
;             PG8_WAIT_V(8); PG8_WAIT_L(0); PG8_BAR; PG8_MMA(1, 0, At, B0); PG8_MMA(1, 1, At, B1); PG8_BAR; PG8_SCHED;
.LBB0_774:
	s_ashr_i32 s23, s22, 31
	s_lshl_b64 s[24:25], s[22:23], 20
	s_add_u32 s24, s40, s24
	s_addc_u32 s25, s41, s25
	s_and_b64 s[26:27], s[38:39], exec
	s_cselect_b32 s23, s25, s31
	s_cselect_b32 s62, s24, s30
	s_ashr_i32 s21, s20, 31
	s_lshl_b64 s[26:27], s[20:21], 20
	s_add_u32 s26, s44, s26
	s_addc_u32 s27, s45, s27
	s_and_b64 s[36:37], s[38:39], exec
	s_cselect_b32 s21, s27, s35
	s_cselect_b32 s63, s26, s34
	s_add_u32 s30, s30, 0x80080
	s_addc_u32 s31, s31, 0
	s_add_u32 s64, s34, 0x100
	s_addc_u32 s65, s35, 0
	s_mov_b32 s66, -2
	ds_read_b128 v[152:155], v149
	ds_read_b128 v[156:159], v149 offset:1024
	ds_read_b128 v[160:163], v149 offset:2048
	ds_read_b128 v[164:167], v149 offset:3072
	ds_read_b128 v[168:171], v150
	ds_read_b128 v[172:175], v150 offset:1024
	ds_read_b128 v[176:179], v150 offset:2048
	ds_read_b128 v[180:183], v150 offset:3072
	s_add_u32 s34, s30, 0xfff80080
	s_addc_u32 s35, s31, -1
	s_cmp_eq_u32 s66, 28
	s_cselect_b32 s37, s23, s35
	s_cselect_b32 s36, s62, s34
	s_cselect_b32 s35, s21, s65
	s_cselect_b32 s34, s63, s64
	v_lshl_add_u64 v[144:145], s[30:31], 0, v[136:137]
	s_add_i32 m0, s50, 0xc000
	ds_read_b128 v[184:187], v151
	ds_read_b128 v[188:191], v151 offset:1024
	ds_read_b128 v[192:195], v151 offset:2048
	ds_read_b128 v[196:199], v151 offset:3072
	ds_read_b128 v[200:203], v151 offset:4096
	ds_read_b128 v[204:207], v151 offset:5120
	ds_read_b128 v[208:211], v151 offset:6144
	ds_read_b128 v[212:215], v151 offset:7168
	global_load_lds_dwordx4 v[144:145], off
	v_lshl_add_u64 v[144:145], s[30:31], 0, v[138:139]
	s_add_i32 m0, s50, 0xe000
	s_nop 0
	global_load_lds_dwordx4 v[144:145], off
	s_waitcnt vmcnt(8)
	s_waitcnt lgkmcnt(0)
	s_setprio 1
	s_barrier
	v_mfma_f32_16x16x32_bf16 v[124:127], v[152:155], v[184:187], 0
	v_mfma_f32_16x16x32_bf16 v[120:123], v[160:163], v[184:187], 0
	v_mfma_f32_16x16x32_bf16 v[108:111], v[152:155], v[192:195], 0
	v_mfma_f32_16x16x32_bf16 v[104:107], v[160:163], v[192:195], 0
	v_mfma_f32_16x16x32_bf16 v[92:95], v[152:155], v[200:203], 0
	v_mfma_f32_16x16x32_bf16 v[88:91], v[160:163], v[200:203], 0
	v_mfma_f32_16x16x32_bf16 v[76:79], v[152:155], v[208:211], 0
	v_mfma_f32_16x16x32_bf16 v[72:75], v[160:163], v[208:211], 0
	v_mfma_f32_16x16x32_bf16 v[124:127], v[156:159], v[188:191], v[124:127]
	v_mfma_f32_16x16x32_bf16 v[120:123], v[164:167], v[188:191], v[120:123]
	v_mfma_f32_16x16x32_bf16 v[108:111], v[156:159], v[196:199], v[108:111]
	v_mfma_f32_16x16x32_bf16 v[104:107], v[164:167], v[196:199], v[104:107]
	v_mfma_f32_16x16x32_bf16 v[92:95], v[156:159], v[204:207], v[92:95]
	v_mfma_f32_16x16x32_bf16 v[88:91], v[164:167], v[204:207], v[88:91]
	v_mfma_f32_16x16x32_bf16 v[76:79], v[156:159], v[212:215], v[76:79]
	v_mfma_f32_16x16x32_bf16 v[72:75], v[164:167], v[212:215], v[72:75]
	v_mfma_f32_16x16x32_bf16 v[116:119], v[168:171], v[184:187], 0
	v_mfma_f32_16x16x32_bf16 v[112:115], v[176:179], v[184:187], 0
	v_mfma_f32_16x16x32_bf16 v[100:103], v[168:171], v[192:195], 0
	v_mfma_f32_16x16x32_bf16 v[96:99], v[176:179], v[192:195], 0
	v_mfma_f32_16x16x32_bf16 v[84:87], v[168:171], v[200:203], 0
	v_mfma_f32_16x16x32_bf16 v[80:83], v[176:179], v[200:203], 0
	v_mfma_f32_16x16x32_bf16 v[68:71], v[168:171], v[208:211], 0
	v_mfma_f32_16x16x32_bf16 v[64:67], v[176:179], v[208:211], 0
	v_mfma_f32_16x16x32_bf16 v[116:119], v[172:175], v[188:191], v[116:119]
	v_mfma_f32_16x16x32_bf16 v[112:115], v[180:183], v[188:191], v[112:115]
	v_mfma_f32_16x16x32_bf16 v[100:103], v[172:175], v[196:199], v[100:103]
	v_mfma_f32_16x16x32_bf16 v[96:99], v[180:183], v[196:199], v[96:99]
	v_mfma_f32_16x16x32_bf16 v[84:87], v[172:175], v[204:207], v[84:87]
	v_mfma_f32_16x16x32_bf16 v[80:83], v[180:183], v[204:207], v[80:83]
	v_mfma_f32_16x16x32_bf16 v[68:71], v[172:175], v[212:215], v[68:71]
	v_mfma_f32_16x16x32_bf16 v[64:67], v[180:183], v[212:215], v[64:67]
	s_barrier
	s_setprio 0
	s_add_i32 s67, s60, s47
	v_lshl_add_u64 v[144:145], s[34:35], 0, v[132:133]
	s_mov_b32 m0, s67
	ds_read_b128 v[184:187], v151 offset:16384
	ds_read_b128 v[188:191], v151 offset:17408
	ds_read_b128 v[192:195], v151 offset:18432
	ds_read_b128 v[196:199], v151 offset:19456
	ds_read_b128 v[200:203], v151 offset:20480
	ds_read_b128 v[204:207], v151 offset:21504
	ds_read_b128 v[208:211], v151 offset:22528
	ds_read_b128 v[212:215], v151 offset:23552
	global_load_lds_dwordx4 v[144:145], off
	s_add_i32 m0, s67, 0x2000
	s_add_u32 s68, s34, 0x80000
	v_lshl_add_u64 v[218:219], s[34:35], 0, v[128:129]
	s_addc_u32 s69, s35, 0
	s_add_i32 s67, s61, s47
	global_load_lds_dwordx4 v[218:219], off
	v_lshl_add_u64 v[220:221], s[68:69], 0, v[132:133]
	s_mov_b32 m0, s67
	v_lshl_add_u64 v[222:223], s[36:37], 0, v[130:131]
	global_load_lds_dwordx4 v[220:221], off
	v_lshl_add_u64 v[220:221], s[68:69], 0, v[128:129]
	s_add_i32 m0, s67, 0x2000
	s_nop 0
	global_load_lds_dwordx4 v[220:221], off
	v_lshl_add_u64 v[220:221], s[36:37], 0, v[134:135]
	s_mov_b32 m0, s50
	s_nop 0
	global_load_lds_dwordx4 v[220:221], off
	s_mov_b32 m0, s51
	s_nop 0
	global_load_lds_dwordx4 v[222:223], off
	s_waitcnt vmcnt(8)
	s_waitcnt lgkmcnt(0)
	s_setprio 1
	s_barrier
; #define PG8_STAGE(bufoff, gbase, voff) do { _Pragma("unroll") for (int _i = 0; _i < 2; ++_i) \
;         __builtin_amdgcn_global_load_lds((const unsigned*)((const char*)(gbase) + (voff)[_i]), (PG8_LAS unsigned*)(lds + (bufoff) + ldsw + _i * 8192), 16, 0, 0); } while (0)
; #define PG8_LDA(dst, b, h) do { _Pragma("unroll") for (int m = 0; m < 4; ++m) _Pragma("unroll") for (int k = 0; k < 2; ++k) dst[m][k] = *(const PG8_LAS bf16x8*)(lds + PG8_SA(b, h) + aoff + m * 2048 + k * 1024); } while (0)
; #define PG8_LDB(dst, b, h) do { _Pragma("unroll") for (int n = 0; n < 2; ++n) _Pragma("unroll") for (int k = 0; k < 2; ++k) dst[n][k] = *(const PG8_LAS bf16x8*)(lds + PG8_SB(b, h) + boff + n * 2048 + k * 1024); } while (0)
; #define PG8_MMA(ai, bj, At, Bt) do { __builtin_amdgcn_s_setprio(1); _Pragma("unroll") for (int m = 0; m < 4; ++m) _Pragma("unroll") for (int n = 0; n < 2; ++n) _Pragma("unroll") for (int k = 0; k < 2; ++k) \
;         acc[ai][bj][m][n] = __builtin_amdgcn_mfma_f32_16x16x32_bf16(Bt[n][k], At[m][k], acc[ai][bj][m][n], 0, 0, 0); __builtin_amdgcn_s_setprio(0); } while (0)
; #define PG8_WAIT_V(n) asm volatile("s_waitcnt vmcnt(" #n ")" ::: "memory")
; #define PG8_WAIT_L(n) asm volatile("s_waitcnt lgkmcnt(" #n ")" ::: "memory")
; #define PG8_BAR __builtin_amdgcn_s_barrier()
; #define PG8_SCHED __builtin_amdgcn_sched_barrier(0)
; template <class Epi, class Sched, bool ALIGN_EPI = false, bool SP2 = false>
; __device__ __forceinline__ void gemm_phase(PG8_LAS unsigned char* lds, const Gemm g, const Sched& S, const Epi& E) {
;     ...
;             PG8_WAIT_V(8); PG8_WAIT_L(0); PG8_BAR; PG8_MMA(0, 0, At, B0); PG8_MMA(0, 1, At, B1); PG8_BAR; PG8_SCHED;
;             PG8_LDA(At, 0, 1); PG8_STAGE(PG8_SB(0, 0), b2, voffB); PG8_STAGE(PG8_SB(0, 1), b2 + hstep, voffB); PG8_STAGE(PG8_SA(0, 0), a2, voffA);
;             PG8_WAIT_V(8); PG8_WAIT_L(0); PG8_BAR; PG8_MMA(1, 0, At, B0); PG8_MMA(1, 1, At, B1); PG8_BAR; PG8_SCHED;
;             PG8_LDB(B0, 1, 0); PG8_LDB(B1, 1, 1); PG8_SCHED; PG8_LDA(At, 1, 0); PG8_STAGE(PG8_SA(0, 1), a2 + hstep, voffA);
;             PG8_WAIT_V(8); PG8_WAIT_L(0); PG8_BAR; PG8_MMA(0, 0, At, B0); PG8_MMA(0, 1, At, B1); PG8_BAR; PG8_SCHED;
	v_mfma_f32_16x16x32_bf16 v[60:63], v[152:155], v[184:187], 0
	v_mfma_f32_16x16x32_bf16 v[56:59], v[160:163], v[184:187], 0
	v_mfma_f32_16x16x32_bf16 v[44:47], v[152:155], v[192:195], 0
	v_mfma_f32_16x16x32_bf16 v[40:43], v[160:163], v[192:195], 0
	v_mfma_f32_16x16x32_bf16 v[28:31], v[152:155], v[200:203], 0
	v_mfma_f32_16x16x32_bf16 v[24:27], v[160:163], v[200:203], 0
	v_mfma_f32_16x16x32_bf16 v[12:15], v[152:155], v[208:211], 0
	v_mfma_f32_16x16x32_bf16 v[8:11], v[160:163], v[208:211], 0
	v_mfma_f32_16x16x32_bf16 v[60:63], v[156:159], v[188:191], v[60:63]
	v_mfma_f32_16x16x32_bf16 v[56:59], v[164:167], v[188:191], v[56:59]
	v_mfma_f32_16x16x32_bf16 v[44:47], v[156:159], v[196:199], v[44:47]
	v_mfma_f32_16x16x32_bf16 v[40:43], v[164:167], v[196:199], v[40:43]
	v_mfma_f32_16x16x32_bf16 v[28:31], v[156:159], v[204:207], v[28:31]
	v_mfma_f32_16x16x32_bf16 v[24:27], v[164:167], v[204:207], v[24:27]
	v_mfma_f32_16x16x32_bf16 v[12:15], v[156:159], v[212:215], v[12:15]
	v_mfma_f32_16x16x32_bf16 v[8:11], v[164:167], v[212:215], v[8:11]
	v_mfma_f32_16x16x32_bf16 v[52:55], v[168:171], v[184:187], 0
	v_mfma_f32_16x16x32_bf16 v[48:51], v[176:179], v[184:187], 0
	v_mfma_f32_16x16x32_bf16 v[36:39], v[168:171], v[192:195], 0
	v_mfma_f32_16x16x32_bf16 v[32:35], v[176:179], v[192:195], 0
	v_mfma_f32_16x16x32_bf16 v[20:23], v[168:171], v[200:203], 0
	v_mfma_f32_16x16x32_bf16 v[16:19], v[176:179], v[200:203], 0
	v_mfma_f32_16x16x32_bf16 v[4:7], v[168:171], v[208:211], 0
	v_mfma_f32_16x16x32_bf16 v[0:3], v[176:179], v[208:211], 0
	v_mfma_f32_16x16x32_bf16 v[52:55], v[172:175], v[188:191], v[52:55]
	v_mfma_f32_16x16x32_bf16 v[48:51], v[180:183], v[188:191], v[48:51]
	v_mfma_f32_16x16x32_bf16 v[36:39], v[172:175], v[196:199], v[36:39]
	v_mfma_f32_16x16x32_bf16 v[32:35], v[180:183], v[196:199], v[32:35]
	v_mfma_f32_16x16x32_bf16 v[20:23], v[172:175], v[204:207], v[20:23]
	v_mfma_f32_16x16x32_bf16 v[16:19], v[180:183], v[204:207], v[16:19]
	v_mfma_f32_16x16x32_bf16 v[4:7], v[172:175], v[212:215], v[4:7]
	v_mfma_f32_16x16x32_bf16 v[0:3], v[180:183], v[212:215], v[0:3]
	s_barrier
	s_setprio 0
	s_add_i32 s67, 0, 0x18000
	s_add_i32 s68, 0, 0x1c000
	v_add_u32_e32 v164, s67, v147
	v_add_u32_e32 v180, s68, v147
	ds_read_b128 v[152:155], v164
	ds_read_b128 v[156:159], v164 offset:1024
	ds_read_b128 v[160:163], v164 offset:2048
	ds_read_b128 v[164:167], v164 offset:3072
	ds_read_b128 v[168:171], v180
	ds_read_b128 v[172:175], v180 offset:1024
	ds_read_b128 v[176:179], v180 offset:2048
	ds_read_b128 v[180:183], v180 offset:3072
	s_add_u32 s36, s36, 0x80000
	s_addc_u32 s37, s37, 0
	s_mov_b32 m0, s52
	v_lshl_add_u64 v[224:225], s[36:37], 0, v[134:135]
	ds_read_b128 v[184:187], v151 offset:32768
	ds_read_b128 v[188:191], v151 offset:33792
	ds_read_b128 v[192:195], v151 offset:34816
	ds_read_b128 v[196:199], v151 offset:35840
	ds_read_b128 v[200:203], v151 offset:36864
	ds_read_b128 v[204:207], v151 offset:37888
	ds_read_b128 v[208:211], v151 offset:38912
	ds_read_b128 v[212:215], v151 offset:39936
	global_load_lds_dwordx4 v[224:225], off
	v_lshl_add_u64 v[224:225], s[36:37], 0, v[130:131]
	s_mov_b32 m0, s53
	s_nop 0
	global_load_lds_dwordx4 v[224:225], off
	s_waitcnt vmcnt(8)
	s_waitcnt lgkmcnt(0)
	s_setprio 1
	s_barrier
	v_mfma_f32_16x16x32_bf16 v[124:127], v[152:155], v[184:187], v[124:127]
	v_mfma_f32_16x16x32_bf16 v[120:123], v[160:163], v[184:187], v[120:123]
	v_mfma_f32_16x16x32_bf16 v[108:111], v[152:155], v[192:195], v[108:111]
	v_mfma_f32_16x16x32_bf16 v[104:107], v[160:163], v[192:195], v[104:107]
	v_mfma_f32_16x16x32_bf16 v[92:95], v[152:155], v[200:203], v[92:95]
	v_mfma_f32_16x16x32_bf16 v[88:91], v[160:163], v[200:203], v[88:91]
	v_mfma_f32_16x16x32_bf16 v[76:79], v[152:155], v[208:211], v[76:79]
	v_mfma_f32_16x16x32_bf16 v[72:75], v[160:163], v[208:211], v[72:75]
	v_mfma_f32_16x16x32_bf16 v[124:127], v[156:159], v[188:191], v[124:127]
	v_mfma_f32_16x16x32_bf16 v[120:123], v[164:167], v[188:191], v[120:123]
	v_mfma_f32_16x16x32_bf16 v[108:111], v[156:159], v[196:199], v[108:111]
	v_mfma_f32_16x16x32_bf16 v[104:107], v[164:167], v[196:199], v[104:107]
	v_mfma_f32_16x16x32_bf16 v[92:95], v[156:159], v[204:207], v[92:95]
	v_mfma_f32_16x16x32_bf16 v[88:91], v[164:167], v[204:207], v[88:91]
	v_mfma_f32_16x16x32_bf16 v[76:79], v[156:159], v[212:215], v[76:79]
	v_mfma_f32_16x16x32_bf16 v[72:75], v[164:167], v[212:215], v[72:75]
	v_mfma_f32_16x16x32_bf16 v[116:119], v[168:171], v[184:187], v[116:119]
	v_mfma_f32_16x16x32_bf16 v[112:115], v[176:179], v[184:187], v[112:115]
	v_mfma_f32_16x16x32_bf16 v[100:103], v[168:171], v[192:195], v[100:103]
	v_mfma_f32_16x16x32_bf16 v[96:99], v[176:179], v[192:195], v[96:99]
	v_mfma_f32_16x16x32_bf16 v[84:87], v[168:171], v[200:203], v[84:87]
	v_mfma_f32_16x16x32_bf16 v[80:83], v[176:179], v[200:203], v[80:83]
	v_mfma_f32_16x16x32_bf16 v[68:71], v[168:171], v[208:211], v[68:71]
	v_mfma_f32_16x16x32_bf16 v[64:67], v[176:179], v[208:211], v[64:67]
	v_mfma_f32_16x16x32_bf16 v[116:119], v[172:175], v[188:191], v[116:119]
	v_mfma_f32_16x16x32_bf16 v[112:115], v[180:183], v[188:191], v[112:115]
	v_mfma_f32_16x16x32_bf16 v[100:103], v[172:175], v[196:199], v[100:103]
	v_mfma_f32_16x16x32_bf16 v[96:99], v[180:183], v[196:199], v[96:99]
	v_mfma_f32_16x16x32_bf16 v[84:87], v[172:175], v[204:207], v[84:87]
	v_mfma_f32_16x16x32_bf16 v[80:83], v[180:183], v[204:207], v[80:83]
	v_mfma_f32_16x16x32_bf16 v[68:71], v[172:175], v[212:215], v[68:71]
	v_mfma_f32_16x16x32_bf16 v[64:67], v[180:183], v[212:215], v[64:67]
	s_barrier
; #define PG8_STAGE(bufoff, gbase, voff) do { _Pragma("unroll") for (int _i = 0; _i < 2; ++_i) \
;         __builtin_amdgcn_global_load_lds((const unsigned*)((const char*)(gbase) + (voff)[_i]), (PG8_LAS unsigned*)(lds + (bufoff) + ldsw + _i * 8192), 16, 0, 0); } while (0)
; #define PG8_LDA(dst, b, h) do { _Pragma("unroll") for (int m = 0; m < 4; ++m) _Pragma("unroll") for (int k = 0; k < 2; ++k) dst[m][k] = *(const PG8_LAS bf16x8*)(lds + PG8_SA(b, h) + aoff + m * 2048 + k * 1024); } while (0)
; #define PG8_LDB(dst, b, h) do { _Pragma("unroll") for (int n = 0; n < 2; ++n) _Pragma("unroll") for (int k = 0; k < 2; ++k) dst[n][k] = *(const PG8_LAS bf16x8*)(lds + PG8_SB(b, h) + boff + n * 2048 + k * 1024); } while (0)
; template <class Epi, class Sched, bool ALIGN_EPI = false, bool SP2 = false>
; __device__ __forceinline__ void gemm_phase(PG8_LAS unsigned char* lds, const Gemm g, const Sched& S, const Epi& E) {
;     ...
;         for (int t = 0; t < nt; t += 2) {
;             const bool last = (t == nt - 2);
;             const char* a1 = cA + (size_t)(t + 1) * kstep;
;             const char* a2 = last ? nA : cA + (size_t)(t + 2) * kstep; const char* b2 = last ? nB : cB + (size_t)(t + 2) * kstep;
;             const char* a3 = a2 + kstep; const char* b3 = b2 + kstep;
;             if (last && has_next) S.a_ready(nxt);
;             if constexpr (SP2) {
;             PG8_LDB(B0, 0, 0); PG8_LDB(B1, 0, 1); PG8_SCHED; PG8_LDA(At, 0, 0); PG8_STAGE(PG8_SA(1, 1), a1 + hstep, voffA);
;             PG8_WAIT_V(8); PG8_WAIT_L(0); PG8_BAR; PG8_MMA(0, 0, At, B0); PG8_MMA(0, 1, At, B1); PG8_BAR; PG8_SCHED;
;             PG8_LDA(At, 0, 1); PG8_STAGE(PG8_SB(0, 0), b2, voffB); PG8_STAGE(PG8_SB(0, 1), b2 + hstep, voffB); PG8_STAGE(PG8_SA(0, 0), a2, voffA);
;             PG8_WAIT_V(8); PG8_WAIT_L(0); PG8_BAR; PG8_MMA(1, 0, At, B0); PG8_MMA(1, 1, At, B1); PG8_BAR; PG8_SCHED;
;             PG8_LDB(B0, 1, 0); PG8_LDB(B1, 1, 1); PG8_SCHED; PG8_LDA(At, 1, 0); PG8_STAGE(PG8_SA(0, 1), a2 + hstep, voffA);
;             PG8_WAIT_V(8); PG8_WAIT_L(0); PG8_BAR; PG8_MMA(0, 0, At, B0); PG8_MMA(0, 1, At, B1); PG8_BAR; PG8_SCHED;
;             PG8_LDA(At, 1, 1); PG8_STAGE(PG8_SB(1, 0), b3, voffB); PG8_STAGE(PG8_SB(1, 1), b3 + hstep, voffB); PG8_STAGE(PG8_SA(1, 0), a3, voffA);
;             PG8_WAIT_V(8); PG8_WAIT_L(0); PG8_BAR; PG8_MMA(1, 0, At, B0); PG8_MMA(1, 1, At, B1); PG8_BAR; PG8_SCHED;
	s_setprio 0
	s_add_i32 s36, s67, s47
	v_lshl_add_u64 v[144:145], v[144:145], 0, s[16:17]
	s_mov_b32 m0, s36
	ds_read_b128 v[184:187], v151 offset:49152
	ds_read_b128 v[188:191], v151 offset:50176
	ds_read_b128 v[192:195], v151 offset:51200
	ds_read_b128 v[196:199], v151 offset:52224
	ds_read_b128 v[200:203], v151 offset:53248
	ds_read_b128 v[204:207], v151 offset:54272
	ds_read_b128 v[208:211], v151 offset:55296
	ds_read_b128 v[212:215], v151 offset:56320
	global_load_lds_dwordx4 v[144:145], off
	s_add_i32 m0, s36, 0x2000
	s_add_u32 s34, s34, 0x80080
	v_lshl_add_u64 v[144:145], v[218:219], 0, s[16:17]
	s_addc_u32 s35, s35, 0
	s_add_i32 s36, s68, s47
	global_load_lds_dwordx4 v[144:145], off
	v_lshl_add_u64 v[144:145], s[34:35], 0, v[132:133]
	s_mov_b32 m0, s36
	s_nop 0
	global_load_lds_dwordx4 v[144:145], off
	v_lshl_add_u64 v[144:145], s[34:35], 0, v[128:129]
	s_add_i32 m0, s36, 0x2000
	s_nop 0
	global_load_lds_dwordx4 v[144:145], off
	v_lshl_add_u64 v[144:145], v[220:221], 0, s[16:17]
	s_mov_b32 m0, s55
	s_nop 0
	global_load_lds_dwordx4 v[144:145], off
	v_lshl_add_u64 v[144:145], v[222:223], 0, s[16:17]
	s_mov_b32 m0, s59
	s_nop 0
	global_load_lds_dwordx4 v[144:145], off
	s_waitcnt vmcnt(8)
	s_waitcnt lgkmcnt(0)
	s_setprio 1
	s_barrier
	v_mfma_f32_16x16x32_bf16 v[60:63], v[152:155], v[184:187], v[60:63]
	v_mfma_f32_16x16x32_bf16 v[56:59], v[160:163], v[184:187], v[56:59]
	v_mfma_f32_16x16x32_bf16 v[44:47], v[152:155], v[192:195], v[44:47]
	v_mfma_f32_16x16x32_bf16 v[40:43], v[160:163], v[192:195], v[40:43]
	v_mfma_f32_16x16x32_bf16 v[28:31], v[152:155], v[200:203], v[28:31]
	v_mfma_f32_16x16x32_bf16 v[24:27], v[160:163], v[200:203], v[24:27]
	v_mfma_f32_16x16x32_bf16 v[12:15], v[152:155], v[208:211], v[12:15]
	v_mfma_f32_16x16x32_bf16 v[8:11], v[160:163], v[208:211], v[8:11]
	v_mfma_f32_16x16x32_bf16 v[60:63], v[156:159], v[188:191], v[60:63]
	v_mfma_f32_16x16x32_bf16 v[56:59], v[164:167], v[188:191], v[56:59]
	v_mfma_f32_16x16x32_bf16 v[44:47], v[156:159], v[196:199], v[44:47]
	v_mfma_f32_16x16x32_bf16 v[40:43], v[164:167], v[196:199], v[40:43]
	v_mfma_f32_16x16x32_bf16 v[28:31], v[156:159], v[204:207], v[28:31]
	v_mfma_f32_16x16x32_bf16 v[24:27], v[164:167], v[204:207], v[24:27]
	v_mfma_f32_16x16x32_bf16 v[12:15], v[156:159], v[212:215], v[12:15]
	v_mfma_f32_16x16x32_bf16 v[8:11], v[164:167], v[212:215], v[8:11]
	v_mfma_f32_16x16x32_bf16 v[52:55], v[168:171], v[184:187], v[52:55]
	v_mfma_f32_16x16x32_bf16 v[48:51], v[176:179], v[184:187], v[48:51]
	v_mfma_f32_16x16x32_bf16 v[36:39], v[168:171], v[192:195], v[36:39]
	v_mfma_f32_16x16x32_bf16 v[32:35], v[176:179], v[192:195], v[32:35]
	v_mfma_f32_16x16x32_bf16 v[20:23], v[168:171], v[200:203], v[20:23]
	v_mfma_f32_16x16x32_bf16 v[16:19], v[176:179], v[200:203], v[16:19]
	v_mfma_f32_16x16x32_bf16 v[4:7], v[168:171], v[208:211], v[4:7]
	v_mfma_f32_16x16x32_bf16 v[0:3], v[176:179], v[208:211], v[0:3]
	v_mfma_f32_16x16x32_bf16 v[52:55], v[172:175], v[188:191], v[52:55]
	v_mfma_f32_16x16x32_bf16 v[48:51], v[180:183], v[188:191], v[48:51]
	v_mfma_f32_16x16x32_bf16 v[36:39], v[172:175], v[196:199], v[36:39]
	v_mfma_f32_16x16x32_bf16 v[32:35], v[180:183], v[196:199], v[32:35]
	v_mfma_f32_16x16x32_bf16 v[20:23], v[172:175], v[204:207], v[20:23]
	v_mfma_f32_16x16x32_bf16 v[16:19], v[180:183], v[204:207], v[16:19]
	v_mfma_f32_16x16x32_bf16 v[4:7], v[172:175], v[212:215], v[4:7]
	v_mfma_f32_16x16x32_bf16 v[0:3], v[180:183], v[212:215], v[0:3]
	s_barrier
	s_setprio 0
	s_add_i32 s66, s66, 2
	s_add_u32 s30, s30, 0x100
	s_addc_u32 s31, s31, 0
	s_add_u32 s64, s64, 0x100
	s_addc_u32 s65, s65, 0
	s_cmp_gt_u32 s66, 29
.LBB0_775:
	ds_read_b128 v[152:155], v149
	ds_read_b128 v[156:159], v149 offset:1024
	ds_read_b128 v[160:163], v149 offset:2048
	ds_read_b128 v[164:167], v149 offset:3072
	ds_read_b128 v[168:171], v150
	ds_read_b128 v[172:175], v150 offset:1024
	ds_read_b128 v[176:179], v150 offset:2048
	ds_read_b128 v[180:183], v150 offset:3072
	s_add_u32 s34, s30, 0xfff80080
	s_addc_u32 s35, s31, -1
	s_cmp_eq_u32 s66, 28
	s_cselect_b32 s37, s23, s35
	s_cselect_b32 s36, s62, s34
	s_cselect_b32 s35, s21, s65
	s_cselect_b32 s34, s63, s64
	v_lshl_add_u64 v[144:145], s[30:31], 0, v[136:137]
	s_add_i32 m0, s50, 0xc000
	ds_read_b128 v[184:187], v151
	ds_read_b128 v[188:191], v151 offset:1024
	ds_read_b128 v[192:195], v151 offset:2048
	ds_read_b128 v[196:199], v151 offset:3072
	ds_read_b128 v[200:203], v151 offset:4096
	ds_read_b128 v[204:207], v151 offset:5120
	ds_read_b128 v[208:211], v151 offset:6144
	ds_read_b128 v[212:215], v151 offset:7168
	global_load_lds_dwordx4 v[144:145], off
	v_lshl_add_u64 v[144:145], s[30:31], 0, v[138:139]
	s_add_i32 m0, s50, 0xe000
	s_nop 0
	global_load_lds_dwordx4 v[144:145], off
	s_waitcnt vmcnt(8)
	s_waitcnt lgkmcnt(0)
	s_setprio 1
	s_barrier
; #define PG8_STAGE(bufoff, gbase, voff) do { _Pragma("unroll") for (int _i = 0; _i < 2; ++_i) \
;         __builtin_amdgcn_global_load_lds((const unsigned*)((const char*)(gbase) + (voff)[_i]), (PG8_LAS unsigned*)(lds + (bufoff) + ldsw + _i * 8192), 16, 0, 0); } while (0)
; #define PG8_LDA(dst, b, h) do { _Pragma("unroll") for (int m = 0; m < 4; ++m) _Pragma("unroll") for (int k = 0; k < 2; ++k) dst[m][k] = *(const PG8_LAS bf16x8*)(lds + PG8_SA(b, h) + aoff + m * 2048 + k * 1024); } while (0)
; #define PG8_MMA(ai, bj, At, Bt) do { __builtin_amdgcn_s_setprio(1); _Pragma("unroll") for (int m = 0; m < 4; ++m) _Pragma("unroll") for (int n = 0; n < 2; ++n) _Pragma("unroll") for (int k = 0; k < 2; ++k) \
;         acc[ai][bj][m][n] = __builtin_amdgcn_mfma_f32_16x16x32_bf16(Bt[n][k], At[m][k], acc[ai][bj][m][n], 0, 0, 0); __builtin_amdgcn_s_setprio(0); } while (0)
; #define PG8_WAIT_V(n) asm volatile("s_waitcnt vmcnt(" #n ")" ::: "memory")
; #define PG8_WAIT_L(n) asm volatile("s_waitcnt lgkmcnt(" #n ")" ::: "memory")
; #define PG8_BAR __builtin_amdgcn_s_barrier()
; #define PG8_SCHED __builtin_amdgcn_sched_barrier(0)
; template <class Epi, class Sched, bool ALIGN_EPI = false, bool SP2 = false>
; __device__ __forceinline__ void gemm_phase(PG8_LAS unsigned char* lds, const Gemm g, const Sched& S, const Epi& E) {
;     ...
;             PG8_WAIT_V(8); PG8_WAIT_L(0); PG8_BAR; PG8_MMA(0, 0, At, B0); PG8_MMA(0, 1, At, B1); PG8_BAR; PG8_SCHED;
;             PG8_LDA(At, 0, 1); PG8_STAGE(PG8_SB(0, 0), b2, voffB); PG8_STAGE(PG8_SB(0, 1), b2 + hstep, voffB); PG8_STAGE(PG8_SA(0, 0), a2, voffA);
;             PG8_WAIT_V(8); PG8_WAIT_L(0); PG8_BAR; PG8_MMA(1, 0, At, B0); PG8_MMA(1, 1, At, B1); PG8_BAR; PG8_SCHED;
	v_mfma_f32_16x16x32_bf16 v[124:127], v[152:155], v[184:187], v[124:127]
	v_mfma_f32_16x16x32_bf16 v[120:123], v[160:163], v[184:187], v[120:123]
	v_mfma_f32_16x16x32_bf16 v[108:111], v[152:155], v[192:195], v[108:111]
	v_mfma_f32_16x16x32_bf16 v[104:107], v[160:163], v[192:195], v[104:107]
	v_mfma_f32_16x16x32_bf16 v[92:95], v[152:155], v[200:203], v[92:95]
	v_mfma_f32_16x16x32_bf16 v[88:91], v[160:163], v[200:203], v[88:91]
	v_mfma_f32_16x16x32_bf16 v[76:79], v[152:155], v[208:211], v[76:79]
	v_mfma_f32_16x16x32_bf16 v[72:75], v[160:163], v[208:211], v[72:75]
	v_mfma_f32_16x16x32_bf16 v[124:127], v[156:159], v[188:191], v[124:127]
	v_mfma_f32_16x16x32_bf16 v[120:123], v[164:167], v[188:191], v[120:123]
	v_mfma_f32_16x16x32_bf16 v[108:111], v[156:159], v[196:199], v[108:111]
	v_mfma_f32_16x16x32_bf16 v[104:107], v[164:167], v[196:199], v[104:107]
	v_mfma_f32_16x16x32_bf16 v[92:95], v[156:159], v[204:207], v[92:95]
	v_mfma_f32_16x16x32_bf16 v[88:91], v[164:167], v[204:207], v[88:91]
	v_mfma_f32_16x16x32_bf16 v[76:79], v[156:159], v[212:215], v[76:79]
	v_mfma_f32_16x16x32_bf16 v[72:75], v[164:167], v[212:215], v[72:75]
	v_mfma_f32_16x16x32_bf16 v[116:119], v[168:171], v[184:187], v[116:119]
	v_mfma_f32_16x16x32_bf16 v[112:115], v[176:179], v[184:187], v[112:115]
	v_mfma_f32_16x16x32_bf16 v[100:103], v[168:171], v[192:195], v[100:103]
	v_mfma_f32_16x16x32_bf16 v[96:99], v[176:179], v[192:195], v[96:99]
	v_mfma_f32_16x16x32_bf16 v[84:87], v[168:171], v[200:203], v[84:87]
	v_mfma_f32_16x16x32_bf16 v[80:83], v[176:179], v[200:203], v[80:83]
	v_mfma_f32_16x16x32_bf16 v[68:71], v[168:171], v[208:211], v[68:71]
	v_mfma_f32_16x16x32_bf16 v[64:67], v[176:179], v[208:211], v[64:67]
	v_mfma_f32_16x16x32_bf16 v[116:119], v[172:175], v[188:191], v[116:119]
	v_mfma_f32_16x16x32_bf16 v[112:115], v[180:183], v[188:191], v[112:115]
	v_mfma_f32_16x16x32_bf16 v[100:103], v[172:175], v[196:199], v[100:103]
	v_mfma_f32_16x16x32_bf16 v[96:99], v[180:183], v[196:199], v[96:99]
	v_mfma_f32_16x16x32_bf16 v[84:87], v[172:175], v[204:207], v[84:87]
	v_mfma_f32_16x16x32_bf16 v[80:83], v[180:183], v[204:207], v[80:83]
	v_mfma_f32_16x16x32_bf16 v[68:71], v[172:175], v[212:215], v[68:71]
	v_mfma_f32_16x16x32_bf16 v[64:67], v[180:183], v[212:215], v[64:67]
	s_barrier
	s_setprio 0
	s_add_i32 s67, s60, s47
	v_lshl_add_u64 v[144:145], s[34:35], 0, v[132:133]
	s_mov_b32 m0, s67
	ds_read_b128 v[184:187], v151 offset:16384
	ds_read_b128 v[188:191], v151 offset:17408
	ds_read_b128 v[192:195], v151 offset:18432
	ds_read_b128 v[196:199], v151 offset:19456
	ds_read_b128 v[200:203], v151 offset:20480
	ds_read_b128 v[204:207], v151 offset:21504
	ds_read_b128 v[208:211], v151 offset:22528
	ds_read_b128 v[212:215], v151 offset:23552
	global_load_lds_dwordx4 v[144:145], off
	s_add_i32 m0, s67, 0x2000
	s_add_u32 s68, s34, 0x80000
	v_lshl_add_u64 v[218:219], s[34:35], 0, v[128:129]
	s_addc_u32 s69, s35, 0
	s_add_i32 s67, s61, s47
	global_load_lds_dwordx4 v[218:219], off
	v_lshl_add_u64 v[220:221], s[68:69], 0, v[132:133]
	s_mov_b32 m0, s67
	v_lshl_add_u64 v[222:223], s[36:37], 0, v[130:131]
	global_load_lds_dwordx4 v[220:221], off
	v_lshl_add_u64 v[220:221], s[68:69], 0, v[128:129]
	s_add_i32 m0, s67, 0x2000
	s_nop 0
	global_load_lds_dwordx4 v[220:221], off
	v_lshl_add_u64 v[220:221], s[36:37], 0, v[134:135]
	s_mov_b32 m0, s50
	s_nop 0
	global_load_lds_dwordx4 v[220:221], off
	s_mov_b32 m0, s51
	s_nop 0
	global_load_lds_dwordx4 v[222:223], off
	s_waitcnt vmcnt(8)
	s_waitcnt lgkmcnt(0)
	s_setprio 1
	s_barrier
	v_mfma_f32_16x16x32_bf16 v[60:63], v[152:155], v[184:187], v[60:63]
	v_mfma_f32_16x16x32_bf16 v[56:59], v[160:163], v[184:187], v[56:59]
	v_mfma_f32_16x16x32_bf16 v[44:47], v[152:155], v[192:195], v[44:47]
	v_mfma_f32_16x16x32_bf16 v[40:43], v[160:163], v[192:195], v[40:43]
	v_mfma_f32_16x16x32_bf16 v[28:31], v[152:155], v[200:203], v[28:31]
	v_mfma_f32_16x16x32_bf16 v[24:27], v[160:163], v[200:203], v[24:27]
	v_mfma_f32_16x16x32_bf16 v[12:15], v[152:155], v[208:211], v[12:15]
	v_mfma_f32_16x16x32_bf16 v[8:11], v[160:163], v[208:211], v[8:11]
	v_mfma_f32_16x16x32_bf16 v[60:63], v[156:159], v[188:191], v[60:63]
	v_mfma_f32_16x16x32_bf16 v[56:59], v[164:167], v[188:191], v[56:59]
	v_mfma_f32_16x16x32_bf16 v[44:47], v[156:159], v[196:199], v[44:47]
	v_mfma_f32_16x16x32_bf16 v[40:43], v[164:167], v[196:199], v[40:43]
	v_mfma_f32_16x16x32_bf16 v[28:31], v[156:159], v[204:207], v[28:31]
	v_mfma_f32_16x16x32_bf16 v[24:27], v[164:167], v[204:207], v[24:27]
	v_mfma_f32_16x16x32_bf16 v[12:15], v[156:159], v[212:215], v[12:15]
	v_mfma_f32_16x16x32_bf16 v[8:11], v[164:167], v[212:215], v[8:11]
	v_mfma_f32_16x16x32_bf16 v[52:55], v[168:171], v[184:187], v[52:55]
	v_mfma_f32_16x16x32_bf16 v[48:51], v[176:179], v[184:187], v[48:51]
	v_mfma_f32_16x16x32_bf16 v[36:39], v[168:171], v[192:195], v[36:39]
	v_mfma_f32_16x16x32_bf16 v[32:35], v[176:179], v[192:195], v[32:35]
	v_mfma_f32_16x16x32_bf16 v[20:23], v[168:171], v[200:203], v[20:23]
	v_mfma_f32_16x16x32_bf16 v[16:19], v[176:179], v[200:203], v[16:19]
	v_mfma_f32_16x16x32_bf16 v[4:7], v[168:171], v[208:211], v[4:7]
	v_mfma_f32_16x16x32_bf16 v[0:3], v[176:179], v[208:211], v[0:3]
	v_mfma_f32_16x16x32_bf16 v[52:55], v[172:175], v[188:191], v[52:55]
	v_mfma_f32_16x16x32_bf16 v[48:51], v[180:183], v[188:191], v[48:51]
	v_mfma_f32_16x16x32_bf16 v[36:39], v[172:175], v[196:199], v[36:39]
	v_mfma_f32_16x16x32_bf16 v[32:35], v[180:183], v[196:199], v[32:35]
	v_mfma_f32_16x16x32_bf16 v[20:23], v[172:175], v[204:207], v[20:23]
	v_mfma_f32_16x16x32_bf16 v[16:19], v[180:183], v[204:207], v[16:19]
	v_mfma_f32_16x16x32_bf16 v[4:7], v[172:175], v[212:215], v[4:7]
	v_mfma_f32_16x16x32_bf16 v[0:3], v[180:183], v[212:215], v[0:3]
	s_barrier
; #define PG8_STAGE(bufoff, gbase, voff) do { _Pragma("unroll") for (int _i = 0; _i < 2; ++_i) \
;         __builtin_amdgcn_global_load_lds((const unsigned*)((const char*)(gbase) + (voff)[_i]), (PG8_LAS unsigned*)(lds + (bufoff) + ldsw + _i * 8192), 16, 0, 0); } while (0)
; #define PG8_LDA(dst, b, h) do { _Pragma("unroll") for (int m = 0; m < 4; ++m) _Pragma("unroll") for (int k = 0; k < 2; ++k) dst[m][k] = *(const PG8_LAS bf16x8*)(lds + PG8_SA(b, h) + aoff + m * 2048 + k * 1024); } while (0)
; #define PG8_LDB(dst, b, h) do { _Pragma("unroll") for (int n = 0; n < 2; ++n) _Pragma("unroll") for (int k = 0; k < 2; ++k) dst[n][k] = *(const PG8_LAS bf16x8*)(lds + PG8_SB(b, h) + boff + n * 2048 + k * 1024); } while (0)
; #define PG8_MMA(ai, bj, At, Bt) do { __builtin_amdgcn_s_setprio(1); _Pragma("unroll") for (int m = 0; m < 4; ++m) _Pragma("unroll") for (int n = 0; n < 2; ++n) _Pragma("unroll") for (int k = 0; k < 2; ++k) \
;         acc[ai][bj][m][n] = __builtin_amdgcn_mfma_f32_16x16x32_bf16(Bt[n][k], At[m][k], acc[ai][bj][m][n], 0, 0, 0); __builtin_amdgcn_s_setprio(0); } while (0)
; #define PG8_WAIT_V(n) asm volatile("s_waitcnt vmcnt(" #n ")" ::: "memory")
; #define PG8_WAIT_L(n) asm volatile("s_waitcnt lgkmcnt(" #n ")" ::: "memory")
; #define PG8_BAR __builtin_amdgcn_s_barrier()
; #define PG8_SCHED __builtin_amdgcn_sched_barrier(0)
; template <class Epi, class Sched, bool ALIGN_EPI = false, bool SP2 = false>
; __device__ __forceinline__ void gemm_phase(PG8_LAS unsigned char* lds, const Gemm g, const Sched& S, const Epi& E) {
;     ...
;             PG8_WAIT_V(8); PG8_WAIT_L(0); PG8_BAR; PG8_MMA(1, 0, At, B0); PG8_MMA(1, 1, At, B1); PG8_BAR; PG8_SCHED;
;             PG8_LDB(B0, 1, 0); PG8_LDB(B1, 1, 1); PG8_SCHED; PG8_LDA(At, 1, 0); PG8_STAGE(PG8_SA(0, 1), a2 + hstep, voffA);
;             PG8_WAIT_V(8); PG8_WAIT_L(0); PG8_BAR; PG8_MMA(0, 0, At, B0); PG8_MMA(0, 1, At, B1); PG8_BAR; PG8_SCHED;
	s_setprio 0
	s_add_i32 s67, 0, 0x18000
	s_add_i32 s68, 0, 0x1c000
	v_add_u32_e32 v164, s67, v147
	v_add_u32_e32 v180, s68, v147
	ds_read_b128 v[152:155], v164
	ds_read_b128 v[156:159], v164 offset:1024
	ds_read_b128 v[160:163], v164 offset:2048
	ds_read_b128 v[164:167], v164 offset:3072
	ds_read_b128 v[168:171], v180
	ds_read_b128 v[172:175], v180 offset:1024
	ds_read_b128 v[176:179], v180 offset:2048
	ds_read_b128 v[180:183], v180 offset:3072
	s_add_u32 s36, s36, 0x80000
	s_addc_u32 s37, s37, 0
	s_mov_b32 m0, s52
	v_lshl_add_u64 v[224:225], s[36:37], 0, v[134:135]
	ds_read_b128 v[184:187], v151 offset:32768
	ds_read_b128 v[188:191], v151 offset:33792
	ds_read_b128 v[192:195], v151 offset:34816
	ds_read_b128 v[196:199], v151 offset:35840
	ds_read_b128 v[200:203], v151 offset:36864
	ds_read_b128 v[204:207], v151 offset:37888
	ds_read_b128 v[208:211], v151 offset:38912
	ds_read_b128 v[212:215], v151 offset:39936
	global_load_lds_dwordx4 v[224:225], off
	v_lshl_add_u64 v[224:225], s[36:37], 0, v[130:131]
	s_mov_b32 m0, s53
	s_nop 0
	global_load_lds_dwordx4 v[224:225], off
	s_waitcnt vmcnt(8)
	s_waitcnt lgkmcnt(0)
	s_setprio 1
	s_barrier
	v_mfma_f32_16x16x32_bf16 v[124:127], v[152:155], v[184:187], v[124:127]
	v_mfma_f32_16x16x32_bf16 v[120:123], v[160:163], v[184:187], v[120:123]
	v_mfma_f32_16x16x32_bf16 v[108:111], v[152:155], v[192:195], v[108:111]
	v_mfma_f32_16x16x32_bf16 v[104:107], v[160:163], v[192:195], v[104:107]
	v_mfma_f32_16x16x32_bf16 v[92:95], v[152:155], v[200:203], v[92:95]
	v_mfma_f32_16x16x32_bf16 v[88:91], v[160:163], v[200:203], v[88:91]
	v_mfma_f32_16x16x32_bf16 v[76:79], v[152:155], v[208:211], v[76:79]
	v_mfma_f32_16x16x32_bf16 v[72:75], v[160:163], v[208:211], v[72:75]
	v_mfma_f32_16x16x32_bf16 v[124:127], v[156:159], v[188:191], v[124:127]
	v_mfma_f32_16x16x32_bf16 v[120:123], v[164:167], v[188:191], v[120:123]
	v_mfma_f32_16x16x32_bf16 v[108:111], v[156:159], v[196:199], v[108:111]
	v_mfma_f32_16x16x32_bf16 v[104:107], v[164:167], v[196:199], v[104:107]
	v_mfma_f32_16x16x32_bf16 v[92:95], v[156:159], v[204:207], v[92:95]
	v_mfma_f32_16x16x32_bf16 v[88:91], v[164:167], v[204:207], v[88:91]
	v_mfma_f32_16x16x32_bf16 v[76:79], v[156:159], v[212:215], v[76:79]
	v_mfma_f32_16x16x32_bf16 v[72:75], v[164:167], v[212:215], v[72:75]
	v_mfma_f32_16x16x32_bf16 v[116:119], v[168:171], v[184:187], v[116:119]
	v_mfma_f32_16x16x32_bf16 v[112:115], v[176:179], v[184:187], v[112:115]
	v_mfma_f32_16x16x32_bf16 v[100:103], v[168:171], v[192:195], v[100:103]
	v_mfma_f32_16x16x32_bf16 v[96:99], v[176:179], v[192:195], v[96:99]
	v_mfma_f32_16x16x32_bf16 v[84:87], v[168:171], v[200:203], v[84:87]
	v_mfma_f32_16x16x32_bf16 v[80:83], v[176:179], v[200:203], v[80:83]
	v_mfma_f32_16x16x32_bf16 v[68:71], v[168:171], v[208:211], v[68:71]
	v_mfma_f32_16x16x32_bf16 v[64:67], v[176:179], v[208:211], v[64:67]
	v_mfma_f32_16x16x32_bf16 v[116:119], v[172:175], v[188:191], v[116:119]
	v_mfma_f32_16x16x32_bf16 v[112:115], v[180:183], v[188:191], v[112:115]
	v_mfma_f32_16x16x32_bf16 v[100:103], v[172:175], v[196:199], v[100:103]
	v_mfma_f32_16x16x32_bf16 v[96:99], v[180:183], v[196:199], v[96:99]
	v_mfma_f32_16x16x32_bf16 v[84:87], v[172:175], v[204:207], v[84:87]
	v_mfma_f32_16x16x32_bf16 v[80:83], v[180:183], v[204:207], v[80:83]
	v_mfma_f32_16x16x32_bf16 v[68:71], v[172:175], v[212:215], v[68:71]
	v_mfma_f32_16x16x32_bf16 v[64:67], v[180:183], v[212:215], v[64:67]
	s_barrier
; #define PG8_STAGE(bufoff, gbase, voff) do { _Pragma("unroll") for (int _i = 0; _i < 2; ++_i) \
;         __builtin_amdgcn_global_load_lds((const unsigned*)((const char*)(gbase) + (voff)[_i]), (PG8_LAS unsigned*)(lds + (bufoff) + ldsw + _i * 8192), 16, 0, 0); } while (0)
; #define PG8_WAIT_V(n) asm volatile("s_waitcnt vmcnt(" #n ")" ::: "memory")
; #define PG8_WAIT_L(n) asm volatile("s_waitcnt lgkmcnt(" #n ")" ::: "memory")
; template <class Epi, class Sched, bool ALIGN_EPI = false, bool SP2 = false>
; __device__ __forceinline__ void gemm_phase(PG8_LAS unsigned char* lds, const Gemm g, const Sched& S, const Epi& E) {
;     ...
;             PG8_WAIT_V(8); PG8_WAIT_L(0); PG8_BAR; PG8_MMA(0, 0, At, B0); PG8_MMA(0, 1, At, B1); PG8_BAR; PG8_SCHED;
;             PG8_LDA(At, 1, 1); PG8_STAGE(PG8_SB(1, 0), b3, voffB); PG8_STAGE(PG8_SB(1, 1), b3 + hstep, voffB); PG8_STAGE(PG8_SA(1, 0), a3, voffA);
;             PG8_WAIT_V(8); PG8_WAIT_L(0); PG8_BAR; PG8_MMA(1, 0, At, B0); PG8_MMA(1, 1, At, B1); PG8_BAR; PG8_SCHED;
;             } else {
;             PG8_LDB(B0, 0, 0); PG8_SCHED; PG8_LDA(At, 0, 0); PG8_STAGE(PG8_SA(1, 1), a1 + hstep, voffA);
;             PG8_WAIT_L(8); PG8_BAR; PG8_WAIT_L(0); PG8_MMA(0, 0, At, B0); PG8_BAR; PG8_SCHED;
;             PG8_LDB(B1, 0, 1); PG8_STAGE(PG8_SB(0, 0), b2, voffB);
;             PG8_BAR; PG8_WAIT_L(0); PG8_MMA(0, 1, At, B1); PG8_BAR;
;             PG8_LDA(At, 0, 1); PG8_STAGE(PG8_SA(0, 0), a2, voffA);
;             PG8_BAR; PG8_WAIT_L(0); PG8_MMA(1, 0, At, B0); PG8_BAR; PG8_SCHED;
;             PG8_STAGE(PG8_SB(0, 1), b2 + hstep, voffB);
;             PG8_WAIT_V(6); PG8_BAR; PG8_MMA(1, 1, At, B1); PG8_BAR;
;             PG8_LDB(B0, 1, 0); PG8_SCHED; PG8_LDA(At, 1, 0); PG8_STAGE(PG8_SA(0, 1), a2 + hstep, voffA);
;             PG8_WAIT_L(8); PG8_BAR; PG8_WAIT_L(0); PG8_MMA(0, 0, At, B0); PG8_BAR; PG8_SCHED;
;             PG8_LDB(B1, 1, 1); PG8_STAGE(PG8_SB(1, 0), b3, voffB);
;             PG8_BAR; PG8_WAIT_L(0); PG8_MMA(0, 1, At, B1); PG8_BAR;
;             PG8_LDA(At, 1, 1); PG8_STAGE(PG8_SA(1, 0), a3, voffA);
;             PG8_BAR; PG8_WAIT_L(0); PG8_MMA(1, 0, At, B0); PG8_BAR; PG8_SCHED;
;             PG8_STAGE(PG8_SB(1, 1), b3 + hstep, voffB);
;             PG8_WAIT_V(6); PG8_BAR; PG8_MMA(1, 1, At, B1); PG8_BAR;
;             }
;         }
;         if constexpr (ALIGN_EPI) { if (wr == 0) PG8_BAR; }
	s_setprio 0
	s_add_i32 s36, s67, s47
	v_lshl_add_u64 v[144:145], v[144:145], 0, s[16:17]
	s_mov_b32 m0, s36
	ds_read_b128 v[184:187], v151 offset:49152
	ds_read_b128 v[188:191], v151 offset:50176
	ds_read_b128 v[192:195], v151 offset:51200
	ds_read_b128 v[196:199], v151 offset:52224
	ds_read_b128 v[200:203], v151 offset:53248
	ds_read_b128 v[204:207], v151 offset:54272
	ds_read_b128 v[208:211], v151 offset:55296
	ds_read_b128 v[212:215], v151 offset:56320
	global_load_lds_dwordx4 v[144:145], off
	s_add_i32 m0, s36, 0x2000
	s_add_u32 s34, s34, 0x80080
	v_lshl_add_u64 v[144:145], v[218:219], 0, s[16:17]
	s_addc_u32 s35, s35, 0
	s_add_i32 s36, s68, s47
	global_load_lds_dwordx4 v[144:145], off
	v_lshl_add_u64 v[144:145], s[34:35], 0, v[132:133]
	s_mov_b32 m0, s36
	s_nop 0
	global_load_lds_dwordx4 v[144:145], off
	v_lshl_add_u64 v[144:145], s[34:35], 0, v[128:129]
	s_add_i32 m0, s36, 0x2000
	s_nop 0
	global_load_lds_dwordx4 v[144:145], off
	v_lshl_add_u64 v[144:145], v[220:221], 0, s[16:17]
	s_mov_b32 m0, s55
	s_nop 0
	global_load_lds_dwordx4 v[144:145], off
	v_lshl_add_u64 v[144:145], v[222:223], 0, s[16:17]
	s_mov_b32 m0, s59
	s_nop 0
	global_load_lds_dwordx4 v[144:145], off
	s_waitcnt vmcnt(8)
	s_waitcnt lgkmcnt(0)
	s_setprio 1
	s_barrier
	v_mfma_f32_16x16x32_bf16 v[60:63], v[152:155], v[184:187], v[60:63]
	v_mfma_f32_16x16x32_bf16 v[56:59], v[160:163], v[184:187], v[56:59]
	v_mfma_f32_16x16x32_bf16 v[44:47], v[152:155], v[192:195], v[44:47]
	v_mfma_f32_16x16x32_bf16 v[40:43], v[160:163], v[192:195], v[40:43]
	v_mfma_f32_16x16x32_bf16 v[28:31], v[152:155], v[200:203], v[28:31]
	v_mfma_f32_16x16x32_bf16 v[24:27], v[160:163], v[200:203], v[24:27]
	v_mfma_f32_16x16x32_bf16 v[12:15], v[152:155], v[208:211], v[12:15]
	v_mfma_f32_16x16x32_bf16 v[8:11], v[160:163], v[208:211], v[8:11]
	v_mfma_f32_16x16x32_bf16 v[60:63], v[156:159], v[188:191], v[60:63]
	v_mfma_f32_16x16x32_bf16 v[56:59], v[164:167], v[188:191], v[56:59]
	v_mfma_f32_16x16x32_bf16 v[44:47], v[156:159], v[196:199], v[44:47]
	v_mfma_f32_16x16x32_bf16 v[40:43], v[164:167], v[196:199], v[40:43]
	v_mfma_f32_16x16x32_bf16 v[28:31], v[156:159], v[204:207], v[28:31]
	v_mfma_f32_16x16x32_bf16 v[24:27], v[164:167], v[204:207], v[24:27]
	v_mfma_f32_16x16x32_bf16 v[12:15], v[156:159], v[212:215], v[12:15]
	v_mfma_f32_16x16x32_bf16 v[8:11], v[164:167], v[212:215], v[8:11]
	v_mfma_f32_16x16x32_bf16 v[52:55], v[168:171], v[184:187], v[52:55]
	v_mfma_f32_16x16x32_bf16 v[48:51], v[176:179], v[184:187], v[48:51]
	v_mfma_f32_16x16x32_bf16 v[36:39], v[168:171], v[192:195], v[36:39]
	v_mfma_f32_16x16x32_bf16 v[32:35], v[176:179], v[192:195], v[32:35]
	v_mfma_f32_16x16x32_bf16 v[20:23], v[168:171], v[200:203], v[20:23]
	v_mfma_f32_16x16x32_bf16 v[16:19], v[176:179], v[200:203], v[16:19]
	v_mfma_f32_16x16x32_bf16 v[4:7], v[168:171], v[208:211], v[4:7]
	v_mfma_f32_16x16x32_bf16 v[0:3], v[176:179], v[208:211], v[0:3]
	v_mfma_f32_16x16x32_bf16 v[52:55], v[172:175], v[188:191], v[52:55]
	v_mfma_f32_16x16x32_bf16 v[48:51], v[180:183], v[188:191], v[48:51]
	v_mfma_f32_16x16x32_bf16 v[36:39], v[172:175], v[196:199], v[36:39]
	v_mfma_f32_16x16x32_bf16 v[32:35], v[180:183], v[196:199], v[32:35]
	v_mfma_f32_16x16x32_bf16 v[20:23], v[172:175], v[204:207], v[20:23]
	v_mfma_f32_16x16x32_bf16 v[16:19], v[180:183], v[204:207], v[16:19]
	v_mfma_f32_16x16x32_bf16 v[4:7], v[172:175], v[212:215], v[4:7]
	v_mfma_f32_16x16x32_bf16 v[0:3], v[180:183], v[212:215], v[0:3]
	s_barrier
	s_setprio 0
	s_add_i32 s66, s66, 2
	s_add_u32 s30, s30, 0x100
	s_addc_u32 s31, s31, 0
	s_add_u32 s64, s64, 0x100
	s_addc_u32 s65, s65, 0
	s_cmp_gt_u32 s66, 29
	s_cbranch_scc0 .LBB0_775
	s_and_b64 vcc, exec, s[18:19]
	s_cbranch_vccz .LBB0_778
	s_barrier

; #define PG8_STAGE(bufoff, gbase, voff) do { _Pragma("unroll") for (int _i = 0; _i < 2; ++_i) \
;         __builtin_amdgcn_global_load_lds((const unsigned*)((const char*)(gbase) + (voff)[_i]), (PG8_LAS unsigned*)(lds + (bufoff) + ldsw + _i * 8192), 16, 0, 0); } while (0)
; #define PG8_LDA(dst, b, h) do { _Pragma("unroll") for (int m = 0; m < 4; ++m) _Pragma("unroll") for (int k = 0; k < 2; ++k) dst[m][k] = *(const PG8_LAS bf16x8*)(lds + PG8_SA(b, h) + aoff + m * 2048 + k * 1024); } while (0)
; #define PG8_LDB(dst, b, h) do { _Pragma("unroll") for (int n = 0; n < 2; ++n) _Pragma("unroll") for (int k = 0; k < 2; ++k) dst[n][k] = *(const PG8_LAS bf16x8*)(lds + PG8_SB(b, h) + boff + n * 2048 + k * 1024); } while (0)
; #define PG8_WAIT_V(n) asm volatile("s_waitcnt vmcnt(" #n ")" ::: "memory")
; #define PG8_WAIT_L(n) asm volatile("s_waitcnt lgkmcnt(" #n ")" ::: "memory")
; #define PG8_BAR __builtin_amdgcn_s_barrier()
; #define PG8_SCHED __builtin_amdgcn_sched_barrier(0)
; template <class Epi, class Sched, bool ALIGN_EPI = false, bool SP2 = false>
; __device__ __forceinline__ void gemm_phase(PG8_LAS unsigned char* lds, const Gemm g, const Sched& S, const Epi& E) {
;     ...
;         const bool has_next = S.next(ui + 1, nxt);
;         const char* nA = has_next ? (const char*)g.A + (size_t)nxt.pm * tstep : cA; const char* nB = has_next ? (const char*)g.Bt + (size_t)nxt.pn * tstep : cB;
;         for (int t = 0; t < nt; t += 2) {
;             const bool last = (t == nt - 2);
;             const char* a1 = cA + (size_t)(t + 1) * kstep;
;             const char* a2 = last ? nA : cA + (size_t)(t + 2) * kstep; const char* b2 = last ? nB : cB + (size_t)(t + 2) * kstep;
;             const char* a3 = a2 + kstep; const char* b3 = b2 + kstep;
;             if (last && has_next) S.a_ready(nxt);
;             if constexpr (SP2) {
;             PG8_LDB(B0, 0, 0); PG8_LDB(B1, 0, 1); PG8_SCHED; PG8_LDA(At, 0, 0); PG8_STAGE(PG8_SA(1, 1), a1 + hstep, voffA);
;             PG8_WAIT_V(8); PG8_WAIT_L(0); PG8_BAR; PG8_MMA(0, 0, At, B0); PG8_MMA(0, 1, At, B1); PG8_BAR; PG8_SCHED;
;             PG8_LDA(At, 0, 1); PG8_STAGE(PG8_SB(0, 0), b2, voffB); PG8_STAGE(PG8_SB(0, 1), b2 + hstep, voffB); PG8_STAGE(PG8_SA(0, 0), a2, voffA);
;             PG8_WAIT_V(8); PG8_WAIT_L(0); PG8_BAR; PG8_MMA(1, 0, At, B0); PG8_MMA(1, 1, At, B1); PG8_BAR; PG8_SCHED;
.LBB0_846:
	s_ashr_i32 s23, s22, 31
	s_lshl_b64 s[24:25], s[22:23], 22
	s_add_u32 s24, s40, s24
	s_addc_u32 s25, s41, s25
	s_and_b64 s[26:27], s[0:1], exec
	s_cselect_b32 s23, s25, s31
	s_cselect_b32 s57, s24, s30
	s_ashr_i32 s21, s20, 31
	s_lshl_b64 s[26:27], s[20:21], 22
	s_add_u32 s26, s44, s26
	s_addc_u32 s27, s45, s27
	s_and_b64 s[36:37], s[0:1], exec
	s_cselect_b32 s21, s27, s35
	s_cselect_b32 s58, s26, s34
	s_add_u32 s59, s34, 0x100
	s_addc_u32 s60, s35, 0
	s_mov_b32 s61, -2
	ds_read_b128 v[72:75], v165
	ds_read_b128 v[84:87], v165 offset:1024
	ds_read_b128 v[92:95], v165 offset:2048
	ds_read_b128 v[108:111], v165 offset:3072
	ds_read_b128 v[156:159], v166
	ds_read_b128 v[168:171], v166 offset:1024
	ds_read_b128 v[172:175], v166 offset:2048
	ds_read_b128 v[176:179], v166 offset:3072
	s_add_u32 s34, s30, 0x100
	s_addc_u32 s35, s31, 0
	s_cmpk_eq_i32 s61, 0x7c
	s_cselect_b32 s39, s23, s35
	s_cselect_b32 s38, s57, s34
	s_cselect_b32 s37, s21, s60
	s_cselect_b32 s36, s58, s59
	v_lshl_add_u64 v[160:161], s[30:31], 0, v[148:149]
	s_add_i32 m0, s42, 0xc000
	ds_read_b128 v[180:183], v167
	ds_read_b128 v[184:187], v167 offset:1024
	ds_read_b128 v[188:191], v167 offset:2048
	ds_read_b128 v[192:195], v167 offset:3072
	ds_read_b128 v[196:199], v167 offset:4096
	ds_read_b128 v[200:203], v167 offset:5120
	ds_read_b128 v[204:207], v167 offset:6144
	ds_read_b128 v[208:211], v167 offset:7168
	global_load_lds_dwordx4 v[160:161], off
	v_lshl_add_u64 v[160:161], s[30:31], 0, v[150:151]
	s_add_i32 m0, s42, 0xe000
	s_nop 0
	global_load_lds_dwordx4 v[160:161], off
	s_waitcnt vmcnt(8)
	s_waitcnt lgkmcnt(0)
	s_setprio 1
	s_barrier
	v_mfma_f32_16x16x32_bf16 v[140:143], v[72:75], v[180:183], 0
	v_mfma_f32_16x16x32_bf16 v[136:139], v[92:95], v[180:183], 0
	v_mfma_f32_16x16x32_bf16 v[132:135], v[72:75], v[188:191], 0
	v_mfma_f32_16x16x32_bf16 v[128:131], v[92:95], v[188:191], 0
	v_mfma_f32_16x16x32_bf16 v[120:123], v[72:75], v[196:199], 0
	v_mfma_f32_16x16x32_bf16 v[112:115], v[92:95], v[196:199], 0
	v_mfma_f32_16x16x32_bf16 v[100:103], v[72:75], v[204:207], 0
	v_mfma_f32_16x16x32_bf16 v[88:91], v[92:95], v[204:207], 0
	v_mfma_f32_16x16x32_bf16 v[140:143], v[84:87], v[184:187], v[140:143]
	v_mfma_f32_16x16x32_bf16 v[136:139], v[108:111], v[184:187], v[136:139]
	v_mfma_f32_16x16x32_bf16 v[132:135], v[84:87], v[192:195], v[132:135]
	v_mfma_f32_16x16x32_bf16 v[128:131], v[108:111], v[192:195], v[128:131]
	v_mfma_f32_16x16x32_bf16 v[120:123], v[84:87], v[200:203], v[120:123]
	v_mfma_f32_16x16x32_bf16 v[112:115], v[108:111], v[200:203], v[112:115]
	v_mfma_f32_16x16x32_bf16 v[100:103], v[84:87], v[208:211], v[100:103]
	v_mfma_f32_16x16x32_bf16 v[88:91], v[108:111], v[208:211], v[88:91]
	v_mfma_f32_16x16x32_bf16 v[124:127], v[156:159], v[180:183], 0
	v_mfma_f32_16x16x32_bf16 v[116:119], v[172:175], v[180:183], 0
	v_mfma_f32_16x16x32_bf16 v[104:107], v[156:159], v[188:191], 0
	v_mfma_f32_16x16x32_bf16 v[96:99], v[172:175], v[188:191], 0
	v_mfma_f32_16x16x32_bf16 v[80:83], v[156:159], v[196:199], 0
	v_mfma_f32_16x16x32_bf16 v[76:79], v[172:175], v[196:199], 0
	v_mfma_f32_16x16x32_bf16 v[68:71], v[156:159], v[204:207], 0
	v_mfma_f32_16x16x32_bf16 v[64:67], v[172:175], v[204:207], 0
	v_mfma_f32_16x16x32_bf16 v[124:127], v[168:171], v[184:187], v[124:127]
	v_mfma_f32_16x16x32_bf16 v[116:119], v[176:179], v[184:187], v[116:119]
	v_mfma_f32_16x16x32_bf16 v[104:107], v[168:171], v[192:195], v[104:107]
	v_mfma_f32_16x16x32_bf16 v[96:99], v[176:179], v[192:195], v[96:99]
	v_mfma_f32_16x16x32_bf16 v[80:83], v[168:171], v[200:203], v[80:83]
	v_mfma_f32_16x16x32_bf16 v[76:79], v[176:179], v[200:203], v[76:79]
	v_mfma_f32_16x16x32_bf16 v[68:71], v[168:171], v[208:211], v[68:71]
	v_mfma_f32_16x16x32_bf16 v[64:67], v[176:179], v[208:211], v[64:67]
	s_barrier
	s_setprio 0
	s_add_i32 s30, s55, s47
	v_lshl_add_u64 v[160:161], s[36:37], 0, v[146:147]
	s_mov_b32 m0, s30
	ds_read_b128 v[180:183], v167 offset:16384
	ds_read_b128 v[184:187], v167 offset:17408
	ds_read_b128 v[188:191], v167 offset:18432
	ds_read_b128 v[192:195], v167 offset:19456
	ds_read_b128 v[196:199], v167 offset:20480
	ds_read_b128 v[200:203], v167 offset:21504
	ds_read_b128 v[204:207], v167 offset:22528
	ds_read_b128 v[208:211], v167 offset:23552
	global_load_lds_dwordx4 v[160:161], off
	s_add_i32 m0, s30, 0x2000
	s_add_u32 s30, s36, 0x200000
	v_lshl_add_u64 v[212:213], s[36:37], 0, v[144:145]
	s_addc_u32 s31, s37, 0
	s_add_i32 s62, s56, s47
	global_load_lds_dwordx4 v[212:213], off
	v_lshl_add_u64 v[214:215], s[30:31], 0, v[146:147]
	s_mov_b32 m0, s62
	v_lshl_add_u64 v[216:217], s[38:39], 0, v[144:145]
	global_load_lds_dwordx4 v[214:215], off
	v_lshl_add_u64 v[214:215], s[30:31], 0, v[144:145]
	s_add_i32 m0, s62, 0x2000
	s_nop 0
	global_load_lds_dwordx4 v[214:215], off
	v_lshl_add_u64 v[214:215], s[38:39], 0, v[146:147]
	s_mov_b32 m0, s42
	s_nop 0
	global_load_lds_dwordx4 v[214:215], off
	s_mov_b32 m0, s43
	s_nop 0
	global_load_lds_dwordx4 v[216:217], off
	s_waitcnt vmcnt(8)
	s_waitcnt lgkmcnt(0)
	s_setprio 1
	s_barrier
; #define PG8_STAGE(bufoff, gbase, voff) do { _Pragma("unroll") for (int _i = 0; _i < 2; ++_i) \
;         __builtin_amdgcn_global_load_lds((const unsigned*)((const char*)(gbase) + (voff)[_i]), (PG8_LAS unsigned*)(lds + (bufoff) + ldsw + _i * 8192), 16, 0, 0); } while (0)
; #define PG8_LDA(dst, b, h) do { _Pragma("unroll") for (int m = 0; m < 4; ++m) _Pragma("unroll") for (int k = 0; k < 2; ++k) dst[m][k] = *(const PG8_LAS bf16x8*)(lds + PG8_SA(b, h) + aoff + m * 2048 + k * 1024); } while (0)
; #define PG8_LDB(dst, b, h) do { _Pragma("unroll") for (int n = 0; n < 2; ++n) _Pragma("unroll") for (int k = 0; k < 2; ++k) dst[n][k] = *(const PG8_LAS bf16x8*)(lds + PG8_SB(b, h) + boff + n * 2048 + k * 1024); } while (0)
; #define PG8_MMA(ai, bj, At, Bt) do { __builtin_amdgcn_s_setprio(1); _Pragma("unroll") for (int m = 0; m < 4; ++m) _Pragma("unroll") for (int n = 0; n < 2; ++n) _Pragma("unroll") for (int k = 0; k < 2; ++k) \
;         acc[ai][bj][m][n] = __builtin_amdgcn_mfma_f32_16x16x32_bf16(Bt[n][k], At[m][k], acc[ai][bj][m][n], 0, 0, 0); __builtin_amdgcn_s_setprio(0); } while (0)
; #define PG8_WAIT_V(n) asm volatile("s_waitcnt vmcnt(" #n ")" ::: "memory")
; #define PG8_WAIT_L(n) asm volatile("s_waitcnt lgkmcnt(" #n ")" ::: "memory")
; #define PG8_BAR __builtin_amdgcn_s_barrier()
; #define PG8_SCHED __builtin_amdgcn_sched_barrier(0)
; template <class Epi, class Sched, bool ALIGN_EPI = false, bool SP2 = false>
; __device__ __forceinline__ void gemm_phase(PG8_LAS unsigned char* lds, const Gemm g, const Sched& S, const Epi& E) {
;     ...
;             PG8_WAIT_V(8); PG8_WAIT_L(0); PG8_BAR; PG8_MMA(0, 0, At, B0); PG8_MMA(0, 1, At, B1); PG8_BAR; PG8_SCHED;
;             PG8_LDA(At, 0, 1); PG8_STAGE(PG8_SB(0, 0), b2, voffB); PG8_STAGE(PG8_SB(0, 1), b2 + hstep, voffB); PG8_STAGE(PG8_SA(0, 0), a2, voffA);
;             PG8_WAIT_V(8); PG8_WAIT_L(0); PG8_BAR; PG8_MMA(1, 0, At, B0); PG8_MMA(1, 1, At, B1); PG8_BAR; PG8_SCHED;
;             PG8_LDB(B0, 1, 0); PG8_LDB(B1, 1, 1); PG8_SCHED; PG8_LDA(At, 1, 0); PG8_STAGE(PG8_SA(0, 1), a2 + hstep, voffA);
;             PG8_WAIT_V(8); PG8_WAIT_L(0); PG8_BAR; PG8_MMA(0, 0, At, B0); PG8_MMA(0, 1, At, B1); PG8_BAR; PG8_SCHED;
	v_mfma_f32_16x16x32_bf16 v[60:63], v[72:75], v[180:183], 0
	v_mfma_f32_16x16x32_bf16 v[56:59], v[92:95], v[180:183], 0
	v_mfma_f32_16x16x32_bf16 v[52:55], v[72:75], v[188:191], 0
	v_mfma_f32_16x16x32_bf16 v[44:47], v[92:95], v[188:191], 0
	v_mfma_f32_16x16x32_bf16 v[36:39], v[72:75], v[196:199], 0
	v_mfma_f32_16x16x32_bf16 v[28:31], v[92:95], v[196:199], 0
	v_mfma_f32_16x16x32_bf16 v[20:23], v[72:75], v[204:207], 0
	v_mfma_f32_16x16x32_bf16 v[12:15], v[92:95], v[204:207], 0
	v_mfma_f32_16x16x32_bf16 v[60:63], v[84:87], v[184:187], v[60:63]
	v_mfma_f32_16x16x32_bf16 v[56:59], v[108:111], v[184:187], v[56:59]
	v_mfma_f32_16x16x32_bf16 v[52:55], v[84:87], v[192:195], v[52:55]
	v_mfma_f32_16x16x32_bf16 v[44:47], v[108:111], v[192:195], v[44:47]
	v_mfma_f32_16x16x32_bf16 v[36:39], v[84:87], v[200:203], v[36:39]
	v_mfma_f32_16x16x32_bf16 v[28:31], v[108:111], v[200:203], v[28:31]
	v_mfma_f32_16x16x32_bf16 v[20:23], v[84:87], v[208:211], v[20:23]
	v_mfma_f32_16x16x32_bf16 v[12:15], v[108:111], v[208:211], v[12:15]
	v_mfma_f32_16x16x32_bf16 v[48:51], v[156:159], v[180:183], 0
	v_mfma_f32_16x16x32_bf16 v[40:43], v[172:175], v[180:183], 0
	v_mfma_f32_16x16x32_bf16 v[32:35], v[156:159], v[188:191], 0
	v_mfma_f32_16x16x32_bf16 v[24:27], v[172:175], v[188:191], 0
	v_mfma_f32_16x16x32_bf16 v[16:19], v[156:159], v[196:199], 0
	v_mfma_f32_16x16x32_bf16 v[8:11], v[172:175], v[196:199], 0
	v_mfma_f32_16x16x32_bf16 v[4:7], v[156:159], v[204:207], 0
	v_mfma_f32_16x16x32_bf16 v[0:3], v[172:175], v[204:207], 0
	v_mfma_f32_16x16x32_bf16 v[48:51], v[168:171], v[184:187], v[48:51]
	v_mfma_f32_16x16x32_bf16 v[40:43], v[176:179], v[184:187], v[40:43]
	v_mfma_f32_16x16x32_bf16 v[32:35], v[168:171], v[192:195], v[32:35]
	v_mfma_f32_16x16x32_bf16 v[24:27], v[176:179], v[192:195], v[24:27]
	v_mfma_f32_16x16x32_bf16 v[16:19], v[168:171], v[200:203], v[16:19]
	v_mfma_f32_16x16x32_bf16 v[8:11], v[176:179], v[200:203], v[8:11]
	v_mfma_f32_16x16x32_bf16 v[4:7], v[168:171], v[208:211], v[4:7]
	v_mfma_f32_16x16x32_bf16 v[0:3], v[176:179], v[208:211], v[0:3]
	s_barrier
	s_setprio 0
	s_add_i32 s62, 0, 0x18000
	s_add_i32 s63, 0, 0x1c000
	v_add_u32_e32 v108, s62, v163
	v_add_u32_e32 v176, s63, v163
	ds_read_b128 v[72:75], v108
	ds_read_b128 v[84:87], v108 offset:1024
	ds_read_b128 v[92:95], v108 offset:2048
	ds_read_b128 v[108:111], v108 offset:3072
	ds_read_b128 v[156:159], v176
	ds_read_b128 v[168:171], v176 offset:1024
	ds_read_b128 v[172:175], v176 offset:2048
	ds_read_b128 v[176:179], v176 offset:3072
	s_add_u32 s30, s38, 0x200000
	s_addc_u32 s31, s39, 0
	s_mov_b32 m0, s48
	v_lshl_add_u64 v[218:219], s[30:31], 0, v[146:147]
	ds_read_b128 v[180:183], v167 offset:32768
	ds_read_b128 v[184:187], v167 offset:33792
	ds_read_b128 v[188:191], v167 offset:34816
	ds_read_b128 v[192:195], v167 offset:35840
	ds_read_b128 v[196:199], v167 offset:36864
	ds_read_b128 v[200:203], v167 offset:37888
	ds_read_b128 v[204:207], v167 offset:38912
	ds_read_b128 v[208:211], v167 offset:39936
	global_load_lds_dwordx4 v[218:219], off
	v_lshl_add_u64 v[218:219], s[30:31], 0, v[144:145]
	s_mov_b32 m0, s49
	s_nop 0
	global_load_lds_dwordx4 v[218:219], off
	s_waitcnt vmcnt(8)
	s_waitcnt lgkmcnt(0)
	s_setprio 1
	s_barrier
	v_mfma_f32_16x16x32_bf16 v[140:143], v[72:75], v[180:183], v[140:143]
	v_mfma_f32_16x16x32_bf16 v[136:139], v[92:95], v[180:183], v[136:139]
	v_mfma_f32_16x16x32_bf16 v[132:135], v[72:75], v[188:191], v[132:135]
	v_mfma_f32_16x16x32_bf16 v[128:131], v[92:95], v[188:191], v[128:131]
	v_mfma_f32_16x16x32_bf16 v[120:123], v[72:75], v[196:199], v[120:123]
	v_mfma_f32_16x16x32_bf16 v[112:115], v[92:95], v[196:199], v[112:115]
	v_mfma_f32_16x16x32_bf16 v[100:103], v[72:75], v[204:207], v[100:103]
	v_mfma_f32_16x16x32_bf16 v[88:91], v[92:95], v[204:207], v[88:91]
	v_mfma_f32_16x16x32_bf16 v[140:143], v[84:87], v[184:187], v[140:143]
	v_mfma_f32_16x16x32_bf16 v[136:139], v[108:111], v[184:187], v[136:139]
	v_mfma_f32_16x16x32_bf16 v[132:135], v[84:87], v[192:195], v[132:135]
	v_mfma_f32_16x16x32_bf16 v[128:131], v[108:111], v[192:195], v[128:131]
	v_mfma_f32_16x16x32_bf16 v[120:123], v[84:87], v[200:203], v[120:123]
	v_mfma_f32_16x16x32_bf16 v[112:115], v[108:111], v[200:203], v[112:115]
	v_mfma_f32_16x16x32_bf16 v[100:103], v[84:87], v[208:211], v[100:103]
	v_mfma_f32_16x16x32_bf16 v[88:91], v[108:111], v[208:211], v[88:91]
	v_mfma_f32_16x16x32_bf16 v[124:127], v[156:159], v[180:183], v[124:127]
	v_mfma_f32_16x16x32_bf16 v[116:119], v[172:175], v[180:183], v[116:119]
	v_mfma_f32_16x16x32_bf16 v[104:107], v[156:159], v[188:191], v[104:107]
	v_mfma_f32_16x16x32_bf16 v[96:99], v[172:175], v[188:191], v[96:99]
	v_mfma_f32_16x16x32_bf16 v[80:83], v[156:159], v[196:199], v[80:83]
	v_mfma_f32_16x16x32_bf16 v[76:79], v[172:175], v[196:199], v[76:79]
	v_mfma_f32_16x16x32_bf16 v[68:71], v[156:159], v[204:207], v[68:71]
	v_mfma_f32_16x16x32_bf16 v[64:67], v[172:175], v[204:207], v[64:67]
	v_mfma_f32_16x16x32_bf16 v[124:127], v[168:171], v[184:187], v[124:127]
	v_mfma_f32_16x16x32_bf16 v[116:119], v[176:179], v[184:187], v[116:119]
	v_mfma_f32_16x16x32_bf16 v[104:107], v[168:171], v[192:195], v[104:107]
	v_mfma_f32_16x16x32_bf16 v[96:99], v[176:179], v[192:195], v[96:99]
	v_mfma_f32_16x16x32_bf16 v[80:83], v[168:171], v[200:203], v[80:83]
	v_mfma_f32_16x16x32_bf16 v[76:79], v[176:179], v[200:203], v[76:79]
	v_mfma_f32_16x16x32_bf16 v[68:71], v[168:171], v[208:211], v[68:71]
	v_mfma_f32_16x16x32_bf16 v[64:67], v[176:179], v[208:211], v[64:67]
	s_barrier
; #define PG8_STAGE(bufoff, gbase, voff) do { _Pragma("unroll") for (int _i = 0; _i < 2; ++_i) \
;         __builtin_amdgcn_global_load_lds((const unsigned*)((const char*)(gbase) + (voff)[_i]), (PG8_LAS unsigned*)(lds + (bufoff) + ldsw + _i * 8192), 16, 0, 0); } while (0)
; #define PG8_LDA(dst, b, h) do { _Pragma("unroll") for (int m = 0; m < 4; ++m) _Pragma("unroll") for (int k = 0; k < 2; ++k) dst[m][k] = *(const PG8_LAS bf16x8*)(lds + PG8_SA(b, h) + aoff + m * 2048 + k * 1024); } while (0)
; #define PG8_LDB(dst, b, h) do { _Pragma("unroll") for (int n = 0; n < 2; ++n) _Pragma("unroll") for (int k = 0; k < 2; ++k) dst[n][k] = *(const PG8_LAS bf16x8*)(lds + PG8_SB(b, h) + boff + n * 2048 + k * 1024); } while (0)
; template <class Epi, class Sched, bool ALIGN_EPI = false, bool SP2 = false>
; __device__ __forceinline__ void gemm_phase(PG8_LAS unsigned char* lds, const Gemm g, const Sched& S, const Epi& E) {
;     ...
;         for (int t = 0; t < nt; t += 2) {
;             const bool last = (t == nt - 2);
;             const char* a1 = cA + (size_t)(t + 1) * kstep;
;             const char* a2 = last ? nA : cA + (size_t)(t + 2) * kstep; const char* b2 = last ? nB : cB + (size_t)(t + 2) * kstep;
;             const char* a3 = a2 + kstep; const char* b3 = b2 + kstep;
;             if (last && has_next) S.a_ready(nxt);
;             if constexpr (SP2) {
;             PG8_LDB(B0, 0, 0); PG8_LDB(B1, 0, 1); PG8_SCHED; PG8_LDA(At, 0, 0); PG8_STAGE(PG8_SA(1, 1), a1 + hstep, voffA);
;             PG8_WAIT_V(8); PG8_WAIT_L(0); PG8_BAR; PG8_MMA(0, 0, At, B0); PG8_MMA(0, 1, At, B1); PG8_BAR; PG8_SCHED;
;             PG8_LDA(At, 0, 1); PG8_STAGE(PG8_SB(0, 0), b2, voffB); PG8_STAGE(PG8_SB(0, 1), b2 + hstep, voffB); PG8_STAGE(PG8_SA(0, 0), a2, voffA);
;             PG8_WAIT_V(8); PG8_WAIT_L(0); PG8_BAR; PG8_MMA(1, 0, At, B0); PG8_MMA(1, 1, At, B1); PG8_BAR; PG8_SCHED;
;             PG8_LDB(B0, 1, 0); PG8_LDB(B1, 1, 1); PG8_SCHED; PG8_LDA(At, 1, 0); PG8_STAGE(PG8_SA(0, 1), a2 + hstep, voffA);
;             PG8_WAIT_V(8); PG8_WAIT_L(0); PG8_BAR; PG8_MMA(0, 0, At, B0); PG8_MMA(0, 1, At, B1); PG8_BAR; PG8_SCHED;
;             PG8_LDA(At, 1, 1); PG8_STAGE(PG8_SB(1, 0), b3, voffB); PG8_STAGE(PG8_SB(1, 1), b3 + hstep, voffB); PG8_STAGE(PG8_SA(1, 0), a3, voffA);
;             PG8_WAIT_V(8); PG8_WAIT_L(0); PG8_BAR; PG8_MMA(1, 0, At, B0); PG8_MMA(1, 1, At, B1); PG8_BAR; PG8_SCHED;
	s_setprio 0
	s_add_i32 s30, s62, s47
	v_lshl_add_u64 v[160:161], v[160:161], 0, s[8:9]
	s_mov_b32 m0, s30
	ds_read_b128 v[180:183], v167 offset:49152
	ds_read_b128 v[184:187], v167 offset:50176
	ds_read_b128 v[188:191], v167 offset:51200
	ds_read_b128 v[192:195], v167 offset:52224
	ds_read_b128 v[196:199], v167 offset:53248
	ds_read_b128 v[200:203], v167 offset:54272
	ds_read_b128 v[204:207], v167 offset:55296
	ds_read_b128 v[208:211], v167 offset:56320
	global_load_lds_dwordx4 v[160:161], off
	s_add_i32 m0, s30, 0x2000
	s_add_u32 s30, s36, 0x200080
	v_lshl_add_u64 v[160:161], v[212:213], 0, s[8:9]
	s_addc_u32 s31, s37, 0
	s_add_i32 s36, s63, s47
	global_load_lds_dwordx4 v[160:161], off
	v_lshl_add_u64 v[160:161], s[30:31], 0, v[146:147]
	s_mov_b32 m0, s36
	s_nop 0
	global_load_lds_dwordx4 v[160:161], off
	v_lshl_add_u64 v[160:161], s[30:31], 0, v[144:145]
	s_add_i32 m0, s36, 0x2000
	s_nop 0
	global_load_lds_dwordx4 v[160:161], off
	v_lshl_add_u64 v[160:161], v[214:215], 0, s[8:9]
	s_mov_b32 m0, s53
	s_nop 0
	global_load_lds_dwordx4 v[160:161], off
	v_lshl_add_u64 v[160:161], v[216:217], 0, s[8:9]
	s_mov_b32 m0, s54
	s_nop 0
	global_load_lds_dwordx4 v[160:161], off
	s_waitcnt vmcnt(8)
	s_waitcnt lgkmcnt(0)
	s_setprio 1
	s_barrier
	v_mfma_f32_16x16x32_bf16 v[60:63], v[72:75], v[180:183], v[60:63]
	v_mfma_f32_16x16x32_bf16 v[56:59], v[92:95], v[180:183], v[56:59]
	v_mfma_f32_16x16x32_bf16 v[52:55], v[72:75], v[188:191], v[52:55]
	v_mfma_f32_16x16x32_bf16 v[44:47], v[92:95], v[188:191], v[44:47]
	v_mfma_f32_16x16x32_bf16 v[36:39], v[72:75], v[196:199], v[36:39]
	v_mfma_f32_16x16x32_bf16 v[28:31], v[92:95], v[196:199], v[28:31]
	v_mfma_f32_16x16x32_bf16 v[20:23], v[72:75], v[204:207], v[20:23]
	v_mfma_f32_16x16x32_bf16 v[12:15], v[92:95], v[204:207], v[12:15]
	v_mfma_f32_16x16x32_bf16 v[60:63], v[84:87], v[184:187], v[60:63]
	v_mfma_f32_16x16x32_bf16 v[56:59], v[108:111], v[184:187], v[56:59]
	v_mfma_f32_16x16x32_bf16 v[52:55], v[84:87], v[192:195], v[52:55]
	v_mfma_f32_16x16x32_bf16 v[44:47], v[108:111], v[192:195], v[44:47]
	v_mfma_f32_16x16x32_bf16 v[36:39], v[84:87], v[200:203], v[36:39]
	v_mfma_f32_16x16x32_bf16 v[28:31], v[108:111], v[200:203], v[28:31]
	v_mfma_f32_16x16x32_bf16 v[20:23], v[84:87], v[208:211], v[20:23]
	v_mfma_f32_16x16x32_bf16 v[12:15], v[108:111], v[208:211], v[12:15]
	v_mfma_f32_16x16x32_bf16 v[48:51], v[156:159], v[180:183], v[48:51]
	v_mfma_f32_16x16x32_bf16 v[40:43], v[172:175], v[180:183], v[40:43]
	v_mfma_f32_16x16x32_bf16 v[32:35], v[156:159], v[188:191], v[32:35]
	v_mfma_f32_16x16x32_bf16 v[24:27], v[172:175], v[188:191], v[24:27]
	v_mfma_f32_16x16x32_bf16 v[16:19], v[156:159], v[196:199], v[16:19]
	v_mfma_f32_16x16x32_bf16 v[8:11], v[172:175], v[196:199], v[8:11]
	v_mfma_f32_16x16x32_bf16 v[4:7], v[156:159], v[204:207], v[4:7]
	v_mfma_f32_16x16x32_bf16 v[0:3], v[172:175], v[204:207], v[0:3]
	v_mfma_f32_16x16x32_bf16 v[48:51], v[168:171], v[184:187], v[48:51]
	v_mfma_f32_16x16x32_bf16 v[40:43], v[176:179], v[184:187], v[40:43]
	v_mfma_f32_16x16x32_bf16 v[32:35], v[168:171], v[192:195], v[32:35]
	v_mfma_f32_16x16x32_bf16 v[24:27], v[176:179], v[192:195], v[24:27]
	v_mfma_f32_16x16x32_bf16 v[16:19], v[168:171], v[200:203], v[16:19]
	v_mfma_f32_16x16x32_bf16 v[8:11], v[176:179], v[200:203], v[8:11]
	v_mfma_f32_16x16x32_bf16 v[4:7], v[168:171], v[208:211], v[4:7]
	v_mfma_f32_16x16x32_bf16 v[0:3], v[176:179], v[208:211], v[0:3]
	s_barrier
	s_setprio 0
	s_add_i32 s61, s61, 2
	s_add_u32 s59, s59, 0x100
	s_addc_u32 s60, s60, 0
	s_cmpk_gt_u32 s61, 0x7d
	s_mov_b64 s[30:31], s[34:35]
.LBB0_847:
	ds_read_b128 v[72:75], v165
	ds_read_b128 v[84:87], v165 offset:1024
	ds_read_b128 v[92:95], v165 offset:2048
	ds_read_b128 v[108:111], v165 offset:3072
	ds_read_b128 v[156:159], v166
	ds_read_b128 v[168:171], v166 offset:1024
	ds_read_b128 v[172:175], v166 offset:2048
	ds_read_b128 v[176:179], v166 offset:3072
	s_add_u32 s34, s30, 0x100
	s_addc_u32 s35, s31, 0
	s_cmpk_eq_i32 s61, 0x7c
	s_cselect_b32 s39, s23, s35
	s_cselect_b32 s38, s57, s34
	s_cselect_b32 s37, s21, s60
	s_cselect_b32 s36, s58, s59
	v_lshl_add_u64 v[160:161], s[30:31], 0, v[148:149]
	s_add_i32 m0, s42, 0xc000
	ds_read_b128 v[180:183], v167
	ds_read_b128 v[184:187], v167 offset:1024
	ds_read_b128 v[188:191], v167 offset:2048
	ds_read_b128 v[192:195], v167 offset:3072
	ds_read_b128 v[196:199], v167 offset:4096
	ds_read_b128 v[200:203], v167 offset:5120
	ds_read_b128 v[204:207], v167 offset:6144
	ds_read_b128 v[208:211], v167 offset:7168
	global_load_lds_dwordx4 v[160:161], off
	v_lshl_add_u64 v[160:161], s[30:31], 0, v[150:151]
	s_add_i32 m0, s42, 0xe000
	s_nop 0
	global_load_lds_dwordx4 v[160:161], off
	s_waitcnt vmcnt(8)
	s_waitcnt lgkmcnt(0)
	s_setprio 1
	s_barrier
; #define PG8_STAGE(bufoff, gbase, voff) do { _Pragma("unroll") for (int _i = 0; _i < 2; ++_i) \
;         __builtin_amdgcn_global_load_lds((const unsigned*)((const char*)(gbase) + (voff)[_i]), (PG8_LAS unsigned*)(lds + (bufoff) + ldsw + _i * 8192), 16, 0, 0); } while (0)
; #define PG8_LDA(dst, b, h) do { _Pragma("unroll") for (int m = 0; m < 4; ++m) _Pragma("unroll") for (int k = 0; k < 2; ++k) dst[m][k] = *(const PG8_LAS bf16x8*)(lds + PG8_SA(b, h) + aoff + m * 2048 + k * 1024); } while (0)
; #define PG8_MMA(ai, bj, At, Bt) do { __builtin_amdgcn_s_setprio(1); _Pragma("unroll") for (int m = 0; m < 4; ++m) _Pragma("unroll") for (int n = 0; n < 2; ++n) _Pragma("unroll") for (int k = 0; k < 2; ++k) \
;         acc[ai][bj][m][n] = __builtin_amdgcn_mfma_f32_16x16x32_bf16(Bt[n][k], At[m][k], acc[ai][bj][m][n], 0, 0, 0); __builtin_amdgcn_s_setprio(0); } while (0)
; #define PG8_WAIT_V(n) asm volatile("s_waitcnt vmcnt(" #n ")" ::: "memory")
; #define PG8_WAIT_L(n) asm volatile("s_waitcnt lgkmcnt(" #n ")" ::: "memory")
; #define PG8_BAR __builtin_amdgcn_s_barrier()
; #define PG8_SCHED __builtin_amdgcn_sched_barrier(0)
; template <class Epi, class Sched, bool ALIGN_EPI = false, bool SP2 = false>
; __device__ __forceinline__ void gemm_phase(PG8_LAS unsigned char* lds, const Gemm g, const Sched& S, const Epi& E) {
;     ...
;             PG8_WAIT_V(8); PG8_WAIT_L(0); PG8_BAR; PG8_MMA(0, 0, At, B0); PG8_MMA(0, 1, At, B1); PG8_BAR; PG8_SCHED;
;             PG8_LDA(At, 0, 1); PG8_STAGE(PG8_SB(0, 0), b2, voffB); PG8_STAGE(PG8_SB(0, 1), b2 + hstep, voffB); PG8_STAGE(PG8_SA(0, 0), a2, voffA);
;             PG8_WAIT_V(8); PG8_WAIT_L(0); PG8_BAR; PG8_MMA(1, 0, At, B0); PG8_MMA(1, 1, At, B1); PG8_BAR; PG8_SCHED;
	v_mfma_f32_16x16x32_bf16 v[140:143], v[72:75], v[180:183], v[140:143]
	v_mfma_f32_16x16x32_bf16 v[136:139], v[92:95], v[180:183], v[136:139]
	v_mfma_f32_16x16x32_bf16 v[132:135], v[72:75], v[188:191], v[132:135]
	v_mfma_f32_16x16x32_bf16 v[128:131], v[92:95], v[188:191], v[128:131]
	v_mfma_f32_16x16x32_bf16 v[120:123], v[72:75], v[196:199], v[120:123]
	v_mfma_f32_16x16x32_bf16 v[112:115], v[92:95], v[196:199], v[112:115]
	v_mfma_f32_16x16x32_bf16 v[100:103], v[72:75], v[204:207], v[100:103]
	v_mfma_f32_16x16x32_bf16 v[88:91], v[92:95], v[204:207], v[88:91]
	v_mfma_f32_16x16x32_bf16 v[140:143], v[84:87], v[184:187], v[140:143]
	v_mfma_f32_16x16x32_bf16 v[136:139], v[108:111], v[184:187], v[136:139]
	v_mfma_f32_16x16x32_bf16 v[132:135], v[84:87], v[192:195], v[132:135]
	v_mfma_f32_16x16x32_bf16 v[128:131], v[108:111], v[192:195], v[128:131]
	v_mfma_f32_16x16x32_bf16 v[120:123], v[84:87], v[200:203], v[120:123]
	v_mfma_f32_16x16x32_bf16 v[112:115], v[108:111], v[200:203], v[112:115]
	v_mfma_f32_16x16x32_bf16 v[100:103], v[84:87], v[208:211], v[100:103]
	v_mfma_f32_16x16x32_bf16 v[88:91], v[108:111], v[208:211], v[88:91]
	v_mfma_f32_16x16x32_bf16 v[124:127], v[156:159], v[180:183], v[124:127]
	v_mfma_f32_16x16x32_bf16 v[116:119], v[172:175], v[180:183], v[116:119]
	v_mfma_f32_16x16x32_bf16 v[104:107], v[156:159], v[188:191], v[104:107]
	v_mfma_f32_16x16x32_bf16 v[96:99], v[172:175], v[188:191], v[96:99]
	v_mfma_f32_16x16x32_bf16 v[80:83], v[156:159], v[196:199], v[80:83]
	v_mfma_f32_16x16x32_bf16 v[76:79], v[172:175], v[196:199], v[76:79]
	v_mfma_f32_16x16x32_bf16 v[68:71], v[156:159], v[204:207], v[68:71]
	v_mfma_f32_16x16x32_bf16 v[64:67], v[172:175], v[204:207], v[64:67]
	v_mfma_f32_16x16x32_bf16 v[124:127], v[168:171], v[184:187], v[124:127]
	v_mfma_f32_16x16x32_bf16 v[116:119], v[176:179], v[184:187], v[116:119]
	v_mfma_f32_16x16x32_bf16 v[104:107], v[168:171], v[192:195], v[104:107]
	v_mfma_f32_16x16x32_bf16 v[96:99], v[176:179], v[192:195], v[96:99]
	v_mfma_f32_16x16x32_bf16 v[80:83], v[168:171], v[200:203], v[80:83]
	v_mfma_f32_16x16x32_bf16 v[76:79], v[176:179], v[200:203], v[76:79]
	v_mfma_f32_16x16x32_bf16 v[68:71], v[168:171], v[208:211], v[68:71]
	v_mfma_f32_16x16x32_bf16 v[64:67], v[176:179], v[208:211], v[64:67]
	s_barrier
	s_setprio 0
	s_add_i32 s30, s55, s47
	v_lshl_add_u64 v[160:161], s[36:37], 0, v[146:147]
	s_mov_b32 m0, s30
	ds_read_b128 v[180:183], v167 offset:16384
	ds_read_b128 v[184:187], v167 offset:17408
	ds_read_b128 v[188:191], v167 offset:18432
	ds_read_b128 v[192:195], v167 offset:19456
	ds_read_b128 v[196:199], v167 offset:20480
	ds_read_b128 v[200:203], v167 offset:21504
	ds_read_b128 v[204:207], v167 offset:22528
	ds_read_b128 v[208:211], v167 offset:23552
	global_load_lds_dwordx4 v[160:161], off
	s_add_i32 m0, s30, 0x2000
	s_add_u32 s30, s36, 0x200000
	v_lshl_add_u64 v[212:213], s[36:37], 0, v[144:145]
	s_addc_u32 s31, s37, 0
	s_add_i32 s62, s56, s47
	global_load_lds_dwordx4 v[212:213], off
	v_lshl_add_u64 v[214:215], s[30:31], 0, v[146:147]
	s_mov_b32 m0, s62
	v_lshl_add_u64 v[216:217], s[38:39], 0, v[144:145]
	global_load_lds_dwordx4 v[214:215], off
	v_lshl_add_u64 v[214:215], s[30:31], 0, v[144:145]
	s_add_i32 m0, s62, 0x2000
	s_nop 0
	global_load_lds_dwordx4 v[214:215], off
	v_lshl_add_u64 v[214:215], s[38:39], 0, v[146:147]
	s_mov_b32 m0, s42
	s_nop 0
	global_load_lds_dwordx4 v[214:215], off
	s_mov_b32 m0, s43
	s_nop 0
	global_load_lds_dwordx4 v[216:217], off
	s_waitcnt vmcnt(8)
	s_waitcnt lgkmcnt(0)
	s_setprio 1
	s_barrier
	v_mfma_f32_16x16x32_bf16 v[60:63], v[72:75], v[180:183], v[60:63]
	v_mfma_f32_16x16x32_bf16 v[56:59], v[92:95], v[180:183], v[56:59]
	v_mfma_f32_16x16x32_bf16 v[52:55], v[72:75], v[188:191], v[52:55]
	v_mfma_f32_16x16x32_bf16 v[44:47], v[92:95], v[188:191], v[44:47]
	v_mfma_f32_16x16x32_bf16 v[36:39], v[72:75], v[196:199], v[36:39]
	v_mfma_f32_16x16x32_bf16 v[28:31], v[92:95], v[196:199], v[28:31]
	v_mfma_f32_16x16x32_bf16 v[20:23], v[72:75], v[204:207], v[20:23]
	v_mfma_f32_16x16x32_bf16 v[12:15], v[92:95], v[204:207], v[12:15]
	v_mfma_f32_16x16x32_bf16 v[60:63], v[84:87], v[184:187], v[60:63]
	v_mfma_f32_16x16x32_bf16 v[56:59], v[108:111], v[184:187], v[56:59]
	v_mfma_f32_16x16x32_bf16 v[52:55], v[84:87], v[192:195], v[52:55]
	v_mfma_f32_16x16x32_bf16 v[44:47], v[108:111], v[192:195], v[44:47]
	v_mfma_f32_16x16x32_bf16 v[36:39], v[84:87], v[200:203], v[36:39]
	v_mfma_f32_16x16x32_bf16 v[28:31], v[108:111], v[200:203], v[28:31]
	v_mfma_f32_16x16x32_bf16 v[20:23], v[84:87], v[208:211], v[20:23]
	v_mfma_f32_16x16x32_bf16 v[12:15], v[108:111], v[208:211], v[12:15]
	v_mfma_f32_16x16x32_bf16 v[48:51], v[156:159], v[180:183], v[48:51]
	v_mfma_f32_16x16x32_bf16 v[40:43], v[172:175], v[180:183], v[40:43]
	v_mfma_f32_16x16x32_bf16 v[32:35], v[156:159], v[188:191], v[32:35]
	v_mfma_f32_16x16x32_bf16 v[24:27], v[172:175], v[188:191], v[24:27]
	v_mfma_f32_16x16x32_bf16 v[16:19], v[156:159], v[196:199], v[16:19]
	v_mfma_f32_16x16x32_bf16 v[8:11], v[172:175], v[196:199], v[8:11]
	v_mfma_f32_16x16x32_bf16 v[4:7], v[156:159], v[204:207], v[4:7]
	v_mfma_f32_16x16x32_bf16 v[0:3], v[172:175], v[204:207], v[0:3]
	v_mfma_f32_16x16x32_bf16 v[48:51], v[168:171], v[184:187], v[48:51]
	v_mfma_f32_16x16x32_bf16 v[40:43], v[176:179], v[184:187], v[40:43]
	v_mfma_f32_16x16x32_bf16 v[32:35], v[168:171], v[192:195], v[32:35]
	v_mfma_f32_16x16x32_bf16 v[24:27], v[176:179], v[192:195], v[24:27]
	v_mfma_f32_16x16x32_bf16 v[16:19], v[168:171], v[200:203], v[16:19]
	v_mfma_f32_16x16x32_bf16 v[8:11], v[176:179], v[200:203], v[8:11]
	v_mfma_f32_16x16x32_bf16 v[4:7], v[168:171], v[208:211], v[4:7]
	v_mfma_f32_16x16x32_bf16 v[0:3], v[176:179], v[208:211], v[0:3]
	s_barrier
; #define PG8_STAGE(bufoff, gbase, voff) do { _Pragma("unroll") for (int _i = 0; _i < 2; ++_i) \
;         __builtin_amdgcn_global_load_lds((const unsigned*)((const char*)(gbase) + (voff)[_i]), (PG8_LAS unsigned*)(lds + (bufoff) + ldsw + _i * 8192), 16, 0, 0); } while (0)
; #define PG8_LDA(dst, b, h) do { _Pragma("unroll") for (int m = 0; m < 4; ++m) _Pragma("unroll") for (int k = 0; k < 2; ++k) dst[m][k] = *(const PG8_LAS bf16x8*)(lds + PG8_SA(b, h) + aoff + m * 2048 + k * 1024); } while (0)
; #define PG8_LDB(dst, b, h) do { _Pragma("unroll") for (int n = 0; n < 2; ++n) _Pragma("unroll") for (int k = 0; k < 2; ++k) dst[n][k] = *(const PG8_LAS bf16x8*)(lds + PG8_SB(b, h) + boff + n * 2048 + k * 1024); } while (0)
; #define PG8_MMA(ai, bj, At, Bt) do { __builtin_amdgcn_s_setprio(1); _Pragma("unroll") for (int m = 0; m < 4; ++m) _Pragma("unroll") for (int n = 0; n < 2; ++n) _Pragma("unroll") for (int k = 0; k < 2; ++k) \
;         acc[ai][bj][m][n] = __builtin_amdgcn_mfma_f32_16x16x32_bf16(Bt[n][k], At[m][k], acc[ai][bj][m][n], 0, 0, 0); __builtin_amdgcn_s_setprio(0); } while (0)
; #define PG8_WAIT_V(n) asm volatile("s_waitcnt vmcnt(" #n ")" ::: "memory")
; #define PG8_WAIT_L(n) asm volatile("s_waitcnt lgkmcnt(" #n ")" ::: "memory")
; #define PG8_BAR __builtin_amdgcn_s_barrier()
; #define PG8_SCHED __builtin_amdgcn_sched_barrier(0)
; template <class Epi, class Sched, bool ALIGN_EPI = false, bool SP2 = false>
; __device__ __forceinline__ void gemm_phase(PG8_LAS unsigned char* lds, const Gemm g, const Sched& S, const Epi& E) {
;     ...
;             PG8_WAIT_V(8); PG8_WAIT_L(0); PG8_BAR; PG8_MMA(1, 0, At, B0); PG8_MMA(1, 1, At, B1); PG8_BAR; PG8_SCHED;
;             PG8_LDB(B0, 1, 0); PG8_LDB(B1, 1, 1); PG8_SCHED; PG8_LDA(At, 1, 0); PG8_STAGE(PG8_SA(0, 1), a2 + hstep, voffA);
;             PG8_WAIT_V(8); PG8_WAIT_L(0); PG8_BAR; PG8_MMA(0, 0, At, B0); PG8_MMA(0, 1, At, B1); PG8_BAR; PG8_SCHED;
	s_setprio 0
	s_add_i32 s62, 0, 0x18000
	s_add_i32 s63, 0, 0x1c000
	v_add_u32_e32 v108, s62, v163
	v_add_u32_e32 v176, s63, v163
	ds_read_b128 v[72:75], v108
	ds_read_b128 v[84:87], v108 offset:1024
	ds_read_b128 v[92:95], v108 offset:2048
	ds_read_b128 v[108:111], v108 offset:3072
	ds_read_b128 v[156:159], v176
	ds_read_b128 v[168:171], v176 offset:1024
	ds_read_b128 v[172:175], v176 offset:2048
	ds_read_b128 v[176:179], v176 offset:3072
	s_add_u32 s30, s38, 0x200000
	s_addc_u32 s31, s39, 0
	s_mov_b32 m0, s48
	v_lshl_add_u64 v[218:219], s[30:31], 0, v[146:147]
	ds_read_b128 v[180:183], v167 offset:32768
	ds_read_b128 v[184:187], v167 offset:33792
	ds_read_b128 v[188:191], v167 offset:34816
	ds_read_b128 v[192:195], v167 offset:35840
	ds_read_b128 v[196:199], v167 offset:36864
	ds_read_b128 v[200:203], v167 offset:37888
	ds_read_b128 v[204:207], v167 offset:38912
	ds_read_b128 v[208:211], v167 offset:39936
	global_load_lds_dwordx4 v[218:219], off
	v_lshl_add_u64 v[218:219], s[30:31], 0, v[144:145]
	s_mov_b32 m0, s49
	s_nop 0
	global_load_lds_dwordx4 v[218:219], off
	s_waitcnt vmcnt(8)
	s_waitcnt lgkmcnt(0)
	s_setprio 1
	s_barrier
	v_mfma_f32_16x16x32_bf16 v[140:143], v[72:75], v[180:183], v[140:143]
	v_mfma_f32_16x16x32_bf16 v[136:139], v[92:95], v[180:183], v[136:139]
	v_mfma_f32_16x16x32_bf16 v[132:135], v[72:75], v[188:191], v[132:135]
	v_mfma_f32_16x16x32_bf16 v[128:131], v[92:95], v[188:191], v[128:131]
	v_mfma_f32_16x16x32_bf16 v[120:123], v[72:75], v[196:199], v[120:123]
	v_mfma_f32_16x16x32_bf16 v[112:115], v[92:95], v[196:199], v[112:115]
	v_mfma_f32_16x16x32_bf16 v[100:103], v[72:75], v[204:207], v[100:103]
	v_mfma_f32_16x16x32_bf16 v[88:91], v[92:95], v[204:207], v[88:91]
	v_mfma_f32_16x16x32_bf16 v[140:143], v[84:87], v[184:187], v[140:143]
	v_mfma_f32_16x16x32_bf16 v[136:139], v[108:111], v[184:187], v[136:139]
	v_mfma_f32_16x16x32_bf16 v[132:135], v[84:87], v[192:195], v[132:135]
	v_mfma_f32_16x16x32_bf16 v[128:131], v[108:111], v[192:195], v[128:131]
	v_mfma_f32_16x16x32_bf16 v[120:123], v[84:87], v[200:203], v[120:123]
	v_mfma_f32_16x16x32_bf16 v[112:115], v[108:111], v[200:203], v[112:115]
	v_mfma_f32_16x16x32_bf16 v[100:103], v[84:87], v[208:211], v[100:103]
	v_mfma_f32_16x16x32_bf16 v[88:91], v[108:111], v[208:211], v[88:91]
	v_mfma_f32_16x16x32_bf16 v[124:127], v[156:159], v[180:183], v[124:127]
	v_mfma_f32_16x16x32_bf16 v[116:119], v[172:175], v[180:183], v[116:119]
	v_mfma_f32_16x16x32_bf16 v[104:107], v[156:159], v[188:191], v[104:107]
	v_mfma_f32_16x16x32_bf16 v[96:99], v[172:175], v[188:191], v[96:99]
	v_mfma_f32_16x16x32_bf16 v[80:83], v[156:159], v[196:199], v[80:83]
	v_mfma_f32_16x16x32_bf16 v[76:79], v[172:175], v[196:199], v[76:79]
	v_mfma_f32_16x16x32_bf16 v[68:71], v[156:159], v[204:207], v[68:71]
	v_mfma_f32_16x16x32_bf16 v[64:67], v[172:175], v[204:207], v[64:67]
	v_mfma_f32_16x16x32_bf16 v[124:127], v[168:171], v[184:187], v[124:127]
	v_mfma_f32_16x16x32_bf16 v[116:119], v[176:179], v[184:187], v[116:119]
	v_mfma_f32_16x16x32_bf16 v[104:107], v[168:171], v[192:195], v[104:107]
	v_mfma_f32_16x16x32_bf16 v[96:99], v[176:179], v[192:195], v[96:99]
	v_mfma_f32_16x16x32_bf16 v[80:83], v[168:171], v[200:203], v[80:83]
	v_mfma_f32_16x16x32_bf16 v[76:79], v[176:179], v[200:203], v[76:79]
	v_mfma_f32_16x16x32_bf16 v[68:71], v[168:171], v[208:211], v[68:71]
	v_mfma_f32_16x16x32_bf16 v[64:67], v[176:179], v[208:211], v[64:67]
	s_barrier
; #define PG8_STAGE(bufoff, gbase, voff) do { _Pragma("unroll") for (int _i = 0; _i < 2; ++_i) \
;         __builtin_amdgcn_global_load_lds((const unsigned*)((const char*)(gbase) + (voff)[_i]), (PG8_LAS unsigned*)(lds + (bufoff) + ldsw + _i * 8192), 16, 0, 0); } while (0)
; #define PG8_WAIT_V(n) asm volatile("s_waitcnt vmcnt(" #n ")" ::: "memory")
; #define PG8_WAIT_L(n) asm volatile("s_waitcnt lgkmcnt(" #n ")" ::: "memory")
; template <class Epi, class Sched, bool ALIGN_EPI = false, bool SP2 = false>
; __device__ __forceinline__ void gemm_phase(PG8_LAS unsigned char* lds, const Gemm g, const Sched& S, const Epi& E) {
;     ...
;             PG8_WAIT_V(8); PG8_WAIT_L(0); PG8_BAR; PG8_MMA(0, 0, At, B0); PG8_MMA(0, 1, At, B1); PG8_BAR; PG8_SCHED;
;             PG8_LDA(At, 1, 1); PG8_STAGE(PG8_SB(1, 0), b3, voffB); PG8_STAGE(PG8_SB(1, 1), b3 + hstep, voffB); PG8_STAGE(PG8_SA(1, 0), a3, voffA);
;             PG8_WAIT_V(8); PG8_WAIT_L(0); PG8_BAR; PG8_MMA(1, 0, At, B0); PG8_MMA(1, 1, At, B1); PG8_BAR; PG8_SCHED;
;             } else {
;             PG8_LDB(B0, 0, 0); PG8_SCHED; PG8_LDA(At, 0, 0); PG8_STAGE(PG8_SA(1, 1), a1 + hstep, voffA);
;             PG8_WAIT_L(8); PG8_BAR; PG8_WAIT_L(0); PG8_MMA(0, 0, At, B0); PG8_BAR; PG8_SCHED;
;             PG8_LDB(B1, 0, 1); PG8_STAGE(PG8_SB(0, 0), b2, voffB);
;             PG8_BAR; PG8_WAIT_L(0); PG8_MMA(0, 1, At, B1); PG8_BAR;
;             PG8_LDA(At, 0, 1); PG8_STAGE(PG8_SA(0, 0), a2, voffA);
;             PG8_BAR; PG8_WAIT_L(0); PG8_MMA(1, 0, At, B0); PG8_BAR; PG8_SCHED;
;             PG8_STAGE(PG8_SB(0, 1), b2 + hstep, voffB);
;             PG8_WAIT_V(6); PG8_BAR; PG8_MMA(1, 1, At, B1); PG8_BAR;
;             PG8_LDB(B0, 1, 0); PG8_SCHED; PG8_LDA(At, 1, 0); PG8_STAGE(PG8_SA(0, 1), a2 + hstep, voffA);
;             PG8_WAIT_L(8); PG8_BAR; PG8_WAIT_L(0); PG8_MMA(0, 0, At, B0); PG8_BAR; PG8_SCHED;
;             PG8_LDB(B1, 1, 1); PG8_STAGE(PG8_SB(1, 0), b3, voffB);
;             PG8_BAR; PG8_WAIT_L(0); PG8_MMA(0, 1, At, B1); PG8_BAR;
;             PG8_LDA(At, 1, 1); PG8_STAGE(PG8_SA(1, 0), a3, voffA);
;             PG8_BAR; PG8_WAIT_L(0); PG8_MMA(1, 0, At, B0); PG8_BAR; PG8_SCHED;
;             PG8_STAGE(PG8_SB(1, 1), b3 + hstep, voffB);
;             PG8_WAIT_V(6); PG8_BAR; PG8_MMA(1, 1, At, B1); PG8_BAR;
;             }
;         }
;         if constexpr (ALIGN_EPI) { if (wr == 0) PG8_BAR; }
	s_setprio 0
	s_add_i32 s30, s62, s47
	v_lshl_add_u64 v[160:161], v[160:161], 0, s[8:9]
	s_mov_b32 m0, s30
	ds_read_b128 v[180:183], v167 offset:49152
	ds_read_b128 v[184:187], v167 offset:50176
	ds_read_b128 v[188:191], v167 offset:51200
	ds_read_b128 v[192:195], v167 offset:52224
	ds_read_b128 v[196:199], v167 offset:53248
	ds_read_b128 v[200:203], v167 offset:54272
	ds_read_b128 v[204:207], v167 offset:55296
	ds_read_b128 v[208:211], v167 offset:56320
	global_load_lds_dwordx4 v[160:161], off
	s_add_i32 m0, s30, 0x2000
	s_add_u32 s30, s36, 0x200080
	v_lshl_add_u64 v[160:161], v[212:213], 0, s[8:9]
	s_addc_u32 s31, s37, 0
	s_add_i32 s36, s63, s47
	global_load_lds_dwordx4 v[160:161], off
	v_lshl_add_u64 v[160:161], s[30:31], 0, v[146:147]
	s_mov_b32 m0, s36
	s_nop 0
	global_load_lds_dwordx4 v[160:161], off
	v_lshl_add_u64 v[160:161], s[30:31], 0, v[144:145]
	s_add_i32 m0, s36, 0x2000
	s_nop 0
	global_load_lds_dwordx4 v[160:161], off
	v_lshl_add_u64 v[160:161], v[214:215], 0, s[8:9]
	s_mov_b32 m0, s53
	s_nop 0
	global_load_lds_dwordx4 v[160:161], off
	v_lshl_add_u64 v[160:161], v[216:217], 0, s[8:9]
	s_mov_b32 m0, s54
	s_nop 0
	global_load_lds_dwordx4 v[160:161], off
	s_waitcnt vmcnt(8)
	s_waitcnt lgkmcnt(0)
	s_setprio 1
	s_barrier
	v_mfma_f32_16x16x32_bf16 v[60:63], v[72:75], v[180:183], v[60:63]
	v_mfma_f32_16x16x32_bf16 v[56:59], v[92:95], v[180:183], v[56:59]
	v_mfma_f32_16x16x32_bf16 v[52:55], v[72:75], v[188:191], v[52:55]
	v_mfma_f32_16x16x32_bf16 v[44:47], v[92:95], v[188:191], v[44:47]
	v_mfma_f32_16x16x32_bf16 v[36:39], v[72:75], v[196:199], v[36:39]
	v_mfma_f32_16x16x32_bf16 v[28:31], v[92:95], v[196:199], v[28:31]
	v_mfma_f32_16x16x32_bf16 v[20:23], v[72:75], v[204:207], v[20:23]
	v_mfma_f32_16x16x32_bf16 v[12:15], v[92:95], v[204:207], v[12:15]
	v_mfma_f32_16x16x32_bf16 v[60:63], v[84:87], v[184:187], v[60:63]
	v_mfma_f32_16x16x32_bf16 v[56:59], v[108:111], v[184:187], v[56:59]
	v_mfma_f32_16x16x32_bf16 v[52:55], v[84:87], v[192:195], v[52:55]
	v_mfma_f32_16x16x32_bf16 v[44:47], v[108:111], v[192:195], v[44:47]
	v_mfma_f32_16x16x32_bf16 v[36:39], v[84:87], v[200:203], v[36:39]
	v_mfma_f32_16x16x32_bf16 v[28:31], v[108:111], v[200:203], v[28:31]
	v_mfma_f32_16x16x32_bf16 v[20:23], v[84:87], v[208:211], v[20:23]
	v_mfma_f32_16x16x32_bf16 v[12:15], v[108:111], v[208:211], v[12:15]
	v_mfma_f32_16x16x32_bf16 v[48:51], v[156:159], v[180:183], v[48:51]
	v_mfma_f32_16x16x32_bf16 v[40:43], v[172:175], v[180:183], v[40:43]
	v_mfma_f32_16x16x32_bf16 v[32:35], v[156:159], v[188:191], v[32:35]
	v_mfma_f32_16x16x32_bf16 v[24:27], v[172:175], v[188:191], v[24:27]
	v_mfma_f32_16x16x32_bf16 v[16:19], v[156:159], v[196:199], v[16:19]
	v_mfma_f32_16x16x32_bf16 v[8:11], v[172:175], v[196:199], v[8:11]
	v_mfma_f32_16x16x32_bf16 v[4:7], v[156:159], v[204:207], v[4:7]
	v_mfma_f32_16x16x32_bf16 v[0:3], v[172:175], v[204:207], v[0:3]
	v_mfma_f32_16x16x32_bf16 v[48:51], v[168:171], v[184:187], v[48:51]
	v_mfma_f32_16x16x32_bf16 v[40:43], v[176:179], v[184:187], v[40:43]
	v_mfma_f32_16x16x32_bf16 v[32:35], v[168:171], v[192:195], v[32:35]
	v_mfma_f32_16x16x32_bf16 v[24:27], v[176:179], v[192:195], v[24:27]
	v_mfma_f32_16x16x32_bf16 v[16:19], v[168:171], v[200:203], v[16:19]
	v_mfma_f32_16x16x32_bf16 v[8:11], v[176:179], v[200:203], v[8:11]
	v_mfma_f32_16x16x32_bf16 v[4:7], v[168:171], v[208:211], v[4:7]
	v_mfma_f32_16x16x32_bf16 v[0:3], v[176:179], v[208:211], v[0:3]
	s_barrier
	s_setprio 0
	s_add_i32 s61, s61, 2
	s_add_u32 s59, s59, 0x100
	s_addc_u32 s60, s60, 0
	s_cmpk_gt_u32 s61, 0x7d
	s_mov_b64 s[30:31], s[34:35]
	s_cbranch_scc0 .LBB0_847
	s_and_b64 vcc, exec, s[10:11]
	s_cbranch_vccz .LBB0_850
	s_barrier
